# speedup vs baseline: 1.0142x; 1.0104x over previous
; #define PG8_STAGE(bufoff, gbase, voff) do { _Pragma("unroll") for (int _i = 0; _i < 2; ++_i) \
;         __builtin_amdgcn_global_load_lds((const unsigned*)((const char*)(gbase) + (voff)[_i]), (PG8_LAS unsigned*)(lds + (bufoff) + ldsw + _i * 8192), 16, 0, 0); } while (0)
; #define PG8_LDA(dst, b, h) do { _Pragma("unroll") for (int m = 0; m < 4; ++m) _Pragma("unroll") for (int k = 0; k < 2; ++k) dst[m][k] = *(const PG8_LAS bf16x8*)(lds + PG8_SA(b, h) + aoff + m * 2048 + k * 1024); } while (0)
; #define PG8_LDB(dst, b, h) do { _Pragma("unroll") for (int n = 0; n < 2; ++n) _Pragma("unroll") for (int k = 0; k < 2; ++k) dst[n][k] = *(const PG8_LAS bf16x8*)(lds + PG8_SB(b, h) + boff + n * 2048 + k * 1024); } while (0)
; #define PG8_MMA(ai, bj, At, Bt) do { __builtin_amdgcn_s_setprio(3); _Pragma("unroll") for (int m = 0; m < 4; ++m) _Pragma("unroll") for (int n = 0; n < 2; ++n) _Pragma("unroll") for (int k = 0; k < 2; ++k) \
;         acc[ai][bj][m][n] = __builtin_amdgcn_mfma_f32_16x16x32_bf16(Bt[n][k], At[m][k], acc[ai][bj][m][n], 0, 0, 0); __builtin_amdgcn_s_setprio(0); } while (0)
; #define PG8_WAIT_V(n) asm volatile("s_waitcnt vmcnt(" #n ")" ::: "memory")
; #define PG8_BAR __builtin_amdgcn_s_barrier()
; template <class Epi, class Sched, bool ALIGN_EPI = false, bool SP2 = false>
; __device__ __forceinline__ void gemm_phase(PG8_LAS unsigned char* lds, const Gemm g, const Sched& S, const Epi& E) {
;     ...
;         for (int t = 0; t < nt; t += 2) {
;             const bool last = (t == nt - 2);
;             const char* a1 = cA + (size_t)(t + 1) * kstep;
;             const char* a2 = last ? nA : cA + (size_t)(t + 2) * kstep; const char* b2 = last ? nB : cB + (size_t)(t + 2) * kstep;
;             const char* a3 = a2 + kstep; const char* b3 = b2 + kstep;
;             if (last && has_next) S.a_ready(nxt);
;             if constexpr (SP2) {
;             PG8_LDB(B0, 0, 0); PG8_LDB(B1, 0, 1); PG8_SCHED; PG8_LDA(At, 0, 0); PG8_STAGE(PG8_SA(1, 1), a1 + hstep, voffA);
;             PG8_WAIT_V(8); PG8_WAIT_L(0); PG8_BAR; PG8_MMA(0, 0, At, B0); PG8_MMA(0, 1, At, B1); PG8_BAR; PG8_SCHED;
;             PG8_LDA(At, 0, 1); PG8_STAGE(PG8_SB(0, 0), b2, voffB); PG8_STAGE(PG8_SB(0, 1), b2 + hstep, voffB); PG8_STAGE(PG8_SA(0, 0), a2, voffA);
;             PG8_WAIT_V(8); PG8_WAIT_L(0); PG8_BAR; PG8_MMA(1, 0, At, B0); PG8_MMA(1, 1, At, B1); PG8_BAR; PG8_SCHED;
.LBB0_70:
	ds_read_b128 v[148:151], v153
	ds_read_b128 v[156:159], v153 offset:1024
	ds_read_b128 v[160:163], v153 offset:2048
	ds_read_b128 v[168:171], v153 offset:3072
	ds_read_b128 v[172:175], v154
	ds_read_b128 v[176:179], v154 offset:1024
	ds_read_b128 v[180:183], v154 offset:2048
	ds_read_b128 v[184:187], v154 offset:3072
	s_add_u32 s50, s48, 0xfff80080
	s_addc_u32 s51, s49, -1
	s_cmp_eq_u32 s70, 28
	s_cselect_b32 s53, s29, s51
	s_cselect_b32 s52, s65, s50
	s_cselect_b32 s51, s27, s69
	s_cselect_b32 s50, s67, s68
	v_lshl_add_u64 v[164:165], s[48:49], 0, v[138:139]
	s_add_i32 m0, s43, 0xc000
	ds_read_b128 v[188:191], v155
	ds_read_b128 v[192:195], v155 offset:1024
	ds_read_b128 v[196:199], v155 offset:2048
	ds_read_b128 v[200:203], v155 offset:3072
	ds_read_b128 v[204:207], v155 offset:4096
	ds_read_b128 v[208:211], v155 offset:5120
	ds_read_b128 v[212:215], v155 offset:6144
	ds_read_b128 v[216:219], v155 offset:7168
	global_load_lds_dwordx4 v[164:165], off
	v_lshl_add_u64 v[164:165], s[48:49], 0, v[142:143]
	s_add_i32 m0, s43, 0xe000
	s_nop 0
	global_load_lds_dwordx4 v[164:165], off
	s_waitcnt vmcnt(8)
	s_waitcnt lgkmcnt(0)
	s_barrier
	s_waitcnt lgkmcnt(0)
	v_mfma_f32_16x16x32_bf16 v[126:129], v[148:151], v[188:191], v[126:129]
	s_setprio 3
	v_mfma_f32_16x16x32_bf16 v[118:121], v[160:163], v[188:191], v[118:121]
	v_mfma_f32_16x16x32_bf16 v[110:113], v[148:151], v[196:199], v[110:113]
	v_mfma_f32_16x16x32_bf16 v[102:105], v[160:163], v[196:199], v[102:105]
	v_mfma_f32_16x16x32_bf16 v[94:97], v[148:151], v[204:207], v[94:97]
	v_mfma_f32_16x16x32_bf16 v[86:89], v[160:163], v[204:207], v[86:89]
	v_mfma_f32_16x16x32_bf16 v[78:81], v[148:151], v[212:215], v[78:81]
	v_mfma_f32_16x16x32_bf16 v[70:73], v[160:163], v[212:215], v[70:73]
	v_mfma_f32_16x16x32_bf16 v[126:129], v[156:159], v[192:195], v[126:129]
	v_mfma_f32_16x16x32_bf16 v[118:121], v[168:171], v[192:195], v[118:121]
	v_mfma_f32_16x16x32_bf16 v[110:113], v[156:159], v[200:203], v[110:113]
	v_mfma_f32_16x16x32_bf16 v[102:105], v[168:171], v[200:203], v[102:105]
	v_mfma_f32_16x16x32_bf16 v[94:97], v[156:159], v[208:211], v[94:97]
	v_mfma_f32_16x16x32_bf16 v[86:89], v[168:171], v[208:211], v[86:89]
	v_mfma_f32_16x16x32_bf16 v[78:81], v[156:159], v[216:219], v[78:81]
	v_mfma_f32_16x16x32_bf16 v[70:73], v[168:171], v[216:219], v[70:73]
	s_setprio 0
	s_setprio 3
	v_mfma_f32_16x16x32_bf16 v[122:125], v[172:175], v[188:191], v[122:125]
	v_mfma_f32_16x16x32_bf16 v[114:117], v[180:183], v[188:191], v[114:117]
	v_mfma_f32_16x16x32_bf16 v[106:109], v[172:175], v[196:199], v[106:109]
	v_mfma_f32_16x16x32_bf16 v[98:101], v[180:183], v[196:199], v[98:101]
	v_mfma_f32_16x16x32_bf16 v[90:93], v[172:175], v[204:207], v[90:93]
	v_mfma_f32_16x16x32_bf16 v[82:85], v[180:183], v[204:207], v[82:85]
	v_mfma_f32_16x16x32_bf16 v[74:77], v[172:175], v[212:215], v[74:77]
	v_mfma_f32_16x16x32_bf16 v[66:69], v[180:183], v[212:215], v[66:69]
	v_mfma_f32_16x16x32_bf16 v[122:125], v[176:179], v[192:195], v[122:125]
	v_mfma_f32_16x16x32_bf16 v[114:117], v[184:187], v[192:195], v[114:117]
	v_mfma_f32_16x16x32_bf16 v[106:109], v[176:179], v[200:203], v[106:109]
	v_mfma_f32_16x16x32_bf16 v[98:101], v[184:187], v[200:203], v[98:101]
	v_mfma_f32_16x16x32_bf16 v[90:93], v[176:179], v[208:211], v[90:93]
	v_mfma_f32_16x16x32_bf16 v[82:85], v[184:187], v[208:211], v[82:85]
	v_mfma_f32_16x16x32_bf16 v[74:77], v[176:179], v[216:219], v[74:77]
	s_barrier
	v_mfma_f32_16x16x32_bf16 v[66:69], v[184:187], v[216:219], v[66:69]
	s_setprio 0
	s_add_i32 s71, s61, s37
	v_lshl_add_u64 v[164:165], s[50:51], 0, v[132:133]
	s_mov_b32 m0, s71
	ds_read_b128 v[188:191], v155 offset:16384
	ds_read_b128 v[192:195], v155 offset:17408
	ds_read_b128 v[196:199], v155 offset:18432
	ds_read_b128 v[200:203], v155 offset:19456
	ds_read_b128 v[204:207], v155 offset:20480
	ds_read_b128 v[208:211], v155 offset:21504
	ds_read_b128 v[212:215], v155 offset:22528
	ds_read_b128 v[216:219], v155 offset:23552
	global_load_lds_dwordx4 v[164:165], off
	s_add_i32 m0, s71, 0x2000
	s_add_u32 s72, s50, 0x80000
	v_lshl_add_u64 v[220:221], s[50:51], 0, v[136:137]
	s_addc_u32 s73, s51, 0
	s_add_i32 s71, s62, s37
	global_load_lds_dwordx4 v[220:221], off
	v_lshl_add_u64 v[222:223], s[72:73], 0, v[132:133]
	s_mov_b32 m0, s71
	v_lshl_add_u64 v[224:225], s[52:53], 0, v[134:135]
	global_load_lds_dwordx4 v[222:223], off
	v_lshl_add_u64 v[222:223], s[72:73], 0, v[136:137]
	s_add_i32 m0, s71, 0x2000
	s_nop 0
	global_load_lds_dwordx4 v[222:223], off
	v_lshl_add_u64 v[222:223], s[52:53], 0, v[130:131]
	s_mov_b32 m0, s43
	s_nop 0
	global_load_lds_dwordx4 v[222:223], off
	s_mov_b32 m0, s47
	s_nop 0
	global_load_lds_dwordx4 v[224:225], off
	s_waitcnt vmcnt(8)
	s_waitcnt lgkmcnt(0)
	s_barrier
; #define PG8_STAGE(bufoff, gbase, voff) do { _Pragma("unroll") for (int _i = 0; _i < 2; ++_i) \
;         __builtin_amdgcn_global_load_lds((const unsigned*)((const char*)(gbase) + (voff)[_i]), (PG8_LAS unsigned*)(lds + (bufoff) + ldsw + _i * 8192), 16, 0, 0); } while (0)
; #define PG8_LDA(dst, b, h) do { _Pragma("unroll") for (int m = 0; m < 4; ++m) _Pragma("unroll") for (int k = 0; k < 2; ++k) dst[m][k] = *(const PG8_LAS bf16x8*)(lds + PG8_SA(b, h) + aoff + m * 2048 + k * 1024); } while (0)
; #define PG8_LDB(dst, b, h) do { _Pragma("unroll") for (int n = 0; n < 2; ++n) _Pragma("unroll") for (int k = 0; k < 2; ++k) dst[n][k] = *(const PG8_LAS bf16x8*)(lds + PG8_SB(b, h) + boff + n * 2048 + k * 1024); } while (0)
; #define PG8_MMA(ai, bj, At, Bt) do { __builtin_amdgcn_s_setprio(3); _Pragma("unroll") for (int m = 0; m < 4; ++m) _Pragma("unroll") for (int n = 0; n < 2; ++n) _Pragma("unroll") for (int k = 0; k < 2; ++k) \
;         acc[ai][bj][m][n] = __builtin_amdgcn_mfma_f32_16x16x32_bf16(Bt[n][k], At[m][k], acc[ai][bj][m][n], 0, 0, 0); __builtin_amdgcn_s_setprio(0); } while (0)
; #define PG8_WAIT_V(n) asm volatile("s_waitcnt vmcnt(" #n ")" ::: "memory")
; #define PG8_WAIT_L(n) asm volatile("s_waitcnt lgkmcnt(" #n ")" ::: "memory")
; #define PG8_BAR __builtin_amdgcn_s_barrier()
; #define PG8_SCHED __builtin_amdgcn_sched_barrier(0)
; template <class Epi, class Sched, bool ALIGN_EPI = false, bool SP2 = false>
; __device__ __forceinline__ void gemm_phase(PG8_LAS unsigned char* lds, const Gemm g, const Sched& S, const Epi& E) {
;     ...
;             PG8_WAIT_V(8); PG8_WAIT_L(0); PG8_BAR; PG8_MMA(1, 0, At, B0); PG8_MMA(1, 1, At, B1); PG8_BAR; PG8_SCHED;
;             PG8_LDB(B0, 1, 0); PG8_LDB(B1, 1, 1); PG8_SCHED; PG8_LDA(At, 1, 0); PG8_STAGE(PG8_SA(0, 1), a2 + hstep, voffA);
;             PG8_WAIT_V(8); PG8_WAIT_L(0); PG8_BAR; PG8_MMA(0, 0, At, B0); PG8_MMA(0, 1, At, B1); PG8_BAR; PG8_SCHED;
	s_waitcnt lgkmcnt(0)
	v_mfma_f32_16x16x32_bf16 v[62:65], v[148:151], v[188:191], v[62:65]
	s_setprio 3
	v_mfma_f32_16x16x32_bf16 v[54:57], v[160:163], v[188:191], v[54:57]
	v_mfma_f32_16x16x32_bf16 v[46:49], v[148:151], v[196:199], v[46:49]
	v_mfma_f32_16x16x32_bf16 v[38:41], v[160:163], v[196:199], v[38:41]
	v_mfma_f32_16x16x32_bf16 v[30:33], v[148:151], v[204:207], v[30:33]
	v_mfma_f32_16x16x32_bf16 v[22:25], v[160:163], v[204:207], v[22:25]
	v_mfma_f32_16x16x32_bf16 v[14:17], v[148:151], v[212:215], v[14:17]
	v_mfma_f32_16x16x32_bf16 v[6:9], v[160:163], v[212:215], v[6:9]
	v_mfma_f32_16x16x32_bf16 v[62:65], v[156:159], v[192:195], v[62:65]
	v_mfma_f32_16x16x32_bf16 v[54:57], v[168:171], v[192:195], v[54:57]
	v_mfma_f32_16x16x32_bf16 v[46:49], v[156:159], v[200:203], v[46:49]
	v_mfma_f32_16x16x32_bf16 v[38:41], v[168:171], v[200:203], v[38:41]
	v_mfma_f32_16x16x32_bf16 v[30:33], v[156:159], v[208:211], v[30:33]
	v_mfma_f32_16x16x32_bf16 v[22:25], v[168:171], v[208:211], v[22:25]
	v_mfma_f32_16x16x32_bf16 v[14:17], v[156:159], v[216:219], v[14:17]
	v_mfma_f32_16x16x32_bf16 v[6:9], v[168:171], v[216:219], v[6:9]
	s_setprio 0
	s_setprio 3
	v_mfma_f32_16x16x32_bf16 v[58:61], v[172:175], v[188:191], v[58:61]
	v_mfma_f32_16x16x32_bf16 v[50:53], v[180:183], v[188:191], v[50:53]
	v_mfma_f32_16x16x32_bf16 v[42:45], v[172:175], v[196:199], v[42:45]
	v_mfma_f32_16x16x32_bf16 v[34:37], v[180:183], v[196:199], v[34:37]
	v_mfma_f32_16x16x32_bf16 v[26:29], v[172:175], v[204:207], v[26:29]
	v_mfma_f32_16x16x32_bf16 v[18:21], v[180:183], v[204:207], v[18:21]
	v_mfma_f32_16x16x32_bf16 v[10:13], v[172:175], v[212:215], v[10:13]
	v_mfma_f32_16x16x32_bf16 v[2:5], v[180:183], v[212:215], v[2:5]
	v_mfma_f32_16x16x32_bf16 v[58:61], v[176:179], v[192:195], v[58:61]
	v_mfma_f32_16x16x32_bf16 v[50:53], v[184:187], v[192:195], v[50:53]
	v_mfma_f32_16x16x32_bf16 v[42:45], v[176:179], v[200:203], v[42:45]
	v_mfma_f32_16x16x32_bf16 v[34:37], v[184:187], v[200:203], v[34:37]
	v_mfma_f32_16x16x32_bf16 v[26:29], v[176:179], v[208:211], v[26:29]
	v_mfma_f32_16x16x32_bf16 v[18:21], v[184:187], v[208:211], v[18:21]
	v_mfma_f32_16x16x32_bf16 v[10:13], v[176:179], v[216:219], v[10:13]
	s_barrier
	v_mfma_f32_16x16x32_bf16 v[2:5], v[184:187], v[216:219], v[2:5]
	s_setprio 0
	s_add_i32 s71, 0, 0x18000
	v_add_u32_e32 v167, s71, v141
	s_add_i32 s72, 0, 0x1c000
	ds_read_b128 v[148:151], v167
	ds_read_b128 v[156:159], v167 offset:1024
	ds_read_b128 v[160:163], v167 offset:2048
	ds_read_b128 v[168:171], v167 offset:3072
	v_add_u32_e32 v167, s72, v141
	ds_read_b128 v[172:175], v167
	ds_read_b128 v[176:179], v167 offset:1024
	ds_read_b128 v[180:183], v167 offset:2048
	ds_read_b128 v[184:187], v167 offset:3072
	s_add_u32 s52, s52, 0x80000
	s_addc_u32 s53, s53, 0
	s_mov_b32 m0, s54
	v_lshl_add_u64 v[226:227], s[52:53], 0, v[130:131]
	ds_read_b128 v[188:191], v155 offset:32768
	ds_read_b128 v[192:195], v155 offset:33792
	ds_read_b128 v[196:199], v155 offset:34816
	ds_read_b128 v[200:203], v155 offset:35840
	ds_read_b128 v[204:207], v155 offset:36864
	ds_read_b128 v[208:211], v155 offset:37888
	ds_read_b128 v[212:215], v155 offset:38912
	ds_read_b128 v[216:219], v155 offset:39936
	global_load_lds_dwordx4 v[226:227], off
	v_lshl_add_u64 v[226:227], s[52:53], 0, v[134:135]
	s_mov_b32 m0, s55
	s_nop 0
	global_load_lds_dwordx4 v[226:227], off
	s_waitcnt vmcnt(8)
	s_waitcnt lgkmcnt(0)
	s_barrier
	s_waitcnt lgkmcnt(0)
	v_mfma_f32_16x16x32_bf16 v[126:129], v[148:151], v[188:191], v[126:129]
	s_setprio 3
	v_mfma_f32_16x16x32_bf16 v[118:121], v[160:163], v[188:191], v[118:121]
	v_mfma_f32_16x16x32_bf16 v[110:113], v[148:151], v[196:199], v[110:113]
	v_mfma_f32_16x16x32_bf16 v[102:105], v[160:163], v[196:199], v[102:105]
	v_mfma_f32_16x16x32_bf16 v[94:97], v[148:151], v[204:207], v[94:97]
	v_mfma_f32_16x16x32_bf16 v[86:89], v[160:163], v[204:207], v[86:89]
	v_mfma_f32_16x16x32_bf16 v[78:81], v[148:151], v[212:215], v[78:81]
	v_mfma_f32_16x16x32_bf16 v[70:73], v[160:163], v[212:215], v[70:73]
	v_mfma_f32_16x16x32_bf16 v[126:129], v[156:159], v[192:195], v[126:129]
	v_mfma_f32_16x16x32_bf16 v[118:121], v[168:171], v[192:195], v[118:121]
	v_mfma_f32_16x16x32_bf16 v[110:113], v[156:159], v[200:203], v[110:113]
	v_mfma_f32_16x16x32_bf16 v[102:105], v[168:171], v[200:203], v[102:105]
	v_mfma_f32_16x16x32_bf16 v[94:97], v[156:159], v[208:211], v[94:97]
	v_mfma_f32_16x16x32_bf16 v[86:89], v[168:171], v[208:211], v[86:89]
	v_mfma_f32_16x16x32_bf16 v[78:81], v[156:159], v[216:219], v[78:81]
	v_mfma_f32_16x16x32_bf16 v[70:73], v[168:171], v[216:219], v[70:73]
	s_setprio 0
	s_setprio 3
	v_mfma_f32_16x16x32_bf16 v[122:125], v[172:175], v[188:191], v[122:125]
	v_mfma_f32_16x16x32_bf16 v[114:117], v[180:183], v[188:191], v[114:117]
	v_mfma_f32_16x16x32_bf16 v[106:109], v[172:175], v[196:199], v[106:109]
	v_mfma_f32_16x16x32_bf16 v[98:101], v[180:183], v[196:199], v[98:101]
	v_mfma_f32_16x16x32_bf16 v[90:93], v[172:175], v[204:207], v[90:93]
	v_mfma_f32_16x16x32_bf16 v[82:85], v[180:183], v[204:207], v[82:85]
	v_mfma_f32_16x16x32_bf16 v[74:77], v[172:175], v[212:215], v[74:77]
	v_mfma_f32_16x16x32_bf16 v[66:69], v[180:183], v[212:215], v[66:69]
	v_mfma_f32_16x16x32_bf16 v[122:125], v[176:179], v[192:195], v[122:125]
	v_mfma_f32_16x16x32_bf16 v[114:117], v[184:187], v[192:195], v[114:117]
	v_mfma_f32_16x16x32_bf16 v[106:109], v[176:179], v[200:203], v[106:109]
	v_mfma_f32_16x16x32_bf16 v[98:101], v[184:187], v[200:203], v[98:101]
	v_mfma_f32_16x16x32_bf16 v[90:93], v[176:179], v[208:211], v[90:93]
	v_mfma_f32_16x16x32_bf16 v[82:85], v[184:187], v[208:211], v[82:85]
	v_mfma_f32_16x16x32_bf16 v[74:77], v[176:179], v[216:219], v[74:77]
	s_barrier
; #define PG8_STAGE(bufoff, gbase, voff) do { _Pragma("unroll") for (int _i = 0; _i < 2; ++_i) \
;         __builtin_amdgcn_global_load_lds((const unsigned*)((const char*)(gbase) + (voff)[_i]), (PG8_LAS unsigned*)(lds + (bufoff) + ldsw + _i * 8192), 16, 0, 0); } while (0)
; #define PG8_LDA(dst, b, h) do { _Pragma("unroll") for (int m = 0; m < 4; ++m) _Pragma("unroll") for (int k = 0; k < 2; ++k) dst[m][k] = *(const PG8_LAS bf16x8*)(lds + PG8_SA(b, h) + aoff + m * 2048 + k * 1024); } while (0)
; #define PG8_MMA(ai, bj, At, Bt) do { __builtin_amdgcn_s_setprio(3); _Pragma("unroll") for (int m = 0; m < 4; ++m) _Pragma("unroll") for (int n = 0; n < 2; ++n) _Pragma("unroll") for (int k = 0; k < 2; ++k) \
;         acc[ai][bj][m][n] = __builtin_amdgcn_mfma_f32_16x16x32_bf16(Bt[n][k], At[m][k], acc[ai][bj][m][n], 0, 0, 0); __builtin_amdgcn_s_setprio(0); } while (0)
; #define PG8_WAIT_V(n) asm volatile("s_waitcnt vmcnt(" #n ")" ::: "memory")
; #define PG8_WAIT_L(n) asm volatile("s_waitcnt lgkmcnt(" #n ")" ::: "memory")
; #define PG8_BAR __builtin_amdgcn_s_barrier()
; #define PG8_SCHED __builtin_amdgcn_sched_barrier(0)
; template <class Epi, class Sched, bool ALIGN_EPI = false, bool SP2 = false>
; __device__ __forceinline__ void gemm_phase(PG8_LAS unsigned char* lds, const Gemm g, const Sched& S, const Epi& E) {
;     ...
;         for (int t = 0; t < nt; t += 2) {
;     ...
;             PG8_WAIT_V(8); PG8_WAIT_L(0); PG8_BAR; PG8_MMA(0, 0, At, B0); PG8_MMA(0, 1, At, B1); PG8_BAR; PG8_SCHED;
;             PG8_LDA(At, 1, 1); PG8_STAGE(PG8_SB(1, 0), b3, voffB); PG8_STAGE(PG8_SB(1, 1), b3 + hstep, voffB); PG8_STAGE(PG8_SA(1, 0), a3, voffA);
;             PG8_WAIT_V(8); PG8_WAIT_L(0); PG8_BAR; PG8_MMA(1, 0, At, B0); PG8_MMA(1, 1, At, B1); PG8_BAR; PG8_SCHED;
	v_mfma_f32_16x16x32_bf16 v[66:69], v[184:187], v[216:219], v[66:69]
	s_setprio 0
	s_add_i32 s52, s71, s37
	v_lshl_add_u64 v[164:165], v[164:165], 0, s[18:19]
	s_mov_b32 m0, s52
	ds_read_b128 v[188:191], v155 offset:49152
	ds_read_b128 v[192:195], v155 offset:50176
	ds_read_b128 v[196:199], v155 offset:51200
	ds_read_b128 v[200:203], v155 offset:52224
	ds_read_b128 v[204:207], v155 offset:53248
	ds_read_b128 v[208:211], v155 offset:54272
	ds_read_b128 v[212:215], v155 offset:55296
	ds_read_b128 v[216:219], v155 offset:56320
	global_load_lds_dwordx4 v[164:165], off
	s_add_i32 m0, s52, 0x2000
	s_add_u32 s50, s50, 0x80080
	v_lshl_add_u64 v[164:165], v[220:221], 0, s[18:19]
	s_addc_u32 s51, s51, 0
	s_add_i32 s52, s72, s37
	global_load_lds_dwordx4 v[164:165], off
	v_lshl_add_u64 v[164:165], s[50:51], 0, v[132:133]
	s_mov_b32 m0, s52
	s_nop 0
	global_load_lds_dwordx4 v[164:165], off
	v_lshl_add_u64 v[164:165], s[50:51], 0, v[136:137]
	s_add_i32 m0, s52, 0x2000
	s_nop 0
	global_load_lds_dwordx4 v[164:165], off
	v_lshl_add_u64 v[164:165], v[222:223], 0, s[18:19]
	s_mov_b32 m0, s58
	s_nop 0
	global_load_lds_dwordx4 v[164:165], off
	v_lshl_add_u64 v[164:165], v[224:225], 0, s[18:19]
	s_mov_b32 m0, s59
	s_nop 0
	global_load_lds_dwordx4 v[164:165], off
	s_waitcnt vmcnt(8)
	s_waitcnt lgkmcnt(0)
	s_barrier
	s_waitcnt lgkmcnt(0)
	v_mfma_f32_16x16x32_bf16 v[62:65], v[148:151], v[188:191], v[62:65]
	s_setprio 3
	v_mfma_f32_16x16x32_bf16 v[54:57], v[160:163], v[188:191], v[54:57]
	v_mfma_f32_16x16x32_bf16 v[46:49], v[148:151], v[196:199], v[46:49]
	v_mfma_f32_16x16x32_bf16 v[38:41], v[160:163], v[196:199], v[38:41]
	v_mfma_f32_16x16x32_bf16 v[30:33], v[148:151], v[204:207], v[30:33]
	v_mfma_f32_16x16x32_bf16 v[22:25], v[160:163], v[204:207], v[22:25]
	v_mfma_f32_16x16x32_bf16 v[14:17], v[148:151], v[212:215], v[14:17]
	v_mfma_f32_16x16x32_bf16 v[6:9], v[160:163], v[212:215], v[6:9]
	v_mfma_f32_16x16x32_bf16 v[62:65], v[156:159], v[192:195], v[62:65]
	v_mfma_f32_16x16x32_bf16 v[54:57], v[168:171], v[192:195], v[54:57]
	v_mfma_f32_16x16x32_bf16 v[46:49], v[156:159], v[200:203], v[46:49]
	v_mfma_f32_16x16x32_bf16 v[38:41], v[168:171], v[200:203], v[38:41]
	v_mfma_f32_16x16x32_bf16 v[30:33], v[156:159], v[208:211], v[30:33]
	v_mfma_f32_16x16x32_bf16 v[22:25], v[168:171], v[208:211], v[22:25]
	v_mfma_f32_16x16x32_bf16 v[14:17], v[156:159], v[216:219], v[14:17]
	v_mfma_f32_16x16x32_bf16 v[6:9], v[168:171], v[216:219], v[6:9]
	s_setprio 0
	s_setprio 3
	v_mfma_f32_16x16x32_bf16 v[58:61], v[172:175], v[188:191], v[58:61]
	v_mfma_f32_16x16x32_bf16 v[50:53], v[180:183], v[188:191], v[50:53]
	v_mfma_f32_16x16x32_bf16 v[42:45], v[172:175], v[196:199], v[42:45]
	v_mfma_f32_16x16x32_bf16 v[34:37], v[180:183], v[196:199], v[34:37]
	v_mfma_f32_16x16x32_bf16 v[26:29], v[172:175], v[204:207], v[26:29]
	v_mfma_f32_16x16x32_bf16 v[18:21], v[180:183], v[204:207], v[18:21]
	v_mfma_f32_16x16x32_bf16 v[10:13], v[172:175], v[212:215], v[10:13]
	v_mfma_f32_16x16x32_bf16 v[2:5], v[180:183], v[212:215], v[2:5]
	v_mfma_f32_16x16x32_bf16 v[58:61], v[176:179], v[192:195], v[58:61]
	v_mfma_f32_16x16x32_bf16 v[50:53], v[184:187], v[192:195], v[50:53]
	v_mfma_f32_16x16x32_bf16 v[42:45], v[176:179], v[200:203], v[42:45]
	v_mfma_f32_16x16x32_bf16 v[34:37], v[184:187], v[200:203], v[34:37]
	v_mfma_f32_16x16x32_bf16 v[26:29], v[176:179], v[208:211], v[26:29]
	v_mfma_f32_16x16x32_bf16 v[18:21], v[184:187], v[208:211], v[18:21]
	v_mfma_f32_16x16x32_bf16 v[10:13], v[176:179], v[216:219], v[10:13]
	s_barrier
	v_mfma_f32_16x16x32_bf16 v[2:5], v[184:187], v[216:219], v[2:5]
	s_setprio 0
	s_add_i32 s70, s70, 2
	s_add_u32 s48, s48, 0x100
	s_addc_u32 s49, s49, 0
	s_add_u32 s68, s68, 0x100
	s_addc_u32 s69, s69, 0
	s_cmp_gt_u32 s70, 29
	s_cbranch_scc0 .LBB0_70
	s_and_b64 vcc, exec, s[24:25]
	s_cbranch_vccz .LBB0_73
	s_barrier

; #define PG8_STAGE(bufoff, gbase, voff) do { _Pragma("unroll") for (int _i = 0; _i < 2; ++_i) \
;         __builtin_amdgcn_global_load_lds((const unsigned*)((const char*)(gbase) + (voff)[_i]), (PG8_LAS unsigned*)(lds + (bufoff) + ldsw + _i * 8192), 16, 0, 0); } while (0)
; #define PG8_LDA(dst, b, h) do { _Pragma("unroll") for (int m = 0; m < 4; ++m) _Pragma("unroll") for (int k = 0; k < 2; ++k) dst[m][k] = *(const PG8_LAS bf16x8*)(lds + PG8_SA(b, h) + aoff + m * 2048 + k * 1024); } while (0)
; #define PG8_LDB(dst, b, h) do { _Pragma("unroll") for (int n = 0; n < 2; ++n) _Pragma("unroll") for (int k = 0; k < 2; ++k) dst[n][k] = *(const PG8_LAS bf16x8*)(lds + PG8_SB(b, h) + boff + n * 2048 + k * 1024); } while (0)
; #define PG8_MMA(ai, bj, At, Bt) do { __builtin_amdgcn_s_setprio(3); _Pragma("unroll") for (int m = 0; m < 4; ++m) _Pragma("unroll") for (int n = 0; n < 2; ++n) _Pragma("unroll") for (int k = 0; k < 2; ++k) \
;         acc[ai][bj][m][n] = __builtin_amdgcn_mfma_f32_16x16x32_bf16(Bt[n][k], At[m][k], acc[ai][bj][m][n], 0, 0, 0); __builtin_amdgcn_s_setprio(0); } while (0)
; #define PG8_WAIT_V(n) asm volatile("s_waitcnt vmcnt(" #n ")" ::: "memory")
; #define PG8_WAIT_L(n) asm volatile("s_waitcnt lgkmcnt(" #n ")" ::: "memory")
; #define PG8_BAR __builtin_amdgcn_s_barrier()
; #define PG8_SCHED __builtin_amdgcn_sched_barrier(0)
; template <class Epi, class Sched, bool ALIGN_EPI = false, bool SP2 = false>
; __device__ __forceinline__ void gemm_phase(PG8_LAS unsigned char* lds, const Gemm g, const Sched& S, const Epi& E) {
;     ...
;             const bool last = (t == nt - 2);
;             const char* a1 = cA + (size_t)(t + 1) * kstep;
;             const char* a2 = last ? nA : cA + (size_t)(t + 2) * kstep; const char* b2 = last ? nB : cB + (size_t)(t + 2) * kstep;
;             const char* a3 = a2 + kstep; const char* b3 = b2 + kstep;
;             if (last && has_next) S.a_ready(nxt);
;             if constexpr (SP2) {
;             PG8_LDB(B0, 0, 0); PG8_LDB(B1, 0, 1); PG8_SCHED; PG8_LDA(At, 0, 0); PG8_STAGE(PG8_SA(1, 1), a1 + hstep, voffA);
;             PG8_WAIT_V(8); PG8_WAIT_L(0); PG8_BAR; PG8_MMA(0, 0, At, B0); PG8_MMA(0, 1, At, B1); PG8_BAR; PG8_SCHED;
;             PG8_LDA(At, 0, 1); PG8_STAGE(PG8_SB(0, 0), b2, voffB); PG8_STAGE(PG8_SB(0, 1), b2 + hstep, voffB); PG8_STAGE(PG8_SA(0, 0), a2, voffA);
.LBB0_179:
	ds_read_b128 v[148:151], v157
	ds_read_b128 v[152:155], v157 offset:1024
	ds_read_b128 v[160:163], v157 offset:2048
	ds_read_b128 v[168:171], v157 offset:3072
	ds_read_b128 v[172:175], v158
	ds_read_b128 v[176:179], v158 offset:1024
	ds_read_b128 v[180:183], v158 offset:2048
	ds_read_b128 v[184:187], v158 offset:3072
	s_add_i32 s79, s50, 2
	s_add_u32 s51, s8, 0xffea8080
	s_addc_u32 s52, s9, -1
	s_cmp_eq_u32 s76, s50
	s_cselect_b32 s50, s48, s77
	s_cselect_b32 s53, s47, s52
	s_cselect_b32 s52, s46, s51
	s_cselect_b32 s51, s49, s78
	v_lshl_add_u64 v[164:165], s[8:9], 0, v[138:139]
	s_add_i32 m0, s54, 0xc000
	ds_read_b128 v[188:191], v159
	ds_read_b128 v[192:195], v159 offset:1024
	ds_read_b128 v[196:199], v159 offset:2048
	ds_read_b128 v[200:203], v159 offset:3072
	ds_read_b128 v[204:207], v159 offset:4096
	ds_read_b128 v[208:211], v159 offset:5120
	ds_read_b128 v[212:215], v159 offset:6144
	ds_read_b128 v[216:219], v159 offset:7168
	global_load_lds_dwordx4 v[164:165], off
	v_lshl_add_u64 v[164:165], s[8:9], 0, v[142:143]
	s_add_i32 m0, s54, 0xe000
	s_nop 0
	global_load_lds_dwordx4 v[164:165], off
	s_waitcnt vmcnt(8)
	s_waitcnt lgkmcnt(0)
	s_barrier
	s_waitcnt lgkmcnt(0)
	v_mfma_f32_16x16x32_bf16 v[126:129], v[148:151], v[188:191], v[126:129]
	s_setprio 3
	v_mfma_f32_16x16x32_bf16 v[122:125], v[160:163], v[188:191], v[122:125]
	v_mfma_f32_16x16x32_bf16 v[114:117], v[148:151], v[196:199], v[114:117]
	v_mfma_f32_16x16x32_bf16 v[106:109], v[160:163], v[196:199], v[106:109]
	v_mfma_f32_16x16x32_bf16 v[98:101], v[148:151], v[204:207], v[98:101]
	v_mfma_f32_16x16x32_bf16 v[90:93], v[160:163], v[204:207], v[90:93]
	v_mfma_f32_16x16x32_bf16 v[82:85], v[148:151], v[212:215], v[82:85]
	v_mfma_f32_16x16x32_bf16 v[74:77], v[160:163], v[212:215], v[74:77]
	v_mfma_f32_16x16x32_bf16 v[126:129], v[152:155], v[192:195], v[126:129]
	v_mfma_f32_16x16x32_bf16 v[122:125], v[168:171], v[192:195], v[122:125]
	v_mfma_f32_16x16x32_bf16 v[114:117], v[152:155], v[200:203], v[114:117]
	v_mfma_f32_16x16x32_bf16 v[106:109], v[168:171], v[200:203], v[106:109]
	v_mfma_f32_16x16x32_bf16 v[98:101], v[152:155], v[208:211], v[98:101]
	v_mfma_f32_16x16x32_bf16 v[90:93], v[168:171], v[208:211], v[90:93]
	v_mfma_f32_16x16x32_bf16 v[82:85], v[152:155], v[216:219], v[82:85]
	v_mfma_f32_16x16x32_bf16 v[74:77], v[168:171], v[216:219], v[74:77]
	s_setprio 0
	s_setprio 3
	v_mfma_f32_16x16x32_bf16 v[118:121], v[172:175], v[188:191], v[118:121]
	v_mfma_f32_16x16x32_bf16 v[110:113], v[180:183], v[188:191], v[110:113]
	v_mfma_f32_16x16x32_bf16 v[102:105], v[172:175], v[196:199], v[102:105]
	v_mfma_f32_16x16x32_bf16 v[94:97], v[180:183], v[196:199], v[94:97]
	v_mfma_f32_16x16x32_bf16 v[86:89], v[172:175], v[204:207], v[86:89]
	v_mfma_f32_16x16x32_bf16 v[78:81], v[180:183], v[204:207], v[78:81]
	v_mfma_f32_16x16x32_bf16 v[70:73], v[172:175], v[212:215], v[70:73]
	v_mfma_f32_16x16x32_bf16 v[66:69], v[180:183], v[212:215], v[66:69]
	v_mfma_f32_16x16x32_bf16 v[118:121], v[176:179], v[192:195], v[118:121]
	v_mfma_f32_16x16x32_bf16 v[110:113], v[184:187], v[192:195], v[110:113]
	v_mfma_f32_16x16x32_bf16 v[102:105], v[176:179], v[200:203], v[102:105]
	v_mfma_f32_16x16x32_bf16 v[94:97], v[184:187], v[200:203], v[94:97]
	v_mfma_f32_16x16x32_bf16 v[86:89], v[176:179], v[208:211], v[86:89]
	v_mfma_f32_16x16x32_bf16 v[78:81], v[184:187], v[208:211], v[78:81]
	v_mfma_f32_16x16x32_bf16 v[70:73], v[176:179], v[216:219], v[70:73]
	s_barrier
	v_mfma_f32_16x16x32_bf16 v[66:69], v[184:187], v[216:219], v[66:69]
	s_setprio 0
	s_add_i32 s81, s65, s43
	v_lshl_add_u64 v[164:165], s[50:51], 0, v[132:133]
	s_mov_b32 m0, s81
	ds_read_b128 v[188:191], v159 offset:16384
	ds_read_b128 v[192:195], v159 offset:17408
	ds_read_b128 v[196:199], v159 offset:18432
	ds_read_b128 v[200:203], v159 offset:19456
	ds_read_b128 v[204:207], v159 offset:20480
	ds_read_b128 v[208:211], v159 offset:21504
	ds_read_b128 v[212:215], v159 offset:22528
	ds_read_b128 v[216:219], v159 offset:23552
	global_load_lds_dwordx4 v[164:165], off
	s_add_i32 m0, s81, 0x2000
	s_add_u32 s82, s50, 0x158000
	v_lshl_add_u64 v[220:221], s[50:51], 0, v[136:137]
	s_addc_u32 s83, s51, 0
	s_add_i32 s81, s67, s43
	global_load_lds_dwordx4 v[220:221], off
	v_lshl_add_u64 v[222:223], s[82:83], 0, v[132:133]
	s_mov_b32 m0, s81
	v_lshl_add_u64 v[224:225], s[52:53], 0, v[134:135]
	global_load_lds_dwordx4 v[222:223], off
	v_lshl_add_u64 v[222:223], s[82:83], 0, v[136:137]
	s_add_i32 m0, s81, 0x2000
	s_nop 0
	global_load_lds_dwordx4 v[222:223], off
	v_lshl_add_u64 v[222:223], s[52:53], 0, v[130:131]
	s_mov_b32 m0, s54
	s_nop 0
	global_load_lds_dwordx4 v[222:223], off
	s_mov_b32 m0, s55
	s_nop 0
	global_load_lds_dwordx4 v[224:225], off
	s_waitcnt vmcnt(8)
	s_waitcnt lgkmcnt(0)
	s_barrier
; #define PG8_STAGE(bufoff, gbase, voff) do { _Pragma("unroll") for (int _i = 0; _i < 2; ++_i) \
;         __builtin_amdgcn_global_load_lds((const unsigned*)((const char*)(gbase) + (voff)[_i]), (PG8_LAS unsigned*)(lds + (bufoff) + ldsw + _i * 8192), 16, 0, 0); } while (0)
; #define PG8_LDA(dst, b, h) do { _Pragma("unroll") for (int m = 0; m < 4; ++m) _Pragma("unroll") for (int k = 0; k < 2; ++k) dst[m][k] = *(const PG8_LAS bf16x8*)(lds + PG8_SA(b, h) + aoff + m * 2048 + k * 1024); } while (0)
; #define PG8_LDB(dst, b, h) do { _Pragma("unroll") for (int n = 0; n < 2; ++n) _Pragma("unroll") for (int k = 0; k < 2; ++k) dst[n][k] = *(const PG8_LAS bf16x8*)(lds + PG8_SB(b, h) + boff + n * 2048 + k * 1024); } while (0)
; #define PG8_MMA(ai, bj, At, Bt) do { __builtin_amdgcn_s_setprio(3); _Pragma("unroll") for (int m = 0; m < 4; ++m) _Pragma("unroll") for (int n = 0; n < 2; ++n) _Pragma("unroll") for (int k = 0; k < 2; ++k) \
;         acc[ai][bj][m][n] = __builtin_amdgcn_mfma_f32_16x16x32_bf16(Bt[n][k], At[m][k], acc[ai][bj][m][n], 0, 0, 0); __builtin_amdgcn_s_setprio(0); } while (0)
; #define PG8_WAIT_V(n) asm volatile("s_waitcnt vmcnt(" #n ")" ::: "memory")
; #define PG8_WAIT_L(n) asm volatile("s_waitcnt lgkmcnt(" #n ")" ::: "memory")
; #define PG8_BAR __builtin_amdgcn_s_barrier()
; #define PG8_SCHED __builtin_amdgcn_sched_barrier(0)
; template <class Epi, class Sched, bool ALIGN_EPI = false, bool SP2 = false>
; __device__ __forceinline__ void gemm_phase(PG8_LAS unsigned char* lds, const Gemm g, const Sched& S, const Epi& E) {
;     ...
;             PG8_WAIT_V(8); PG8_WAIT_L(0); PG8_BAR; PG8_MMA(1, 0, At, B0); PG8_MMA(1, 1, At, B1); PG8_BAR; PG8_SCHED;
;             PG8_LDB(B0, 1, 0); PG8_LDB(B1, 1, 1); PG8_SCHED; PG8_LDA(At, 1, 0); PG8_STAGE(PG8_SA(0, 1), a2 + hstep, voffA);
;             PG8_WAIT_V(8); PG8_WAIT_L(0); PG8_BAR; PG8_MMA(0, 0, At, B0); PG8_MMA(0, 1, At, B1); PG8_BAR; PG8_SCHED;
	s_waitcnt lgkmcnt(0)
	v_mfma_f32_16x16x32_bf16 v[62:65], v[148:151], v[188:191], v[62:65]
	s_setprio 3
	v_mfma_f32_16x16x32_bf16 v[58:61], v[160:163], v[188:191], v[58:61]
	v_mfma_f32_16x16x32_bf16 v[50:53], v[148:151], v[196:199], v[50:53]
	v_mfma_f32_16x16x32_bf16 v[42:45], v[160:163], v[196:199], v[42:45]
	v_mfma_f32_16x16x32_bf16 v[34:37], v[148:151], v[204:207], v[34:37]
	v_mfma_f32_16x16x32_bf16 v[26:29], v[160:163], v[204:207], v[26:29]
	v_mfma_f32_16x16x32_bf16 v[18:21], v[148:151], v[212:215], v[18:21]
	v_mfma_f32_16x16x32_bf16 v[10:13], v[160:163], v[212:215], v[10:13]
	v_mfma_f32_16x16x32_bf16 v[62:65], v[152:155], v[192:195], v[62:65]
	v_mfma_f32_16x16x32_bf16 v[58:61], v[168:171], v[192:195], v[58:61]
	v_mfma_f32_16x16x32_bf16 v[50:53], v[152:155], v[200:203], v[50:53]
	v_mfma_f32_16x16x32_bf16 v[42:45], v[168:171], v[200:203], v[42:45]
	v_mfma_f32_16x16x32_bf16 v[34:37], v[152:155], v[208:211], v[34:37]
	v_mfma_f32_16x16x32_bf16 v[26:29], v[168:171], v[208:211], v[26:29]
	v_mfma_f32_16x16x32_bf16 v[18:21], v[152:155], v[216:219], v[18:21]
	v_mfma_f32_16x16x32_bf16 v[10:13], v[168:171], v[216:219], v[10:13]
	s_setprio 0
	s_setprio 3
	v_mfma_f32_16x16x32_bf16 v[54:57], v[172:175], v[188:191], v[54:57]
	v_mfma_f32_16x16x32_bf16 v[46:49], v[180:183], v[188:191], v[46:49]
	v_mfma_f32_16x16x32_bf16 v[38:41], v[172:175], v[196:199], v[38:41]
	v_mfma_f32_16x16x32_bf16 v[30:33], v[180:183], v[196:199], v[30:33]
	v_mfma_f32_16x16x32_bf16 v[22:25], v[172:175], v[204:207], v[22:25]
	v_mfma_f32_16x16x32_bf16 v[14:17], v[180:183], v[204:207], v[14:17]
	v_mfma_f32_16x16x32_bf16 v[6:9], v[172:175], v[212:215], v[6:9]
	v_mfma_f32_16x16x32_bf16 v[2:5], v[180:183], v[212:215], v[2:5]
	v_mfma_f32_16x16x32_bf16 v[54:57], v[176:179], v[192:195], v[54:57]
	v_mfma_f32_16x16x32_bf16 v[46:49], v[184:187], v[192:195], v[46:49]
	v_mfma_f32_16x16x32_bf16 v[38:41], v[176:179], v[200:203], v[38:41]
	v_mfma_f32_16x16x32_bf16 v[30:33], v[184:187], v[200:203], v[30:33]
	v_mfma_f32_16x16x32_bf16 v[22:25], v[176:179], v[208:211], v[22:25]
	v_mfma_f32_16x16x32_bf16 v[14:17], v[184:187], v[208:211], v[14:17]
	v_mfma_f32_16x16x32_bf16 v[6:9], v[176:179], v[216:219], v[6:9]
	s_barrier
	v_mfma_f32_16x16x32_bf16 v[2:5], v[184:187], v[216:219], v[2:5]
	s_setprio 0
	s_add_i32 s81, 0, 0x18000
	v_add_u32_e32 v167, s81, v141
	s_add_i32 s82, 0, 0x1c000
	ds_read_b128 v[148:151], v167
	ds_read_b128 v[152:155], v167 offset:1024
	ds_read_b128 v[160:163], v167 offset:2048
	ds_read_b128 v[168:171], v167 offset:3072
	v_add_u32_e32 v167, s82, v141
	ds_read_b128 v[172:175], v167
	ds_read_b128 v[176:179], v167 offset:1024
	ds_read_b128 v[180:183], v167 offset:2048
	ds_read_b128 v[184:187], v167 offset:3072
	s_add_u32 s52, s52, 0x158000
	s_addc_u32 s53, s53, 0
	s_mov_b32 m0, s56
	v_lshl_add_u64 v[226:227], s[52:53], 0, v[130:131]
	ds_read_b128 v[188:191], v159 offset:32768
	ds_read_b128 v[192:195], v159 offset:33792
	ds_read_b128 v[196:199], v159 offset:34816
	ds_read_b128 v[200:203], v159 offset:35840
	ds_read_b128 v[204:207], v159 offset:36864
	ds_read_b128 v[208:211], v159 offset:37888
	ds_read_b128 v[212:215], v159 offset:38912
	ds_read_b128 v[216:219], v159 offset:39936
	global_load_lds_dwordx4 v[226:227], off
	v_lshl_add_u64 v[226:227], s[52:53], 0, v[134:135]
	s_mov_b32 m0, s57
	s_nop 0
	global_load_lds_dwordx4 v[226:227], off
	s_waitcnt vmcnt(8)
	s_waitcnt lgkmcnt(0)
	s_barrier
	s_waitcnt lgkmcnt(0)
	v_mfma_f32_16x16x32_bf16 v[126:129], v[148:151], v[188:191], v[126:129]
	s_setprio 3
	v_mfma_f32_16x16x32_bf16 v[122:125], v[160:163], v[188:191], v[122:125]
	v_mfma_f32_16x16x32_bf16 v[114:117], v[148:151], v[196:199], v[114:117]
	v_mfma_f32_16x16x32_bf16 v[106:109], v[160:163], v[196:199], v[106:109]
	v_mfma_f32_16x16x32_bf16 v[98:101], v[148:151], v[204:207], v[98:101]
	v_mfma_f32_16x16x32_bf16 v[90:93], v[160:163], v[204:207], v[90:93]
	v_mfma_f32_16x16x32_bf16 v[82:85], v[148:151], v[212:215], v[82:85]
	v_mfma_f32_16x16x32_bf16 v[74:77], v[160:163], v[212:215], v[74:77]
	v_mfma_f32_16x16x32_bf16 v[126:129], v[152:155], v[192:195], v[126:129]
	v_mfma_f32_16x16x32_bf16 v[122:125], v[168:171], v[192:195], v[122:125]
	v_mfma_f32_16x16x32_bf16 v[114:117], v[152:155], v[200:203], v[114:117]
	v_mfma_f32_16x16x32_bf16 v[106:109], v[168:171], v[200:203], v[106:109]
	v_mfma_f32_16x16x32_bf16 v[98:101], v[152:155], v[208:211], v[98:101]
	v_mfma_f32_16x16x32_bf16 v[90:93], v[168:171], v[208:211], v[90:93]
	v_mfma_f32_16x16x32_bf16 v[82:85], v[152:155], v[216:219], v[82:85]
	v_mfma_f32_16x16x32_bf16 v[74:77], v[168:171], v[216:219], v[74:77]
	s_setprio 0
	s_setprio 3
	v_mfma_f32_16x16x32_bf16 v[118:121], v[172:175], v[188:191], v[118:121]
	v_mfma_f32_16x16x32_bf16 v[110:113], v[180:183], v[188:191], v[110:113]
	v_mfma_f32_16x16x32_bf16 v[102:105], v[172:175], v[196:199], v[102:105]
	v_mfma_f32_16x16x32_bf16 v[94:97], v[180:183], v[196:199], v[94:97]
	v_mfma_f32_16x16x32_bf16 v[86:89], v[172:175], v[204:207], v[86:89]
	v_mfma_f32_16x16x32_bf16 v[78:81], v[180:183], v[204:207], v[78:81]
	v_mfma_f32_16x16x32_bf16 v[70:73], v[172:175], v[212:215], v[70:73]
	v_mfma_f32_16x16x32_bf16 v[66:69], v[180:183], v[212:215], v[66:69]
	v_mfma_f32_16x16x32_bf16 v[118:121], v[176:179], v[192:195], v[118:121]
	v_mfma_f32_16x16x32_bf16 v[110:113], v[184:187], v[192:195], v[110:113]
	v_mfma_f32_16x16x32_bf16 v[102:105], v[176:179], v[200:203], v[102:105]
	v_mfma_f32_16x16x32_bf16 v[94:97], v[184:187], v[200:203], v[94:97]
	v_mfma_f32_16x16x32_bf16 v[86:89], v[176:179], v[208:211], v[86:89]
	v_mfma_f32_16x16x32_bf16 v[78:81], v[184:187], v[208:211], v[78:81]
	v_mfma_f32_16x16x32_bf16 v[70:73], v[176:179], v[216:219], v[70:73]
	s_barrier
; #define PG8_STAGE(bufoff, gbase, voff) do { _Pragma("unroll") for (int _i = 0; _i < 2; ++_i) \
;         __builtin_amdgcn_global_load_lds((const unsigned*)((const char*)(gbase) + (voff)[_i]), (PG8_LAS unsigned*)(lds + (bufoff) + ldsw + _i * 8192), 16, 0, 0); } while (0)
; #define PG8_LDA(dst, b, h) do { _Pragma("unroll") for (int m = 0; m < 4; ++m) _Pragma("unroll") for (int k = 0; k < 2; ++k) dst[m][k] = *(const PG8_LAS bf16x8*)(lds + PG8_SA(b, h) + aoff + m * 2048 + k * 1024); } while (0)
; #define PG8_MMA(ai, bj, At, Bt) do { __builtin_amdgcn_s_setprio(3); _Pragma("unroll") for (int m = 0; m < 4; ++m) _Pragma("unroll") for (int n = 0; n < 2; ++n) _Pragma("unroll") for (int k = 0; k < 2; ++k) \
;         acc[ai][bj][m][n] = __builtin_amdgcn_mfma_f32_16x16x32_bf16(Bt[n][k], At[m][k], acc[ai][bj][m][n], 0, 0, 0); __builtin_amdgcn_s_setprio(0); } while (0)
; #define PG8_WAIT_V(n) asm volatile("s_waitcnt vmcnt(" #n ")" ::: "memory")
; #define PG8_WAIT_L(n) asm volatile("s_waitcnt lgkmcnt(" #n ")" ::: "memory")
; #define PG8_BAR __builtin_amdgcn_s_barrier()
; #define PG8_SCHED __builtin_amdgcn_sched_barrier(0)
; template <class Epi, class Sched, bool ALIGN_EPI = false, bool SP2 = false>
; __device__ __forceinline__ void gemm_phase(PG8_LAS unsigned char* lds, const Gemm g, const Sched& S, const Epi& E) {
;     ...
;         for (int t = 0; t < nt; t += 2) {
;     ...
;             PG8_WAIT_V(8); PG8_WAIT_L(0); PG8_BAR; PG8_MMA(0, 0, At, B0); PG8_MMA(0, 1, At, B1); PG8_BAR; PG8_SCHED;
;             PG8_LDA(At, 1, 1); PG8_STAGE(PG8_SB(1, 0), b3, voffB); PG8_STAGE(PG8_SB(1, 1), b3 + hstep, voffB); PG8_STAGE(PG8_SA(1, 0), a3, voffA);
;             PG8_WAIT_V(8); PG8_WAIT_L(0); PG8_BAR; PG8_MMA(1, 0, At, B0); PG8_MMA(1, 1, At, B1); PG8_BAR; PG8_SCHED;
	v_mfma_f32_16x16x32_bf16 v[66:69], v[184:187], v[216:219], v[66:69]
	s_setprio 0
	s_add_i32 s52, s81, s43
	v_lshl_add_u64 v[164:165], v[164:165], 0, s[18:19]
	s_mov_b32 m0, s52
	ds_read_b128 v[188:191], v159 offset:49152
	ds_read_b128 v[192:195], v159 offset:50176
	ds_read_b128 v[196:199], v159 offset:51200
	ds_read_b128 v[200:203], v159 offset:52224
	ds_read_b128 v[204:207], v159 offset:53248
	ds_read_b128 v[208:211], v159 offset:54272
	ds_read_b128 v[212:215], v159 offset:55296
	ds_read_b128 v[216:219], v159 offset:56320
	global_load_lds_dwordx4 v[164:165], off
	s_add_i32 m0, s52, 0x2000
	s_add_u32 s50, s50, 0x158080
	v_lshl_add_u64 v[164:165], v[220:221], 0, s[18:19]
	s_addc_u32 s51, s51, 0
	s_add_i32 s52, s82, s43
	global_load_lds_dwordx4 v[164:165], off
	v_lshl_add_u64 v[164:165], s[50:51], 0, v[132:133]
	s_mov_b32 m0, s52
	s_nop 0
	global_load_lds_dwordx4 v[164:165], off
	v_lshl_add_u64 v[164:165], s[50:51], 0, v[136:137]
	s_add_i32 m0, s52, 0x2000
	s_nop 0
	global_load_lds_dwordx4 v[164:165], off
	v_lshl_add_u64 v[164:165], v[222:223], 0, s[18:19]
	s_mov_b32 m0, s62
	s_nop 0
	global_load_lds_dwordx4 v[164:165], off
	v_lshl_add_u64 v[164:165], v[224:225], 0, s[18:19]
	s_mov_b32 m0, s63
	s_nop 0
	global_load_lds_dwordx4 v[164:165], off
	s_waitcnt vmcnt(8)
	s_waitcnt lgkmcnt(0)
	s_barrier
	s_waitcnt lgkmcnt(0)
	v_mfma_f32_16x16x32_bf16 v[62:65], v[148:151], v[188:191], v[62:65]
	s_setprio 3
	v_mfma_f32_16x16x32_bf16 v[58:61], v[160:163], v[188:191], v[58:61]
	v_mfma_f32_16x16x32_bf16 v[50:53], v[148:151], v[196:199], v[50:53]
	v_mfma_f32_16x16x32_bf16 v[42:45], v[160:163], v[196:199], v[42:45]
	v_mfma_f32_16x16x32_bf16 v[34:37], v[148:151], v[204:207], v[34:37]
	v_mfma_f32_16x16x32_bf16 v[26:29], v[160:163], v[204:207], v[26:29]
	v_mfma_f32_16x16x32_bf16 v[18:21], v[148:151], v[212:215], v[18:21]
	v_mfma_f32_16x16x32_bf16 v[10:13], v[160:163], v[212:215], v[10:13]
	v_mfma_f32_16x16x32_bf16 v[62:65], v[152:155], v[192:195], v[62:65]
	v_mfma_f32_16x16x32_bf16 v[58:61], v[168:171], v[192:195], v[58:61]
	v_mfma_f32_16x16x32_bf16 v[50:53], v[152:155], v[200:203], v[50:53]
	v_mfma_f32_16x16x32_bf16 v[42:45], v[168:171], v[200:203], v[42:45]
	v_mfma_f32_16x16x32_bf16 v[34:37], v[152:155], v[208:211], v[34:37]
	v_mfma_f32_16x16x32_bf16 v[26:29], v[168:171], v[208:211], v[26:29]
	v_mfma_f32_16x16x32_bf16 v[18:21], v[152:155], v[216:219], v[18:21]
	v_mfma_f32_16x16x32_bf16 v[10:13], v[168:171], v[216:219], v[10:13]
	s_setprio 0
	s_setprio 3
	v_mfma_f32_16x16x32_bf16 v[54:57], v[172:175], v[188:191], v[54:57]
	v_mfma_f32_16x16x32_bf16 v[46:49], v[180:183], v[188:191], v[46:49]
	v_mfma_f32_16x16x32_bf16 v[38:41], v[172:175], v[196:199], v[38:41]
	v_mfma_f32_16x16x32_bf16 v[30:33], v[180:183], v[196:199], v[30:33]
	v_mfma_f32_16x16x32_bf16 v[22:25], v[172:175], v[204:207], v[22:25]
	v_mfma_f32_16x16x32_bf16 v[14:17], v[180:183], v[204:207], v[14:17]
	v_mfma_f32_16x16x32_bf16 v[6:9], v[172:175], v[212:215], v[6:9]
	v_mfma_f32_16x16x32_bf16 v[2:5], v[180:183], v[212:215], v[2:5]
	v_mfma_f32_16x16x32_bf16 v[54:57], v[176:179], v[192:195], v[54:57]
	v_mfma_f32_16x16x32_bf16 v[46:49], v[184:187], v[192:195], v[46:49]
	v_mfma_f32_16x16x32_bf16 v[38:41], v[176:179], v[200:203], v[38:41]
	v_mfma_f32_16x16x32_bf16 v[30:33], v[184:187], v[200:203], v[30:33]
	v_mfma_f32_16x16x32_bf16 v[22:25], v[176:179], v[208:211], v[22:25]
	v_mfma_f32_16x16x32_bf16 v[14:17], v[184:187], v[208:211], v[14:17]
	v_mfma_f32_16x16x32_bf16 v[6:9], v[176:179], v[216:219], v[6:9]
	s_barrier
	v_mfma_f32_16x16x32_bf16 v[2:5], v[184:187], v[216:219], v[2:5]
	s_setprio 0
	s_add_u32 s8, s8, 0x100
	s_addc_u32 s9, s9, 0
	s_add_u32 s77, s77, 0x100
	s_addc_u32 s78, s78, 0
	s_cmp_ge_u32 s79, s75
	s_mov_b32 s50, s79
	s_cbranch_scc0 .LBB0_179
	s_and_b64 vcc, exec, s[24:25]
	s_cbranch_vccz .LBB0_182
	s_barrier

; #define PG8_STAGE(bufoff, gbase, voff) do { _Pragma("unroll") for (int _i = 0; _i < 2; ++_i) \
;         __builtin_amdgcn_global_load_lds((const unsigned*)((const char*)(gbase) + (voff)[_i]), (PG8_LAS unsigned*)(lds + (bufoff) + ldsw + _i * 8192), 16, 0, 0); } while (0)
; #define PG8_LDA(dst, b, h) do { _Pragma("unroll") for (int m = 0; m < 4; ++m) _Pragma("unroll") for (int k = 0; k < 2; ++k) dst[m][k] = *(const PG8_LAS bf16x8*)(lds + PG8_SA(b, h) + aoff + m * 2048 + k * 1024); } while (0)
; #define PG8_LDB(dst, b, h) do { _Pragma("unroll") for (int n = 0; n < 2; ++n) _Pragma("unroll") for (int k = 0; k < 2; ++k) dst[n][k] = *(const PG8_LAS bf16x8*)(lds + PG8_SB(b, h) + boff + n * 2048 + k * 1024); } while (0)
; #define PG8_MMA(ai, bj, At, Bt) do { __builtin_amdgcn_s_setprio(3); _Pragma("unroll") for (int m = 0; m < 4; ++m) _Pragma("unroll") for (int n = 0; n < 2; ++n) _Pragma("unroll") for (int k = 0; k < 2; ++k) \
;         acc[ai][bj][m][n] = __builtin_amdgcn_mfma_f32_16x16x32_bf16(Bt[n][k], At[m][k], acc[ai][bj][m][n], 0, 0, 0); __builtin_amdgcn_s_setprio(0); } while (0)
; #define PG8_WAIT_V(n) asm volatile("s_waitcnt vmcnt(" #n ")" ::: "memory")
; #define PG8_WAIT_L(n) asm volatile("s_waitcnt lgkmcnt(" #n ")" ::: "memory")
; #define PG8_BAR __builtin_amdgcn_s_barrier()
; #define PG8_SCHED __builtin_amdgcn_sched_barrier(0)
; template <class Epi, class Sched, bool ALIGN_EPI = false, bool SP2 = false>
; __device__ __forceinline__ void gemm_phase(PG8_LAS unsigned char* lds, const Gemm g, const Sched& S, const Epi& E) {
;     ...
;             const bool last = (t == nt - 2);
;             const char* a1 = cA + (size_t)(t + 1) * kstep;
;             const char* a2 = last ? nA : cA + (size_t)(t + 2) * kstep; const char* b2 = last ? nB : cB + (size_t)(t + 2) * kstep;
;             const char* a3 = a2 + kstep; const char* b3 = b2 + kstep;
;             if (last && has_next) S.a_ready(nxt);
;             if constexpr (SP2) {
;             PG8_LDB(B0, 0, 0); PG8_LDB(B1, 0, 1); PG8_SCHED; PG8_LDA(At, 0, 0); PG8_STAGE(PG8_SA(1, 1), a1 + hstep, voffA);
;             PG8_WAIT_V(8); PG8_WAIT_L(0); PG8_BAR; PG8_MMA(0, 0, At, B0); PG8_MMA(0, 1, At, B1); PG8_BAR; PG8_SCHED;
;             PG8_LDA(At, 0, 1); PG8_STAGE(PG8_SB(0, 0), b2, voffB); PG8_STAGE(PG8_SB(0, 1), b2 + hstep, voffB); PG8_STAGE(PG8_SA(0, 0), a2, voffA);
.LBB0_394:
	ds_read_b128 v[148:151], v155
	ds_read_b128 v[158:161], v155 offset:1024
	ds_read_b128 v[162:165], v155 offset:2048
	ds_read_b128 v[168:171], v155 offset:3072
	ds_read_b128 v[172:175], v156
	ds_read_b128 v[176:179], v156 offset:1024
	ds_read_b128 v[180:183], v156 offset:2048
	ds_read_b128 v[184:187], v156 offset:3072
	s_add_u32 s48, s46, 0xfff80080
	s_addc_u32 s49, s47, -1
	s_cmp_eq_u32 s70, 28
	s_cselect_b32 s51, s7, s49
	s_cselect_b32 s50, s27, s48
	s_cselect_b32 s49, s25, s69
	s_cselect_b32 s48, s45, s68
	v_lshl_add_u64 v[152:153], s[46:47], 0, v[138:139]
	s_add_i32 m0, s52, 0xc000
	ds_read_b128 v[188:191], v157
	ds_read_b128 v[192:195], v157 offset:1024
	ds_read_b128 v[196:199], v157 offset:2048
	ds_read_b128 v[200:203], v157 offset:3072
	ds_read_b128 v[204:207], v157 offset:4096
	ds_read_b128 v[208:211], v157 offset:5120
	ds_read_b128 v[212:215], v157 offset:6144
	ds_read_b128 v[216:219], v157 offset:7168
	global_load_lds_dwordx4 v[152:153], off
	v_lshl_add_u64 v[152:153], s[46:47], 0, v[142:143]
	s_add_i32 m0, s52, 0xe000
	s_nop 0
	global_load_lds_dwordx4 v[152:153], off
	s_waitcnt vmcnt(8)
	s_waitcnt lgkmcnt(0)
	s_barrier
	s_waitcnt lgkmcnt(0)
	v_mfma_f32_16x16x32_bf16 v[126:129], v[148:151], v[188:191], v[126:129]
	s_setprio 3
	v_mfma_f32_16x16x32_bf16 v[122:125], v[162:165], v[188:191], v[122:125]
	v_mfma_f32_16x16x32_bf16 v[114:117], v[148:151], v[196:199], v[114:117]
	v_mfma_f32_16x16x32_bf16 v[106:109], v[162:165], v[196:199], v[106:109]
	v_mfma_f32_16x16x32_bf16 v[98:101], v[148:151], v[204:207], v[98:101]
	v_mfma_f32_16x16x32_bf16 v[90:93], v[162:165], v[204:207], v[90:93]
	v_mfma_f32_16x16x32_bf16 v[82:85], v[148:151], v[212:215], v[82:85]
	v_mfma_f32_16x16x32_bf16 v[74:77], v[162:165], v[212:215], v[74:77]
	v_mfma_f32_16x16x32_bf16 v[126:129], v[158:161], v[192:195], v[126:129]
	v_mfma_f32_16x16x32_bf16 v[122:125], v[168:171], v[192:195], v[122:125]
	v_mfma_f32_16x16x32_bf16 v[114:117], v[158:161], v[200:203], v[114:117]
	v_mfma_f32_16x16x32_bf16 v[106:109], v[168:171], v[200:203], v[106:109]
	v_mfma_f32_16x16x32_bf16 v[98:101], v[158:161], v[208:211], v[98:101]
	v_mfma_f32_16x16x32_bf16 v[90:93], v[168:171], v[208:211], v[90:93]
	v_mfma_f32_16x16x32_bf16 v[82:85], v[158:161], v[216:219], v[82:85]
	v_mfma_f32_16x16x32_bf16 v[74:77], v[168:171], v[216:219], v[74:77]
	s_setprio 0
	s_setprio 3
	v_mfma_f32_16x16x32_bf16 v[118:121], v[172:175], v[188:191], v[118:121]
	v_mfma_f32_16x16x32_bf16 v[110:113], v[180:183], v[188:191], v[110:113]
	v_mfma_f32_16x16x32_bf16 v[102:105], v[172:175], v[196:199], v[102:105]
	v_mfma_f32_16x16x32_bf16 v[94:97], v[180:183], v[196:199], v[94:97]
	v_mfma_f32_16x16x32_bf16 v[86:89], v[172:175], v[204:207], v[86:89]
	v_mfma_f32_16x16x32_bf16 v[78:81], v[180:183], v[204:207], v[78:81]
	v_mfma_f32_16x16x32_bf16 v[70:73], v[172:175], v[212:215], v[70:73]
	v_mfma_f32_16x16x32_bf16 v[66:69], v[180:183], v[212:215], v[66:69]
	v_mfma_f32_16x16x32_bf16 v[118:121], v[176:179], v[192:195], v[118:121]
	v_mfma_f32_16x16x32_bf16 v[110:113], v[184:187], v[192:195], v[110:113]
	v_mfma_f32_16x16x32_bf16 v[102:105], v[176:179], v[200:203], v[102:105]
	v_mfma_f32_16x16x32_bf16 v[94:97], v[184:187], v[200:203], v[94:97]
	v_mfma_f32_16x16x32_bf16 v[86:89], v[176:179], v[208:211], v[86:89]
	v_mfma_f32_16x16x32_bf16 v[78:81], v[184:187], v[208:211], v[78:81]
	v_mfma_f32_16x16x32_bf16 v[70:73], v[176:179], v[216:219], v[70:73]
	s_barrier
	v_mfma_f32_16x16x32_bf16 v[66:69], v[184:187], v[216:219], v[66:69]
	s_setprio 0
	s_add_i32 s71, s63, s43
	v_lshl_add_u64 v[152:153], s[48:49], 0, v[132:133]
	s_mov_b32 m0, s71
	ds_read_b128 v[188:191], v157 offset:16384
	ds_read_b128 v[192:195], v157 offset:17408
	ds_read_b128 v[196:199], v157 offset:18432
	ds_read_b128 v[200:203], v157 offset:19456
	ds_read_b128 v[204:207], v157 offset:20480
	ds_read_b128 v[208:211], v157 offset:21504
	ds_read_b128 v[212:215], v157 offset:22528
	ds_read_b128 v[216:219], v157 offset:23552
	global_load_lds_dwordx4 v[152:153], off
	s_add_i32 m0, s71, 0x2000
	s_add_u32 s72, s48, 0x80000
	v_lshl_add_u64 v[220:221], s[48:49], 0, v[136:137]
	s_addc_u32 s73, s49, 0
	s_add_i32 s71, s64, s43
	global_load_lds_dwordx4 v[220:221], off
	v_lshl_add_u64 v[222:223], s[72:73], 0, v[132:133]
	s_mov_b32 m0, s71
	v_lshl_add_u64 v[224:225], s[50:51], 0, v[134:135]
	global_load_lds_dwordx4 v[222:223], off
	v_lshl_add_u64 v[222:223], s[72:73], 0, v[136:137]
	s_add_i32 m0, s71, 0x2000
	s_nop 0
	global_load_lds_dwordx4 v[222:223], off
	v_lshl_add_u64 v[222:223], s[50:51], 0, v[130:131]
	s_mov_b32 m0, s52
	s_nop 0
	global_load_lds_dwordx4 v[222:223], off
	s_mov_b32 m0, s53
	s_nop 0
	global_load_lds_dwordx4 v[224:225], off
	s_waitcnt vmcnt(8)
	s_waitcnt lgkmcnt(0)
	s_barrier
; #define PG8_STAGE(bufoff, gbase, voff) do { _Pragma("unroll") for (int _i = 0; _i < 2; ++_i) \
;         __builtin_amdgcn_global_load_lds((const unsigned*)((const char*)(gbase) + (voff)[_i]), (PG8_LAS unsigned*)(lds + (bufoff) + ldsw + _i * 8192), 16, 0, 0); } while (0)
; #define PG8_LDA(dst, b, h) do { _Pragma("unroll") for (int m = 0; m < 4; ++m) _Pragma("unroll") for (int k = 0; k < 2; ++k) dst[m][k] = *(const PG8_LAS bf16x8*)(lds + PG8_SA(b, h) + aoff + m * 2048 + k * 1024); } while (0)
; #define PG8_LDB(dst, b, h) do { _Pragma("unroll") for (int n = 0; n < 2; ++n) _Pragma("unroll") for (int k = 0; k < 2; ++k) dst[n][k] = *(const PG8_LAS bf16x8*)(lds + PG8_SB(b, h) + boff + n * 2048 + k * 1024); } while (0)
; #define PG8_MMA(ai, bj, At, Bt) do { __builtin_amdgcn_s_setprio(3); _Pragma("unroll") for (int m = 0; m < 4; ++m) _Pragma("unroll") for (int n = 0; n < 2; ++n) _Pragma("unroll") for (int k = 0; k < 2; ++k) \
;         acc[ai][bj][m][n] = __builtin_amdgcn_mfma_f32_16x16x32_bf16(Bt[n][k], At[m][k], acc[ai][bj][m][n], 0, 0, 0); __builtin_amdgcn_s_setprio(0); } while (0)
; #define PG8_WAIT_V(n) asm volatile("s_waitcnt vmcnt(" #n ")" ::: "memory")
; #define PG8_WAIT_L(n) asm volatile("s_waitcnt lgkmcnt(" #n ")" ::: "memory")
; #define PG8_BAR __builtin_amdgcn_s_barrier()
; #define PG8_SCHED __builtin_amdgcn_sched_barrier(0)
; template <class Epi, class Sched, bool ALIGN_EPI = false, bool SP2 = false>
; __device__ __forceinline__ void gemm_phase(PG8_LAS unsigned char* lds, const Gemm g, const Sched& S, const Epi& E) {
;     ...
;             PG8_WAIT_V(8); PG8_WAIT_L(0); PG8_BAR; PG8_MMA(1, 0, At, B0); PG8_MMA(1, 1, At, B1); PG8_BAR; PG8_SCHED;
;             PG8_LDB(B0, 1, 0); PG8_LDB(B1, 1, 1); PG8_SCHED; PG8_LDA(At, 1, 0); PG8_STAGE(PG8_SA(0, 1), a2 + hstep, voffA);
;             PG8_WAIT_V(8); PG8_WAIT_L(0); PG8_BAR; PG8_MMA(0, 0, At, B0); PG8_MMA(0, 1, At, B1); PG8_BAR; PG8_SCHED;
	s_waitcnt lgkmcnt(0)
	v_mfma_f32_16x16x32_bf16 v[62:65], v[148:151], v[188:191], v[62:65]
	s_setprio 3
	v_mfma_f32_16x16x32_bf16 v[58:61], v[162:165], v[188:191], v[58:61]
	v_mfma_f32_16x16x32_bf16 v[50:53], v[148:151], v[196:199], v[50:53]
	v_mfma_f32_16x16x32_bf16 v[42:45], v[162:165], v[196:199], v[42:45]
	v_mfma_f32_16x16x32_bf16 v[34:37], v[148:151], v[204:207], v[34:37]
	v_mfma_f32_16x16x32_bf16 v[26:29], v[162:165], v[204:207], v[26:29]
	v_mfma_f32_16x16x32_bf16 v[18:21], v[148:151], v[212:215], v[18:21]
	v_mfma_f32_16x16x32_bf16 v[10:13], v[162:165], v[212:215], v[10:13]
	v_mfma_f32_16x16x32_bf16 v[62:65], v[158:161], v[192:195], v[62:65]
	v_mfma_f32_16x16x32_bf16 v[58:61], v[168:171], v[192:195], v[58:61]
	v_mfma_f32_16x16x32_bf16 v[50:53], v[158:161], v[200:203], v[50:53]
	v_mfma_f32_16x16x32_bf16 v[42:45], v[168:171], v[200:203], v[42:45]
	v_mfma_f32_16x16x32_bf16 v[34:37], v[158:161], v[208:211], v[34:37]
	v_mfma_f32_16x16x32_bf16 v[26:29], v[168:171], v[208:211], v[26:29]
	v_mfma_f32_16x16x32_bf16 v[18:21], v[158:161], v[216:219], v[18:21]
	v_mfma_f32_16x16x32_bf16 v[10:13], v[168:171], v[216:219], v[10:13]
	s_setprio 0
	s_setprio 3
	v_mfma_f32_16x16x32_bf16 v[54:57], v[172:175], v[188:191], v[54:57]
	v_mfma_f32_16x16x32_bf16 v[46:49], v[180:183], v[188:191], v[46:49]
	v_mfma_f32_16x16x32_bf16 v[38:41], v[172:175], v[196:199], v[38:41]
	v_mfma_f32_16x16x32_bf16 v[30:33], v[180:183], v[196:199], v[30:33]
	v_mfma_f32_16x16x32_bf16 v[22:25], v[172:175], v[204:207], v[22:25]
	v_mfma_f32_16x16x32_bf16 v[14:17], v[180:183], v[204:207], v[14:17]
	v_mfma_f32_16x16x32_bf16 v[6:9], v[172:175], v[212:215], v[6:9]
	v_mfma_f32_16x16x32_bf16 v[2:5], v[180:183], v[212:215], v[2:5]
	v_mfma_f32_16x16x32_bf16 v[54:57], v[176:179], v[192:195], v[54:57]
	v_mfma_f32_16x16x32_bf16 v[46:49], v[184:187], v[192:195], v[46:49]
	v_mfma_f32_16x16x32_bf16 v[38:41], v[176:179], v[200:203], v[38:41]
	v_mfma_f32_16x16x32_bf16 v[30:33], v[184:187], v[200:203], v[30:33]
	v_mfma_f32_16x16x32_bf16 v[22:25], v[176:179], v[208:211], v[22:25]
	v_mfma_f32_16x16x32_bf16 v[14:17], v[184:187], v[208:211], v[14:17]
	v_mfma_f32_16x16x32_bf16 v[6:9], v[176:179], v[216:219], v[6:9]
	s_barrier
	v_mfma_f32_16x16x32_bf16 v[2:5], v[184:187], v[216:219], v[2:5]
	s_setprio 0
	s_add_i32 s71, 0, 0x18000
	v_add_u32_e32 v167, s71, v141
	s_add_i32 s72, 0, 0x1c000
	ds_read_b128 v[148:151], v167
	ds_read_b128 v[158:161], v167 offset:1024
	ds_read_b128 v[162:165], v167 offset:2048
	ds_read_b128 v[168:171], v167 offset:3072
	v_add_u32_e32 v167, s72, v141
	ds_read_b128 v[172:175], v167
	ds_read_b128 v[176:179], v167 offset:1024
	ds_read_b128 v[180:183], v167 offset:2048
	ds_read_b128 v[184:187], v167 offset:3072
	s_add_u32 s50, s50, 0x80000
	s_addc_u32 s51, s51, 0
	s_mov_b32 m0, s54
	v_lshl_add_u64 v[226:227], s[50:51], 0, v[130:131]
	ds_read_b128 v[188:191], v157 offset:32768
	ds_read_b128 v[192:195], v157 offset:33792
	ds_read_b128 v[196:199], v157 offset:34816
	ds_read_b128 v[200:203], v157 offset:35840
	ds_read_b128 v[204:207], v157 offset:36864
	ds_read_b128 v[208:211], v157 offset:37888
	ds_read_b128 v[212:215], v157 offset:38912
	ds_read_b128 v[216:219], v157 offset:39936
	global_load_lds_dwordx4 v[226:227], off
	v_lshl_add_u64 v[226:227], s[50:51], 0, v[134:135]
	s_mov_b32 m0, s55
	s_nop 0
	global_load_lds_dwordx4 v[226:227], off
	s_waitcnt vmcnt(8)
	s_waitcnt lgkmcnt(0)
	s_barrier
	s_waitcnt lgkmcnt(0)
	v_mfma_f32_16x16x32_bf16 v[126:129], v[148:151], v[188:191], v[126:129]
	s_setprio 3
	v_mfma_f32_16x16x32_bf16 v[122:125], v[162:165], v[188:191], v[122:125]
	v_mfma_f32_16x16x32_bf16 v[114:117], v[148:151], v[196:199], v[114:117]
	v_mfma_f32_16x16x32_bf16 v[106:109], v[162:165], v[196:199], v[106:109]
	v_mfma_f32_16x16x32_bf16 v[98:101], v[148:151], v[204:207], v[98:101]
	v_mfma_f32_16x16x32_bf16 v[90:93], v[162:165], v[204:207], v[90:93]
	v_mfma_f32_16x16x32_bf16 v[82:85], v[148:151], v[212:215], v[82:85]
	v_mfma_f32_16x16x32_bf16 v[74:77], v[162:165], v[212:215], v[74:77]
	v_mfma_f32_16x16x32_bf16 v[126:129], v[158:161], v[192:195], v[126:129]
	v_mfma_f32_16x16x32_bf16 v[122:125], v[168:171], v[192:195], v[122:125]
	v_mfma_f32_16x16x32_bf16 v[114:117], v[158:161], v[200:203], v[114:117]
	v_mfma_f32_16x16x32_bf16 v[106:109], v[168:171], v[200:203], v[106:109]
	v_mfma_f32_16x16x32_bf16 v[98:101], v[158:161], v[208:211], v[98:101]
	v_mfma_f32_16x16x32_bf16 v[90:93], v[168:171], v[208:211], v[90:93]
	v_mfma_f32_16x16x32_bf16 v[82:85], v[158:161], v[216:219], v[82:85]
	v_mfma_f32_16x16x32_bf16 v[74:77], v[168:171], v[216:219], v[74:77]
	s_setprio 0
	s_setprio 3
	v_mfma_f32_16x16x32_bf16 v[118:121], v[172:175], v[188:191], v[118:121]
	v_mfma_f32_16x16x32_bf16 v[110:113], v[180:183], v[188:191], v[110:113]
	v_mfma_f32_16x16x32_bf16 v[102:105], v[172:175], v[196:199], v[102:105]
	v_mfma_f32_16x16x32_bf16 v[94:97], v[180:183], v[196:199], v[94:97]
	v_mfma_f32_16x16x32_bf16 v[86:89], v[172:175], v[204:207], v[86:89]
	v_mfma_f32_16x16x32_bf16 v[78:81], v[180:183], v[204:207], v[78:81]
	v_mfma_f32_16x16x32_bf16 v[70:73], v[172:175], v[212:215], v[70:73]
	v_mfma_f32_16x16x32_bf16 v[66:69], v[180:183], v[212:215], v[66:69]
	v_mfma_f32_16x16x32_bf16 v[118:121], v[176:179], v[192:195], v[118:121]
	v_mfma_f32_16x16x32_bf16 v[110:113], v[184:187], v[192:195], v[110:113]
	v_mfma_f32_16x16x32_bf16 v[102:105], v[176:179], v[200:203], v[102:105]
	v_mfma_f32_16x16x32_bf16 v[94:97], v[184:187], v[200:203], v[94:97]
	v_mfma_f32_16x16x32_bf16 v[86:89], v[176:179], v[208:211], v[86:89]
	v_mfma_f32_16x16x32_bf16 v[78:81], v[184:187], v[208:211], v[78:81]
	v_mfma_f32_16x16x32_bf16 v[70:73], v[176:179], v[216:219], v[70:73]
	s_barrier
; #define PG8_STAGE(bufoff, gbase, voff) do { _Pragma("unroll") for (int _i = 0; _i < 2; ++_i) \
;         __builtin_amdgcn_global_load_lds((const unsigned*)((const char*)(gbase) + (voff)[_i]), (PG8_LAS unsigned*)(lds + (bufoff) + ldsw + _i * 8192), 16, 0, 0); } while (0)
; #define PG8_LDA(dst, b, h) do { _Pragma("unroll") for (int m = 0; m < 4; ++m) _Pragma("unroll") for (int k = 0; k < 2; ++k) dst[m][k] = *(const PG8_LAS bf16x8*)(lds + PG8_SA(b, h) + aoff + m * 2048 + k * 1024); } while (0)
; #define PG8_MMA(ai, bj, At, Bt) do { __builtin_amdgcn_s_setprio(3); _Pragma("unroll") for (int m = 0; m < 4; ++m) _Pragma("unroll") for (int n = 0; n < 2; ++n) _Pragma("unroll") for (int k = 0; k < 2; ++k) \
;         acc[ai][bj][m][n] = __builtin_amdgcn_mfma_f32_16x16x32_bf16(Bt[n][k], At[m][k], acc[ai][bj][m][n], 0, 0, 0); __builtin_amdgcn_s_setprio(0); } while (0)
; #define PG8_WAIT_V(n) asm volatile("s_waitcnt vmcnt(" #n ")" ::: "memory")
; #define PG8_WAIT_L(n) asm volatile("s_waitcnt lgkmcnt(" #n ")" ::: "memory")
; #define PG8_BAR __builtin_amdgcn_s_barrier()
; #define PG8_SCHED __builtin_amdgcn_sched_barrier(0)
; template <class Epi, class Sched, bool ALIGN_EPI = false, bool SP2 = false>
; __device__ __forceinline__ void gemm_phase(PG8_LAS unsigned char* lds, const Gemm g, const Sched& S, const Epi& E) {
;     ...
;         for (int t = 0; t < nt; t += 2) {
;     ...
;             PG8_WAIT_V(8); PG8_WAIT_L(0); PG8_BAR; PG8_MMA(0, 0, At, B0); PG8_MMA(0, 1, At, B1); PG8_BAR; PG8_SCHED;
;             PG8_LDA(At, 1, 1); PG8_STAGE(PG8_SB(1, 0), b3, voffB); PG8_STAGE(PG8_SB(1, 1), b3 + hstep, voffB); PG8_STAGE(PG8_SA(1, 0), a3, voffA);
;             PG8_WAIT_V(8); PG8_WAIT_L(0); PG8_BAR; PG8_MMA(1, 0, At, B0); PG8_MMA(1, 1, At, B1); PG8_BAR; PG8_SCHED;
	v_mfma_f32_16x16x32_bf16 v[66:69], v[184:187], v[216:219], v[66:69]
	s_setprio 0
	s_add_i32 s50, s71, s43
	v_lshl_add_u64 v[152:153], v[152:153], 0, s[16:17]
	s_mov_b32 m0, s50
	ds_read_b128 v[188:191], v157 offset:49152
	ds_read_b128 v[192:195], v157 offset:50176
	ds_read_b128 v[196:199], v157 offset:51200
	ds_read_b128 v[200:203], v157 offset:52224
	ds_read_b128 v[204:207], v157 offset:53248
	ds_read_b128 v[208:211], v157 offset:54272
	ds_read_b128 v[212:215], v157 offset:55296
	ds_read_b128 v[216:219], v157 offset:56320
	global_load_lds_dwordx4 v[152:153], off
	s_add_i32 m0, s50, 0x2000
	s_add_u32 s48, s48, 0x80080
	v_lshl_add_u64 v[152:153], v[220:221], 0, s[16:17]
	s_addc_u32 s49, s49, 0
	s_add_i32 s50, s72, s43
	global_load_lds_dwordx4 v[152:153], off
	v_lshl_add_u64 v[152:153], s[48:49], 0, v[132:133]
	s_mov_b32 m0, s50
	s_nop 0
	global_load_lds_dwordx4 v[152:153], off
	v_lshl_add_u64 v[152:153], s[48:49], 0, v[136:137]
	s_add_i32 m0, s50, 0x2000
	s_nop 0
	global_load_lds_dwordx4 v[152:153], off
	v_lshl_add_u64 v[152:153], v[222:223], 0, s[16:17]
	s_mov_b32 m0, s59
	s_nop 0
	global_load_lds_dwordx4 v[152:153], off
	v_lshl_add_u64 v[152:153], v[224:225], 0, s[16:17]
	s_mov_b32 m0, s60
	s_nop 0
	global_load_lds_dwordx4 v[152:153], off
	s_waitcnt vmcnt(8)
	s_waitcnt lgkmcnt(0)
	s_barrier
	s_waitcnt lgkmcnt(0)
	v_mfma_f32_16x16x32_bf16 v[62:65], v[148:151], v[188:191], v[62:65]
	s_setprio 3
	v_mfma_f32_16x16x32_bf16 v[58:61], v[162:165], v[188:191], v[58:61]
	v_mfma_f32_16x16x32_bf16 v[50:53], v[148:151], v[196:199], v[50:53]
	v_mfma_f32_16x16x32_bf16 v[42:45], v[162:165], v[196:199], v[42:45]
	v_mfma_f32_16x16x32_bf16 v[34:37], v[148:151], v[204:207], v[34:37]
	v_mfma_f32_16x16x32_bf16 v[26:29], v[162:165], v[204:207], v[26:29]
	v_mfma_f32_16x16x32_bf16 v[18:21], v[148:151], v[212:215], v[18:21]
	v_mfma_f32_16x16x32_bf16 v[10:13], v[162:165], v[212:215], v[10:13]
	v_mfma_f32_16x16x32_bf16 v[62:65], v[158:161], v[192:195], v[62:65]
	v_mfma_f32_16x16x32_bf16 v[58:61], v[168:171], v[192:195], v[58:61]
	v_mfma_f32_16x16x32_bf16 v[50:53], v[158:161], v[200:203], v[50:53]
	v_mfma_f32_16x16x32_bf16 v[42:45], v[168:171], v[200:203], v[42:45]
	v_mfma_f32_16x16x32_bf16 v[34:37], v[158:161], v[208:211], v[34:37]
	v_mfma_f32_16x16x32_bf16 v[26:29], v[168:171], v[208:211], v[26:29]
	v_mfma_f32_16x16x32_bf16 v[18:21], v[158:161], v[216:219], v[18:21]
	v_mfma_f32_16x16x32_bf16 v[10:13], v[168:171], v[216:219], v[10:13]
	s_setprio 0
	s_setprio 3
	v_mfma_f32_16x16x32_bf16 v[54:57], v[172:175], v[188:191], v[54:57]
	v_mfma_f32_16x16x32_bf16 v[46:49], v[180:183], v[188:191], v[46:49]
	v_mfma_f32_16x16x32_bf16 v[38:41], v[172:175], v[196:199], v[38:41]
	v_mfma_f32_16x16x32_bf16 v[30:33], v[180:183], v[196:199], v[30:33]
	v_mfma_f32_16x16x32_bf16 v[22:25], v[172:175], v[204:207], v[22:25]
	v_mfma_f32_16x16x32_bf16 v[14:17], v[180:183], v[204:207], v[14:17]
	v_mfma_f32_16x16x32_bf16 v[6:9], v[172:175], v[212:215], v[6:9]
	v_mfma_f32_16x16x32_bf16 v[2:5], v[180:183], v[212:215], v[2:5]
	v_mfma_f32_16x16x32_bf16 v[54:57], v[176:179], v[192:195], v[54:57]
	v_mfma_f32_16x16x32_bf16 v[46:49], v[184:187], v[192:195], v[46:49]
	v_mfma_f32_16x16x32_bf16 v[38:41], v[176:179], v[200:203], v[38:41]
	v_mfma_f32_16x16x32_bf16 v[30:33], v[184:187], v[200:203], v[30:33]
	v_mfma_f32_16x16x32_bf16 v[22:25], v[176:179], v[208:211], v[22:25]
	v_mfma_f32_16x16x32_bf16 v[14:17], v[184:187], v[208:211], v[14:17]
	v_mfma_f32_16x16x32_bf16 v[6:9], v[176:179], v[216:219], v[6:9]
	s_barrier
	v_mfma_f32_16x16x32_bf16 v[2:5], v[184:187], v[216:219], v[2:5]
	s_setprio 0
	s_add_i32 s70, s70, 2
	s_add_u32 s46, s46, 0x100
	s_addc_u32 s47, s47, 0
	s_add_u32 s68, s68, 0x100
	s_addc_u32 s69, s69, 0
	s_cmp_gt_u32 s70, 29
	s_cbranch_scc0 .LBB0_394
	s_and_b64 vcc, exec, s[18:19]
	s_cbranch_vccz .LBB0_397
	s_barrier

; #define PG8_STAGE(bufoff, gbase, voff) do { _Pragma("unroll") for (int _i = 0; _i < 2; ++_i) \
;         __builtin_amdgcn_global_load_lds((const unsigned*)((const char*)(gbase) + (voff)[_i]), (PG8_LAS unsigned*)(lds + (bufoff) + ldsw + _i * 8192), 16, 0, 0); } while (0)
; #define PG8_LDA(dst, b, h) do { _Pragma("unroll") for (int m = 0; m < 4; ++m) _Pragma("unroll") for (int k = 0; k < 2; ++k) dst[m][k] = *(const PG8_LAS bf16x8*)(lds + PG8_SA(b, h) + aoff + m * 2048 + k * 1024); } while (0)
; #define PG8_LDB(dst, b, h) do { _Pragma("unroll") for (int n = 0; n < 2; ++n) _Pragma("unroll") for (int k = 0; k < 2; ++k) dst[n][k] = *(const PG8_LAS bf16x8*)(lds + PG8_SB(b, h) + boff + n * 2048 + k * 1024); } while (0)
; #define PG8_MMA(ai, bj, At, Bt) do { __builtin_amdgcn_s_setprio(3); _Pragma("unroll") for (int m = 0; m < 4; ++m) _Pragma("unroll") for (int n = 0; n < 2; ++n) _Pragma("unroll") for (int k = 0; k < 2; ++k) \
;         acc[ai][bj][m][n] = __builtin_amdgcn_mfma_f32_16x16x32_bf16(Bt[n][k], At[m][k], acc[ai][bj][m][n], 0, 0, 0); __builtin_amdgcn_s_setprio(0); } while (0)
; #define PG8_WAIT_V(n) asm volatile("s_waitcnt vmcnt(" #n ")" ::: "memory")
; #define PG8_WAIT_L(n) asm volatile("s_waitcnt lgkmcnt(" #n ")" ::: "memory")
; #define PG8_BAR __builtin_amdgcn_s_barrier()
; #define PG8_SCHED __builtin_amdgcn_sched_barrier(0)
; template <class Epi, class Sched, bool ALIGN_EPI = false, bool SP2 = false>
; __device__ __forceinline__ void gemm_phase(PG8_LAS unsigned char* lds, const Gemm g, const Sched& S, const Epi& E) {
;     ...
;             const bool last = (t == nt - 2);
;             const char* a1 = cA + (size_t)(t + 1) * kstep;
;             const char* a2 = last ? nA : cA + (size_t)(t + 2) * kstep; const char* b2 = last ? nB : cB + (size_t)(t + 2) * kstep;
;             const char* a3 = a2 + kstep; const char* b3 = b2 + kstep;
;             if (last && has_next) S.a_ready(nxt);
;             if constexpr (SP2) {
;             PG8_LDB(B0, 0, 0); PG8_LDB(B1, 0, 1); PG8_SCHED; PG8_LDA(At, 0, 0); PG8_STAGE(PG8_SA(1, 1), a1 + hstep, voffA);
;             PG8_WAIT_V(8); PG8_WAIT_L(0); PG8_BAR; PG8_MMA(0, 0, At, B0); PG8_MMA(0, 1, At, B1); PG8_BAR; PG8_SCHED;
;             PG8_LDA(At, 0, 1); PG8_STAGE(PG8_SB(0, 0), b2, voffB); PG8_STAGE(PG8_SB(0, 1), b2 + hstep, voffB); PG8_STAGE(PG8_SA(0, 0), a2, voffA);
.LBB0_677:
	ds_read_b128 v[132:135], v168
	ds_read_b128 v[136:139], v168 offset:1024
	ds_read_b128 v[158:161], v168 offset:2048
	ds_read_b128 v[162:165], v168 offset:3072
	ds_read_b128 v[172:175], v169
	ds_read_b128 v[176:179], v169 offset:1024
	ds_read_b128 v[180:183], v169 offset:2048
	ds_read_b128 v[184:187], v169 offset:3072
	s_add_i32 s74, s48, 2
	s_add_u32 s75, s6, 0x80
	s_addc_u32 s49, s7, 0
	s_cmp_eq_u32 s73, s48
	s_cselect_b32 s48, s44, s75
	s_cselect_b32 s49, s45, s49
	s_cselect_b32 s77, s47, s51
	s_cselect_b32 s76, s46, s50
	v_lshl_add_u64 v[74:75], s[6:7], 0, v[150:151]
	s_add_i32 m0, s54, 0xc000
	ds_read_b128 v[188:191], v170
	ds_read_b128 v[192:195], v170 offset:1024
	ds_read_b128 v[196:199], v170 offset:2048
	ds_read_b128 v[200:203], v170 offset:3072
	ds_read_b128 v[204:207], v170 offset:4096
	ds_read_b128 v[208:211], v170 offset:5120
	ds_read_b128 v[212:215], v170 offset:6144
	ds_read_b128 v[216:219], v170 offset:7168
	global_load_lds_dwordx4 v[74:75], off
	v_lshl_add_u64 v[74:75], s[6:7], 0, v[152:153]
	s_add_i32 m0, s54, 0xe000
	s_nop 0
	global_load_lds_dwordx4 v[74:75], off
	s_waitcnt vmcnt(8)
	s_waitcnt lgkmcnt(0)
	s_barrier
	s_waitcnt lgkmcnt(0)
	v_mfma_f32_16x16x32_bf16 v[128:131], v[132:135], v[188:191], v[128:131]
	s_setprio 3
	v_mfma_f32_16x16x32_bf16 v[124:127], v[158:161], v[188:191], v[124:127]
	v_mfma_f32_16x16x32_bf16 v[120:123], v[132:135], v[196:199], v[120:123]
	v_mfma_f32_16x16x32_bf16 v[116:119], v[158:161], v[196:199], v[116:119]
	v_mfma_f32_16x16x32_bf16 v[112:115], v[132:135], v[204:207], v[112:115]
	v_mfma_f32_16x16x32_bf16 v[108:111], v[158:161], v[204:207], v[108:111]
	v_mfma_f32_16x16x32_bf16 v[104:107], v[132:135], v[212:215], v[104:107]
	v_mfma_f32_16x16x32_bf16 v[100:103], v[158:161], v[212:215], v[100:103]
	v_mfma_f32_16x16x32_bf16 v[128:131], v[136:139], v[192:195], v[128:131]
	v_mfma_f32_16x16x32_bf16 v[124:127], v[162:165], v[192:195], v[124:127]
	v_mfma_f32_16x16x32_bf16 v[120:123], v[136:139], v[200:203], v[120:123]
	v_mfma_f32_16x16x32_bf16 v[116:119], v[162:165], v[200:203], v[116:119]
	v_mfma_f32_16x16x32_bf16 v[112:115], v[136:139], v[208:211], v[112:115]
	v_mfma_f32_16x16x32_bf16 v[108:111], v[162:165], v[208:211], v[108:111]
	v_mfma_f32_16x16x32_bf16 v[104:107], v[136:139], v[216:219], v[104:107]
	v_mfma_f32_16x16x32_bf16 v[100:103], v[162:165], v[216:219], v[100:103]
	s_setprio 0
	s_setprio 3
	v_mfma_f32_16x16x32_bf16 v[62:65], v[172:175], v[188:191], v[62:65]
	v_mfma_f32_16x16x32_bf16 v[58:61], v[180:183], v[188:191], v[58:61]
	v_mfma_f32_16x16x32_bf16 v[54:57], v[172:175], v[196:199], v[54:57]
	v_mfma_f32_16x16x32_bf16 v[50:53], v[180:183], v[196:199], v[50:53]
	v_mfma_f32_16x16x32_bf16 v[46:49], v[172:175], v[204:207], v[46:49]
	v_mfma_f32_16x16x32_bf16 v[42:45], v[180:183], v[204:207], v[42:45]
	v_mfma_f32_16x16x32_bf16 v[38:41], v[172:175], v[212:215], v[38:41]
	v_mfma_f32_16x16x32_bf16 v[34:37], v[180:183], v[212:215], v[34:37]
	v_mfma_f32_16x16x32_bf16 v[62:65], v[176:179], v[192:195], v[62:65]
	v_mfma_f32_16x16x32_bf16 v[58:61], v[184:187], v[192:195], v[58:61]
	v_mfma_f32_16x16x32_bf16 v[54:57], v[176:179], v[200:203], v[54:57]
	v_mfma_f32_16x16x32_bf16 v[50:53], v[184:187], v[200:203], v[50:53]
	v_mfma_f32_16x16x32_bf16 v[46:49], v[176:179], v[208:211], v[46:49]
	v_mfma_f32_16x16x32_bf16 v[42:45], v[184:187], v[208:211], v[42:45]
	v_mfma_f32_16x16x32_bf16 v[38:41], v[176:179], v[216:219], v[38:41]
	s_barrier
	v_mfma_f32_16x16x32_bf16 v[34:37], v[184:187], v[216:219], v[34:37]
	s_setprio 0
	s_add_i32 s75, s63, s43
	v_lshl_add_u64 v[220:221], s[76:77], 0, v[146:147]
	s_mov_b32 m0, s75
	ds_read_b128 v[188:191], v170 offset:16384
	ds_read_b128 v[192:195], v170 offset:17408
	ds_read_b128 v[196:199], v170 offset:18432
	ds_read_b128 v[200:203], v170 offset:19456
	ds_read_b128 v[204:207], v170 offset:20480
	ds_read_b128 v[208:211], v170 offset:21504
	ds_read_b128 v[212:215], v170 offset:22528
	ds_read_b128 v[216:219], v170 offset:23552
	global_load_lds_dwordx4 v[220:221], off
	s_add_i32 m0, s75, 0x2000
	v_lshl_add_u64 v[222:223], s[76:77], 0, v[142:143]
	s_add_u32 s76, s76, s14
	s_addc_u32 s77, s77, s15
	s_add_i32 s75, s64, s43
	global_load_lds_dwordx4 v[222:223], off
	v_lshl_add_u64 v[224:225], s[76:77], 0, v[146:147]
	s_mov_b32 m0, s75
	v_lshl_add_u64 v[226:227], s[76:77], 0, v[142:143]
	global_load_lds_dwordx4 v[224:225], off
	s_add_i32 m0, s75, 0x2000
	v_lshl_add_u64 v[228:229], s[48:49], 0, v[148:149]
	global_load_lds_dwordx4 v[226:227], off
	s_mov_b32 m0, s54
	v_lshl_add_u64 v[230:231], s[48:49], 0, v[144:145]
	global_load_lds_dwordx4 v[228:229], off
	s_mov_b32 m0, s55
	s_nop 0
	global_load_lds_dwordx4 v[230:231], off
	s_waitcnt vmcnt(8)
	s_waitcnt lgkmcnt(0)
	s_barrier
; #define PG8_STAGE(bufoff, gbase, voff) do { _Pragma("unroll") for (int _i = 0; _i < 2; ++_i) \
;         __builtin_amdgcn_global_load_lds((const unsigned*)((const char*)(gbase) + (voff)[_i]), (PG8_LAS unsigned*)(lds + (bufoff) + ldsw + _i * 8192), 16, 0, 0); } while (0)
; #define PG8_LDA(dst, b, h) do { _Pragma("unroll") for (int m = 0; m < 4; ++m) _Pragma("unroll") for (int k = 0; k < 2; ++k) dst[m][k] = *(const PG8_LAS bf16x8*)(lds + PG8_SA(b, h) + aoff + m * 2048 + k * 1024); } while (0)
; #define PG8_LDB(dst, b, h) do { _Pragma("unroll") for (int n = 0; n < 2; ++n) _Pragma("unroll") for (int k = 0; k < 2; ++k) dst[n][k] = *(const PG8_LAS bf16x8*)(lds + PG8_SB(b, h) + boff + n * 2048 + k * 1024); } while (0)
; #define PG8_MMA(ai, bj, At, Bt) do { __builtin_amdgcn_s_setprio(3); _Pragma("unroll") for (int m = 0; m < 4; ++m) _Pragma("unroll") for (int n = 0; n < 2; ++n) _Pragma("unroll") for (int k = 0; k < 2; ++k) \
;         acc[ai][bj][m][n] = __builtin_amdgcn_mfma_f32_16x16x32_bf16(Bt[n][k], At[m][k], acc[ai][bj][m][n], 0, 0, 0); __builtin_amdgcn_s_setprio(0); } while (0)
; #define PG8_WAIT_V(n) asm volatile("s_waitcnt vmcnt(" #n ")" ::: "memory")
; #define PG8_WAIT_L(n) asm volatile("s_waitcnt lgkmcnt(" #n ")" ::: "memory")
; #define PG8_BAR __builtin_amdgcn_s_barrier()
; #define PG8_SCHED __builtin_amdgcn_sched_barrier(0)
; template <class Epi, class Sched, bool ALIGN_EPI = false, bool SP2 = false>
; __device__ __forceinline__ void gemm_phase(PG8_LAS unsigned char* lds, const Gemm g, const Sched& S, const Epi& E) {
;     ...
;             PG8_WAIT_V(8); PG8_WAIT_L(0); PG8_BAR; PG8_MMA(1, 0, At, B0); PG8_MMA(1, 1, At, B1); PG8_BAR; PG8_SCHED;
;             PG8_LDB(B0, 1, 0); PG8_LDB(B1, 1, 1); PG8_SCHED; PG8_LDA(At, 1, 0); PG8_STAGE(PG8_SA(0, 1), a2 + hstep, voffA);
;             PG8_WAIT_V(8); PG8_WAIT_L(0); PG8_BAR; PG8_MMA(0, 0, At, B0); PG8_MMA(0, 1, At, B1); PG8_BAR; PG8_SCHED;
	s_waitcnt lgkmcnt(0)
	v_mfma_f32_16x16x32_bf16 v[96:99], v[132:135], v[188:191], v[96:99]
	s_setprio 3
	v_mfma_f32_16x16x32_bf16 v[92:95], v[158:161], v[188:191], v[92:95]
	v_mfma_f32_16x16x32_bf16 v[88:91], v[132:135], v[196:199], v[88:91]
	v_mfma_f32_16x16x32_bf16 v[84:87], v[158:161], v[196:199], v[84:87]
	v_mfma_f32_16x16x32_bf16 v[80:83], v[132:135], v[204:207], v[80:83]
	v_mfma_f32_16x16x32_bf16 v[74:77], v[158:161], v[204:207], v[76:79]
	v_mfma_f32_16x16x32_bf16 v[70:73], v[132:135], v[212:215], v[70:73]
	v_mfma_f32_16x16x32_bf16 v[66:69], v[158:161], v[212:215], v[66:69]
	v_mfma_f32_16x16x32_bf16 v[96:99], v[136:139], v[192:195], v[96:99]
	v_mfma_f32_16x16x32_bf16 v[92:95], v[162:165], v[192:195], v[92:95]
	v_mfma_f32_16x16x32_bf16 v[88:91], v[136:139], v[200:203], v[88:91]
	v_mfma_f32_16x16x32_bf16 v[84:87], v[162:165], v[200:203], v[84:87]
	v_mfma_f32_16x16x32_bf16 v[80:83], v[136:139], v[208:211], v[80:83]
	v_mfma_f32_16x16x32_bf16 v[74:77], v[162:165], v[208:211], v[74:77]
	v_mfma_f32_16x16x32_bf16 v[70:73], v[136:139], v[216:219], v[70:73]
	v_mfma_f32_16x16x32_bf16 v[66:69], v[162:165], v[216:219], v[66:69]
	s_setprio 0
	s_setprio 3
	v_mfma_f32_16x16x32_bf16 v[30:33], v[172:175], v[188:191], v[30:33]
	v_mfma_f32_16x16x32_bf16 v[26:29], v[180:183], v[188:191], v[26:29]
	v_mfma_f32_16x16x32_bf16 v[22:25], v[172:175], v[196:199], v[22:25]
	v_mfma_f32_16x16x32_bf16 v[18:21], v[180:183], v[196:199], v[18:21]
	v_mfma_f32_16x16x32_bf16 v[14:17], v[172:175], v[204:207], v[14:17]
	v_mfma_f32_16x16x32_bf16 v[10:13], v[180:183], v[204:207], v[10:13]
	v_mfma_f32_16x16x32_bf16 v[6:9], v[172:175], v[212:215], v[6:9]
	v_mfma_f32_16x16x32_bf16 v[2:5], v[180:183], v[212:215], v[2:5]
	v_mfma_f32_16x16x32_bf16 v[30:33], v[176:179], v[192:195], v[30:33]
	v_mfma_f32_16x16x32_bf16 v[26:29], v[184:187], v[192:195], v[26:29]
	v_mfma_f32_16x16x32_bf16 v[22:25], v[176:179], v[200:203], v[22:25]
	v_mfma_f32_16x16x32_bf16 v[18:21], v[184:187], v[200:203], v[18:21]
	v_mfma_f32_16x16x32_bf16 v[14:17], v[176:179], v[208:211], v[14:17]
	v_mfma_f32_16x16x32_bf16 v[10:13], v[184:187], v[208:211], v[10:13]
	v_mfma_f32_16x16x32_bf16 v[6:9], v[176:179], v[216:219], v[6:9]
	s_barrier
	v_mfma_f32_16x16x32_bf16 v[2:5], v[184:187], v[216:219], v[2:5]
	s_setprio 0
	s_add_i32 s75, 0, 0x18000
	v_add_u32_e32 v78, s75, v141
	s_add_i32 s76, 0, 0x1c000
	ds_read_b128 v[132:135], v78
	ds_read_b128 v[136:139], v78 offset:1024
	ds_read_b128 v[158:161], v78 offset:2048
	ds_read_b128 v[162:165], v78 offset:3072
	v_add_u32_e32 v78, s76, v141
	ds_read_b128 v[172:175], v78
	ds_read_b128 v[176:179], v78 offset:1024
	ds_read_b128 v[180:183], v78 offset:2048
	ds_read_b128 v[184:187], v78 offset:3072
	s_add_u32 s48, s48, s14
	s_addc_u32 s49, s49, s15
	s_mov_b32 m0, s56
	v_lshl_add_u64 v[78:79], s[48:49], 0, v[148:149]
	ds_read_b128 v[188:191], v170 offset:32768
	ds_read_b128 v[192:195], v170 offset:33792
	ds_read_b128 v[196:199], v170 offset:34816
	ds_read_b128 v[200:203], v170 offset:35840
	ds_read_b128 v[204:207], v170 offset:36864
	ds_read_b128 v[208:211], v170 offset:37888
	ds_read_b128 v[212:215], v170 offset:38912
	ds_read_b128 v[216:219], v170 offset:39936
	global_load_lds_dwordx4 v[78:79], off
	v_lshl_add_u64 v[78:79], s[48:49], 0, v[144:145]
	s_mov_b32 m0, s57
	s_nop 0
	global_load_lds_dwordx4 v[78:79], off
	s_waitcnt vmcnt(8)
	s_waitcnt lgkmcnt(0)
	s_barrier
	s_waitcnt lgkmcnt(0)
	v_mfma_f32_16x16x32_bf16 v[128:131], v[132:135], v[188:191], v[128:131]
	s_setprio 3
	v_mfma_f32_16x16x32_bf16 v[124:127], v[158:161], v[188:191], v[124:127]
	v_mfma_f32_16x16x32_bf16 v[120:123], v[132:135], v[196:199], v[120:123]
	v_mfma_f32_16x16x32_bf16 v[116:119], v[158:161], v[196:199], v[116:119]
	v_mfma_f32_16x16x32_bf16 v[112:115], v[132:135], v[204:207], v[112:115]
	v_mfma_f32_16x16x32_bf16 v[108:111], v[158:161], v[204:207], v[108:111]
	v_mfma_f32_16x16x32_bf16 v[104:107], v[132:135], v[212:215], v[104:107]
	v_mfma_f32_16x16x32_bf16 v[100:103], v[158:161], v[212:215], v[100:103]
	v_mfma_f32_16x16x32_bf16 v[128:131], v[136:139], v[192:195], v[128:131]
	v_mfma_f32_16x16x32_bf16 v[124:127], v[162:165], v[192:195], v[124:127]
	v_mfma_f32_16x16x32_bf16 v[120:123], v[136:139], v[200:203], v[120:123]
	v_mfma_f32_16x16x32_bf16 v[116:119], v[162:165], v[200:203], v[116:119]
	v_mfma_f32_16x16x32_bf16 v[112:115], v[136:139], v[208:211], v[112:115]
	v_mfma_f32_16x16x32_bf16 v[108:111], v[162:165], v[208:211], v[108:111]
	v_mfma_f32_16x16x32_bf16 v[104:107], v[136:139], v[216:219], v[104:107]
	v_mfma_f32_16x16x32_bf16 v[100:103], v[162:165], v[216:219], v[100:103]
	s_setprio 0
	s_setprio 3
	v_mfma_f32_16x16x32_bf16 v[62:65], v[172:175], v[188:191], v[62:65]
	v_mfma_f32_16x16x32_bf16 v[58:61], v[180:183], v[188:191], v[58:61]
	v_mfma_f32_16x16x32_bf16 v[54:57], v[172:175], v[196:199], v[54:57]
	v_mfma_f32_16x16x32_bf16 v[50:53], v[180:183], v[196:199], v[50:53]
	v_mfma_f32_16x16x32_bf16 v[46:49], v[172:175], v[204:207], v[46:49]
	v_mfma_f32_16x16x32_bf16 v[42:45], v[180:183], v[204:207], v[42:45]
	v_mfma_f32_16x16x32_bf16 v[38:41], v[172:175], v[212:215], v[38:41]
	v_mfma_f32_16x16x32_bf16 v[34:37], v[180:183], v[212:215], v[34:37]
	v_mfma_f32_16x16x32_bf16 v[62:65], v[176:179], v[192:195], v[62:65]
	v_mfma_f32_16x16x32_bf16 v[58:61], v[184:187], v[192:195], v[58:61]
	v_mfma_f32_16x16x32_bf16 v[54:57], v[176:179], v[200:203], v[54:57]
	v_mfma_f32_16x16x32_bf16 v[50:53], v[184:187], v[200:203], v[50:53]
	v_mfma_f32_16x16x32_bf16 v[46:49], v[176:179], v[208:211], v[46:49]
	v_mfma_f32_16x16x32_bf16 v[42:45], v[184:187], v[208:211], v[42:45]
	v_mfma_f32_16x16x32_bf16 v[38:41], v[176:179], v[216:219], v[38:41]
	s_barrier
; #define PG8_STAGE(bufoff, gbase, voff) do { _Pragma("unroll") for (int _i = 0; _i < 2; ++_i) \
;         __builtin_amdgcn_global_load_lds((const unsigned*)((const char*)(gbase) + (voff)[_i]), (PG8_LAS unsigned*)(lds + (bufoff) + ldsw + _i * 8192), 16, 0, 0); } while (0)
; #define PG8_LDA(dst, b, h) do { _Pragma("unroll") for (int m = 0; m < 4; ++m) _Pragma("unroll") for (int k = 0; k < 2; ++k) dst[m][k] = *(const PG8_LAS bf16x8*)(lds + PG8_SA(b, h) + aoff + m * 2048 + k * 1024); } while (0)
; #define PG8_MMA(ai, bj, At, Bt) do { __builtin_amdgcn_s_setprio(3); _Pragma("unroll") for (int m = 0; m < 4; ++m) _Pragma("unroll") for (int n = 0; n < 2; ++n) _Pragma("unroll") for (int k = 0; k < 2; ++k) \
;         acc[ai][bj][m][n] = __builtin_amdgcn_mfma_f32_16x16x32_bf16(Bt[n][k], At[m][k], acc[ai][bj][m][n], 0, 0, 0); __builtin_amdgcn_s_setprio(0); } while (0)
; #define PG8_WAIT_V(n) asm volatile("s_waitcnt vmcnt(" #n ")" ::: "memory")
; #define PG8_WAIT_L(n) asm volatile("s_waitcnt lgkmcnt(" #n ")" ::: "memory")
; #define PG8_BAR __builtin_amdgcn_s_barrier()
; #define PG8_SCHED __builtin_amdgcn_sched_barrier(0)
; template <class Epi, class Sched, bool ALIGN_EPI = false, bool SP2 = false>
; __device__ __forceinline__ void gemm_phase(PG8_LAS unsigned char* lds, const Gemm g, const Sched& S, const Epi& E) {
;     ...
;         for (int t = 0; t < nt; t += 2) {
;     ...
;             PG8_WAIT_V(8); PG8_WAIT_L(0); PG8_BAR; PG8_MMA(0, 0, At, B0); PG8_MMA(0, 1, At, B1); PG8_BAR; PG8_SCHED;
;             PG8_LDA(At, 1, 1); PG8_STAGE(PG8_SB(1, 0), b3, voffB); PG8_STAGE(PG8_SB(1, 1), b3 + hstep, voffB); PG8_STAGE(PG8_SA(1, 0), a3, voffA);
;             PG8_WAIT_V(8); PG8_WAIT_L(0); PG8_BAR; PG8_MMA(1, 0, At, B0); PG8_MMA(1, 1, At, B1); PG8_BAR; PG8_SCHED;
	v_mfma_f32_16x16x32_bf16 v[34:37], v[184:187], v[216:219], v[34:37]
	s_setprio 0
	s_add_i32 s48, s75, s43
	v_lshl_add_u64 v[78:79], v[220:221], 0, s[28:29]
	s_mov_b32 m0, s48
	ds_read_b128 v[188:191], v170 offset:49152
	ds_read_b128 v[192:195], v170 offset:50176
	ds_read_b128 v[196:199], v170 offset:51200
	ds_read_b128 v[200:203], v170 offset:52224
	ds_read_b128 v[204:207], v170 offset:53248
	ds_read_b128 v[208:211], v170 offset:54272
	ds_read_b128 v[212:215], v170 offset:55296
	ds_read_b128 v[216:219], v170 offset:56320
	global_load_lds_dwordx4 v[78:79], off
	v_lshl_add_u64 v[78:79], v[222:223], 0, s[28:29]
	s_add_i32 m0, s48, 0x2000
	s_add_i32 s48, s76, s43
	global_load_lds_dwordx4 v[78:79], off
	v_lshl_add_u64 v[78:79], v[224:225], 0, s[28:29]
	s_mov_b32 m0, s48
	s_nop 0
	global_load_lds_dwordx4 v[78:79], off
	v_lshl_add_u64 v[78:79], v[226:227], 0, s[28:29]
	s_add_i32 m0, s48, 0x2000
	s_nop 0
	global_load_lds_dwordx4 v[78:79], off
	v_lshl_add_u64 v[78:79], v[228:229], 0, s[28:29]
	s_mov_b32 m0, s60
	s_nop 0
	global_load_lds_dwordx4 v[78:79], off
	v_lshl_add_u64 v[78:79], v[230:231], 0, s[28:29]
	s_mov_b32 m0, s61
	s_nop 0
	global_load_lds_dwordx4 v[78:79], off
	s_waitcnt vmcnt(8)
	s_waitcnt lgkmcnt(0)
	s_barrier
	s_waitcnt lgkmcnt(0)
	v_mfma_f32_16x16x32_bf16 v[96:99], v[132:135], v[188:191], v[96:99]
	s_setprio 3
	v_mfma_f32_16x16x32_bf16 v[92:95], v[158:161], v[188:191], v[92:95]
	v_mfma_f32_16x16x32_bf16 v[88:91], v[132:135], v[196:199], v[88:91]
	v_mfma_f32_16x16x32_bf16 v[84:87], v[158:161], v[196:199], v[84:87]
	v_mfma_f32_16x16x32_bf16 v[78:81], v[132:135], v[204:207], v[80:83]
	v_mfma_f32_16x16x32_bf16 v[74:77], v[158:161], v[204:207], v[74:77]
	v_mfma_f32_16x16x32_bf16 v[70:73], v[132:135], v[212:215], v[70:73]
	v_mfma_f32_16x16x32_bf16 v[66:69], v[158:161], v[212:215], v[66:69]
	v_mfma_f32_16x16x32_bf16 v[96:99], v[136:139], v[192:195], v[96:99]
	v_mfma_f32_16x16x32_bf16 v[92:95], v[162:165], v[192:195], v[92:95]
	v_mfma_f32_16x16x32_bf16 v[88:91], v[136:139], v[200:203], v[88:91]
	v_mfma_f32_16x16x32_bf16 v[84:87], v[162:165], v[200:203], v[84:87]
	v_mfma_f32_16x16x32_bf16 v[80:83], v[136:139], v[208:211], v[78:81]
	v_mfma_f32_16x16x32_bf16 v[76:79], v[162:165], v[208:211], v[74:77]
	v_mfma_f32_16x16x32_bf16 v[70:73], v[136:139], v[216:219], v[70:73]
	v_mfma_f32_16x16x32_bf16 v[66:69], v[162:165], v[216:219], v[66:69]
	s_setprio 0
	s_setprio 3
	v_mfma_f32_16x16x32_bf16 v[30:33], v[172:175], v[188:191], v[30:33]
	v_mfma_f32_16x16x32_bf16 v[26:29], v[180:183], v[188:191], v[26:29]
	v_mfma_f32_16x16x32_bf16 v[22:25], v[172:175], v[196:199], v[22:25]
	v_mfma_f32_16x16x32_bf16 v[18:21], v[180:183], v[196:199], v[18:21]
	v_mfma_f32_16x16x32_bf16 v[14:17], v[172:175], v[204:207], v[14:17]
	v_mfma_f32_16x16x32_bf16 v[10:13], v[180:183], v[204:207], v[10:13]
	v_mfma_f32_16x16x32_bf16 v[6:9], v[172:175], v[212:215], v[6:9]
	v_mfma_f32_16x16x32_bf16 v[2:5], v[180:183], v[212:215], v[2:5]
	v_mfma_f32_16x16x32_bf16 v[30:33], v[176:179], v[192:195], v[30:33]
	v_mfma_f32_16x16x32_bf16 v[26:29], v[184:187], v[192:195], v[26:29]
	v_mfma_f32_16x16x32_bf16 v[22:25], v[176:179], v[200:203], v[22:25]
	v_mfma_f32_16x16x32_bf16 v[18:21], v[184:187], v[200:203], v[18:21]
	v_mfma_f32_16x16x32_bf16 v[14:17], v[176:179], v[208:211], v[14:17]
	v_mfma_f32_16x16x32_bf16 v[10:13], v[184:187], v[208:211], v[10:13]
	v_mfma_f32_16x16x32_bf16 v[6:9], v[176:179], v[216:219], v[6:9]
	s_barrier
	v_mfma_f32_16x16x32_bf16 v[2:5], v[184:187], v[216:219], v[2:5]
	s_setprio 0
	s_add_u32 s6, s6, 0x100
	s_addc_u32 s7, s7, 0
	s_add_u32 s50, s50, 0x100
	s_addc_u32 s51, s51, 0
	s_cmp_ge_u32 s74, s72
	s_mov_b32 s48, s74
	s_cbranch_scc0 .LBB0_677
	s_and_b64 vcc, exec, s[30:31]
	s_cbranch_vccz .LBB0_680
	s_barrier

; #define PG8_STAGE(bufoff, gbase, voff) do { _Pragma("unroll") for (int _i = 0; _i < 2; ++_i) \
;         __builtin_amdgcn_global_load_lds((const unsigned*)((const char*)(gbase) + (voff)[_i]), (PG8_LAS unsigned*)(lds + (bufoff) + ldsw + _i * 8192), 16, 0, 0); } while (0)
; #define PG8_LDA(dst, b, h) do { _Pragma("unroll") for (int m = 0; m < 4; ++m) _Pragma("unroll") for (int k = 0; k < 2; ++k) dst[m][k] = *(const PG8_LAS bf16x8*)(lds + PG8_SA(b, h) + aoff + m * 2048 + k * 1024); } while (0)
; #define PG8_LDB(dst, b, h) do { _Pragma("unroll") for (int n = 0; n < 2; ++n) _Pragma("unroll") for (int k = 0; k < 2; ++k) dst[n][k] = *(const PG8_LAS bf16x8*)(lds + PG8_SB(b, h) + boff + n * 2048 + k * 1024); } while (0)
; #define PG8_MMA(ai, bj, At, Bt) do { __builtin_amdgcn_s_setprio(3); _Pragma("unroll") for (int m = 0; m < 4; ++m) _Pragma("unroll") for (int n = 0; n < 2; ++n) _Pragma("unroll") for (int k = 0; k < 2; ++k) \
;         acc[ai][bj][m][n] = __builtin_amdgcn_mfma_f32_16x16x32_bf16(Bt[n][k], At[m][k], acc[ai][bj][m][n], 0, 0, 0); __builtin_amdgcn_s_setprio(0); } while (0)
; #define PG8_WAIT_V(n) asm volatile("s_waitcnt vmcnt(" #n ")" ::: "memory")
; #define PG8_WAIT_L(n) asm volatile("s_waitcnt lgkmcnt(" #n ")" ::: "memory")
; #define PG8_BAR __builtin_amdgcn_s_barrier()
; #define PG8_SCHED __builtin_amdgcn_sched_barrier(0)
; template <class Epi, class Sched, bool ALIGN_EPI = false, bool SP2 = false>
; __device__ __forceinline__ void gemm_phase(PG8_LAS unsigned char* lds, const Gemm g, const Sched& S, const Epi& E) {
;     ...
;             const bool last = (t == nt - 2);
;             const char* a1 = cA + (size_t)(t + 1) * kstep;
;             const char* a2 = last ? nA : cA + (size_t)(t + 2) * kstep; const char* b2 = last ? nB : cB + (size_t)(t + 2) * kstep;
;             const char* a3 = a2 + kstep; const char* b3 = b2 + kstep;
;             if (last && has_next) S.a_ready(nxt);
;             if constexpr (SP2) {
;             PG8_LDB(B0, 0, 0); PG8_LDB(B1, 0, 1); PG8_SCHED; PG8_LDA(At, 0, 0); PG8_STAGE(PG8_SA(1, 1), a1 + hstep, voffA);
;             PG8_WAIT_V(8); PG8_WAIT_L(0); PG8_BAR; PG8_MMA(0, 0, At, B0); PG8_MMA(0, 1, At, B1); PG8_BAR; PG8_SCHED;
;             PG8_LDA(At, 0, 1); PG8_STAGE(PG8_SB(0, 0), b2, voffB); PG8_STAGE(PG8_SB(0, 1), b2 + hstep, voffB); PG8_STAGE(PG8_SA(0, 0), a2, voffA);
.LBB0_1013:
	ds_read_b128 v[148:151], v157
	ds_read_b128 v[152:155], v157 offset:1024
	ds_read_b128 v[160:163], v157 offset:2048
	ds_read_b128 v[168:171], v157 offset:3072
	ds_read_b128 v[172:175], v158
	ds_read_b128 v[176:179], v158 offset:1024
	ds_read_b128 v[180:183], v158 offset:2048
	ds_read_b128 v[184:187], v158 offset:3072
	s_add_i32 s79, s55, 2
	s_add_u32 s10, s56, 0xfff80080
	s_addc_u32 s11, s57, -1
	s_cmp_eq_u32 s9, s55
	s_cselect_b32 s61, s49, s11
	s_cselect_b32 s60, s48, s10
	s_cselect_b32 s59, s53, s51
	s_cselect_b32 s58, s52, s47
	v_lshl_add_u64 v[164:165], s[56:57], 0, v[138:139]
	s_add_i32 m0, s43, 0xc000
	ds_read_b128 v[188:191], v159
	ds_read_b128 v[192:195], v159 offset:1024
	ds_read_b128 v[196:199], v159 offset:2048
	ds_read_b128 v[200:203], v159 offset:3072
	ds_read_b128 v[204:207], v159 offset:4096
	ds_read_b128 v[208:211], v159 offset:5120
	ds_read_b128 v[212:215], v159 offset:6144
	ds_read_b128 v[216:219], v159 offset:7168
	global_load_lds_dwordx4 v[164:165], off
	v_lshl_add_u64 v[164:165], s[56:57], 0, v[142:143]
	s_add_i32 m0, s43, 0xe000
	s_nop 0
	global_load_lds_dwordx4 v[164:165], off
	s_waitcnt vmcnt(8)
	s_waitcnt lgkmcnt(0)
	s_barrier
	s_waitcnt lgkmcnt(0)
	v_mfma_f32_16x16x32_bf16 v[126:129], v[148:151], v[188:191], v[126:129]
	s_setprio 3
	v_mfma_f32_16x16x32_bf16 v[122:125], v[160:163], v[188:191], v[122:125]
	v_mfma_f32_16x16x32_bf16 v[114:117], v[148:151], v[196:199], v[114:117]
	v_mfma_f32_16x16x32_bf16 v[106:109], v[160:163], v[196:199], v[106:109]
	v_mfma_f32_16x16x32_bf16 v[98:101], v[148:151], v[204:207], v[98:101]
	v_mfma_f32_16x16x32_bf16 v[90:93], v[160:163], v[204:207], v[90:93]
	v_mfma_f32_16x16x32_bf16 v[82:85], v[148:151], v[212:215], v[82:85]
	v_mfma_f32_16x16x32_bf16 v[74:77], v[160:163], v[212:215], v[74:77]
	v_mfma_f32_16x16x32_bf16 v[126:129], v[152:155], v[192:195], v[126:129]
	v_mfma_f32_16x16x32_bf16 v[122:125], v[168:171], v[192:195], v[122:125]
	v_mfma_f32_16x16x32_bf16 v[114:117], v[152:155], v[200:203], v[114:117]
	v_mfma_f32_16x16x32_bf16 v[106:109], v[168:171], v[200:203], v[106:109]
	v_mfma_f32_16x16x32_bf16 v[98:101], v[152:155], v[208:211], v[98:101]
	v_mfma_f32_16x16x32_bf16 v[90:93], v[168:171], v[208:211], v[90:93]
	v_mfma_f32_16x16x32_bf16 v[82:85], v[152:155], v[216:219], v[82:85]
	v_mfma_f32_16x16x32_bf16 v[74:77], v[168:171], v[216:219], v[74:77]
	s_setprio 0
	s_setprio 3
	v_mfma_f32_16x16x32_bf16 v[118:121], v[172:175], v[188:191], v[118:121]
	v_mfma_f32_16x16x32_bf16 v[110:113], v[180:183], v[188:191], v[110:113]
	v_mfma_f32_16x16x32_bf16 v[102:105], v[172:175], v[196:199], v[102:105]
	v_mfma_f32_16x16x32_bf16 v[94:97], v[180:183], v[196:199], v[94:97]
	v_mfma_f32_16x16x32_bf16 v[86:89], v[172:175], v[204:207], v[86:89]
	v_mfma_f32_16x16x32_bf16 v[78:81], v[180:183], v[204:207], v[78:81]
	v_mfma_f32_16x16x32_bf16 v[70:73], v[172:175], v[212:215], v[70:73]
	v_mfma_f32_16x16x32_bf16 v[66:69], v[180:183], v[212:215], v[66:69]
	v_mfma_f32_16x16x32_bf16 v[118:121], v[176:179], v[192:195], v[118:121]
	v_mfma_f32_16x16x32_bf16 v[110:113], v[184:187], v[192:195], v[110:113]
	v_mfma_f32_16x16x32_bf16 v[102:105], v[176:179], v[200:203], v[102:105]
	v_mfma_f32_16x16x32_bf16 v[94:97], v[184:187], v[200:203], v[94:97]
	v_mfma_f32_16x16x32_bf16 v[86:89], v[176:179], v[208:211], v[86:89]
	v_mfma_f32_16x16x32_bf16 v[78:81], v[184:187], v[208:211], v[78:81]
	v_mfma_f32_16x16x32_bf16 v[70:73], v[176:179], v[216:219], v[70:73]
	s_barrier
	v_mfma_f32_16x16x32_bf16 v[66:69], v[184:187], v[216:219], v[66:69]
	s_setprio 0
	s_add_i32 s10, s72, s42
	v_lshl_add_u64 v[164:165], s[58:59], 0, v[132:133]
	s_mov_b32 m0, s10
	ds_read_b128 v[188:191], v159 offset:16384
	ds_read_b128 v[192:195], v159 offset:17408
	ds_read_b128 v[196:199], v159 offset:18432
	ds_read_b128 v[200:203], v159 offset:19456
	ds_read_b128 v[204:207], v159 offset:20480
	ds_read_b128 v[208:211], v159 offset:21504
	ds_read_b128 v[212:215], v159 offset:22528
	ds_read_b128 v[216:219], v159 offset:23552
	global_load_lds_dwordx4 v[164:165], off
	s_add_i32 m0, s10, 0x2000
	s_add_u32 s82, s58, 0x80000
	v_lshl_add_u64 v[220:221], s[58:59], 0, v[136:137]
	s_addc_u32 s83, s59, 0
	s_add_i32 s10, s73, s42
	global_load_lds_dwordx4 v[220:221], off
	v_lshl_add_u64 v[222:223], s[82:83], 0, v[132:133]
	s_mov_b32 m0, s10
	v_lshl_add_u64 v[224:225], s[60:61], 0, v[134:135]
	global_load_lds_dwordx4 v[222:223], off
	v_lshl_add_u64 v[222:223], s[82:83], 0, v[136:137]
	s_add_i32 m0, s10, 0x2000
	s_nop 0
	global_load_lds_dwordx4 v[222:223], off
	v_lshl_add_u64 v[222:223], s[60:61], 0, v[130:131]
	s_mov_b32 m0, s43
	s_nop 0
	global_load_lds_dwordx4 v[222:223], off
	s_mov_b32 m0, s62
	s_nop 0
	global_load_lds_dwordx4 v[224:225], off
	s_waitcnt vmcnt(8)
	s_waitcnt lgkmcnt(0)
	s_barrier
; #define PG8_STAGE(bufoff, gbase, voff) do { _Pragma("unroll") for (int _i = 0; _i < 2; ++_i) \
;         __builtin_amdgcn_global_load_lds((const unsigned*)((const char*)(gbase) + (voff)[_i]), (PG8_LAS unsigned*)(lds + (bufoff) + ldsw + _i * 8192), 16, 0, 0); } while (0)
; #define PG8_LDA(dst, b, h) do { _Pragma("unroll") for (int m = 0; m < 4; ++m) _Pragma("unroll") for (int k = 0; k < 2; ++k) dst[m][k] = *(const PG8_LAS bf16x8*)(lds + PG8_SA(b, h) + aoff + m * 2048 + k * 1024); } while (0)
; #define PG8_LDB(dst, b, h) do { _Pragma("unroll") for (int n = 0; n < 2; ++n) _Pragma("unroll") for (int k = 0; k < 2; ++k) dst[n][k] = *(const PG8_LAS bf16x8*)(lds + PG8_SB(b, h) + boff + n * 2048 + k * 1024); } while (0)
; #define PG8_MMA(ai, bj, At, Bt) do { __builtin_amdgcn_s_setprio(3); _Pragma("unroll") for (int m = 0; m < 4; ++m) _Pragma("unroll") for (int n = 0; n < 2; ++n) _Pragma("unroll") for (int k = 0; k < 2; ++k) \
;         acc[ai][bj][m][n] = __builtin_amdgcn_mfma_f32_16x16x32_bf16(Bt[n][k], At[m][k], acc[ai][bj][m][n], 0, 0, 0); __builtin_amdgcn_s_setprio(0); } while (0)
; #define PG8_WAIT_V(n) asm volatile("s_waitcnt vmcnt(" #n ")" ::: "memory")
; #define PG8_WAIT_L(n) asm volatile("s_waitcnt lgkmcnt(" #n ")" ::: "memory")
; #define PG8_BAR __builtin_amdgcn_s_barrier()
; #define PG8_SCHED __builtin_amdgcn_sched_barrier(0)
; template <class Epi, class Sched, bool ALIGN_EPI = false, bool SP2 = false>
; __device__ __forceinline__ void gemm_phase(PG8_LAS unsigned char* lds, const Gemm g, const Sched& S, const Epi& E) {
;     ...
;             PG8_WAIT_V(8); PG8_WAIT_L(0); PG8_BAR; PG8_MMA(1, 0, At, B0); PG8_MMA(1, 1, At, B1); PG8_BAR; PG8_SCHED;
;             PG8_LDB(B0, 1, 0); PG8_LDB(B1, 1, 1); PG8_SCHED; PG8_LDA(At, 1, 0); PG8_STAGE(PG8_SA(0, 1), a2 + hstep, voffA);
;             PG8_WAIT_V(8); PG8_WAIT_L(0); PG8_BAR; PG8_MMA(0, 0, At, B0); PG8_MMA(0, 1, At, B1); PG8_BAR; PG8_SCHED;
	s_waitcnt lgkmcnt(0)
	v_mfma_f32_16x16x32_bf16 v[62:65], v[148:151], v[188:191], v[62:65]
	s_setprio 3
	v_mfma_f32_16x16x32_bf16 v[58:61], v[160:163], v[188:191], v[58:61]
	v_mfma_f32_16x16x32_bf16 v[50:53], v[148:151], v[196:199], v[50:53]
	v_mfma_f32_16x16x32_bf16 v[42:45], v[160:163], v[196:199], v[42:45]
	v_mfma_f32_16x16x32_bf16 v[34:37], v[148:151], v[204:207], v[34:37]
	v_mfma_f32_16x16x32_bf16 v[26:29], v[160:163], v[204:207], v[26:29]
	v_mfma_f32_16x16x32_bf16 v[18:21], v[148:151], v[212:215], v[18:21]
	v_mfma_f32_16x16x32_bf16 v[10:13], v[160:163], v[212:215], v[10:13]
	v_mfma_f32_16x16x32_bf16 v[62:65], v[152:155], v[192:195], v[62:65]
	v_mfma_f32_16x16x32_bf16 v[58:61], v[168:171], v[192:195], v[58:61]
	v_mfma_f32_16x16x32_bf16 v[50:53], v[152:155], v[200:203], v[50:53]
	v_mfma_f32_16x16x32_bf16 v[42:45], v[168:171], v[200:203], v[42:45]
	v_mfma_f32_16x16x32_bf16 v[34:37], v[152:155], v[208:211], v[34:37]
	v_mfma_f32_16x16x32_bf16 v[26:29], v[168:171], v[208:211], v[26:29]
	v_mfma_f32_16x16x32_bf16 v[18:21], v[152:155], v[216:219], v[18:21]
	v_mfma_f32_16x16x32_bf16 v[10:13], v[168:171], v[216:219], v[10:13]
	s_setprio 0
	s_setprio 3
	v_mfma_f32_16x16x32_bf16 v[54:57], v[172:175], v[188:191], v[54:57]
	v_mfma_f32_16x16x32_bf16 v[46:49], v[180:183], v[188:191], v[46:49]
	v_mfma_f32_16x16x32_bf16 v[38:41], v[172:175], v[196:199], v[38:41]
	v_mfma_f32_16x16x32_bf16 v[30:33], v[180:183], v[196:199], v[30:33]
	v_mfma_f32_16x16x32_bf16 v[22:25], v[172:175], v[204:207], v[22:25]
	v_mfma_f32_16x16x32_bf16 v[14:17], v[180:183], v[204:207], v[14:17]
	v_mfma_f32_16x16x32_bf16 v[6:9], v[172:175], v[212:215], v[6:9]
	v_mfma_f32_16x16x32_bf16 v[2:5], v[180:183], v[212:215], v[2:5]
	v_mfma_f32_16x16x32_bf16 v[54:57], v[176:179], v[192:195], v[54:57]
	v_mfma_f32_16x16x32_bf16 v[46:49], v[184:187], v[192:195], v[46:49]
	v_mfma_f32_16x16x32_bf16 v[38:41], v[176:179], v[200:203], v[38:41]
	v_mfma_f32_16x16x32_bf16 v[30:33], v[184:187], v[200:203], v[30:33]
	v_mfma_f32_16x16x32_bf16 v[22:25], v[176:179], v[208:211], v[22:25]
	v_mfma_f32_16x16x32_bf16 v[14:17], v[184:187], v[208:211], v[14:17]
	v_mfma_f32_16x16x32_bf16 v[6:9], v[176:179], v[216:219], v[6:9]
	s_barrier
	v_mfma_f32_16x16x32_bf16 v[2:5], v[184:187], v[216:219], v[2:5]
	s_setprio 0
	s_add_i32 s10, 0, 0x18000
	v_add_u32_e32 v167, s10, v141
	s_add_i32 s11, 0, 0x1c000
	ds_read_b128 v[148:151], v167
	ds_read_b128 v[152:155], v167 offset:1024
	ds_read_b128 v[160:163], v167 offset:2048
	ds_read_b128 v[168:171], v167 offset:3072
	v_add_u32_e32 v167, s11, v141
	ds_read_b128 v[172:175], v167
	ds_read_b128 v[176:179], v167 offset:1024
	ds_read_b128 v[180:183], v167 offset:2048
	ds_read_b128 v[184:187], v167 offset:3072
	s_add_u32 s60, s60, 0x80000
	s_addc_u32 s61, s61, 0
	s_mov_b32 m0, s63
	v_lshl_add_u64 v[226:227], s[60:61], 0, v[130:131]
	ds_read_b128 v[188:191], v159 offset:32768
	ds_read_b128 v[192:195], v159 offset:33792
	ds_read_b128 v[196:199], v159 offset:34816
	ds_read_b128 v[200:203], v159 offset:35840
	ds_read_b128 v[204:207], v159 offset:36864
	ds_read_b128 v[208:211], v159 offset:37888
	ds_read_b128 v[212:215], v159 offset:38912
	ds_read_b128 v[216:219], v159 offset:39936
	global_load_lds_dwordx4 v[226:227], off
	v_lshl_add_u64 v[226:227], s[60:61], 0, v[134:135]
	s_mov_b32 m0, s64
	s_nop 0
	global_load_lds_dwordx4 v[226:227], off
	s_waitcnt vmcnt(8)
	s_waitcnt lgkmcnt(0)
	s_barrier
	s_waitcnt lgkmcnt(0)
	v_mfma_f32_16x16x32_bf16 v[126:129], v[148:151], v[188:191], v[126:129]
	s_setprio 3
	v_mfma_f32_16x16x32_bf16 v[122:125], v[160:163], v[188:191], v[122:125]
	v_mfma_f32_16x16x32_bf16 v[114:117], v[148:151], v[196:199], v[114:117]
	v_mfma_f32_16x16x32_bf16 v[106:109], v[160:163], v[196:199], v[106:109]
	v_mfma_f32_16x16x32_bf16 v[98:101], v[148:151], v[204:207], v[98:101]
	v_mfma_f32_16x16x32_bf16 v[90:93], v[160:163], v[204:207], v[90:93]
	v_mfma_f32_16x16x32_bf16 v[82:85], v[148:151], v[212:215], v[82:85]
	v_mfma_f32_16x16x32_bf16 v[74:77], v[160:163], v[212:215], v[74:77]
	v_mfma_f32_16x16x32_bf16 v[126:129], v[152:155], v[192:195], v[126:129]
	v_mfma_f32_16x16x32_bf16 v[122:125], v[168:171], v[192:195], v[122:125]
	v_mfma_f32_16x16x32_bf16 v[114:117], v[152:155], v[200:203], v[114:117]
	v_mfma_f32_16x16x32_bf16 v[106:109], v[168:171], v[200:203], v[106:109]
	v_mfma_f32_16x16x32_bf16 v[98:101], v[152:155], v[208:211], v[98:101]
	v_mfma_f32_16x16x32_bf16 v[90:93], v[168:171], v[208:211], v[90:93]
	v_mfma_f32_16x16x32_bf16 v[82:85], v[152:155], v[216:219], v[82:85]
	v_mfma_f32_16x16x32_bf16 v[74:77], v[168:171], v[216:219], v[74:77]
	s_setprio 0
	s_setprio 3
	v_mfma_f32_16x16x32_bf16 v[118:121], v[172:175], v[188:191], v[118:121]
	v_mfma_f32_16x16x32_bf16 v[110:113], v[180:183], v[188:191], v[110:113]
	v_mfma_f32_16x16x32_bf16 v[102:105], v[172:175], v[196:199], v[102:105]
	v_mfma_f32_16x16x32_bf16 v[94:97], v[180:183], v[196:199], v[94:97]
	v_mfma_f32_16x16x32_bf16 v[86:89], v[172:175], v[204:207], v[86:89]
	v_mfma_f32_16x16x32_bf16 v[78:81], v[180:183], v[204:207], v[78:81]
	v_mfma_f32_16x16x32_bf16 v[70:73], v[172:175], v[212:215], v[70:73]
	v_mfma_f32_16x16x32_bf16 v[66:69], v[180:183], v[212:215], v[66:69]
	v_mfma_f32_16x16x32_bf16 v[118:121], v[176:179], v[192:195], v[118:121]
	v_mfma_f32_16x16x32_bf16 v[110:113], v[184:187], v[192:195], v[110:113]
	v_mfma_f32_16x16x32_bf16 v[102:105], v[176:179], v[200:203], v[102:105]
	v_mfma_f32_16x16x32_bf16 v[94:97], v[184:187], v[200:203], v[94:97]
	v_mfma_f32_16x16x32_bf16 v[86:89], v[176:179], v[208:211], v[86:89]
	v_mfma_f32_16x16x32_bf16 v[78:81], v[184:187], v[208:211], v[78:81]
	v_mfma_f32_16x16x32_bf16 v[70:73], v[176:179], v[216:219], v[70:73]
	s_barrier
; #define PG8_STAGE(bufoff, gbase, voff) do { _Pragma("unroll") for (int _i = 0; _i < 2; ++_i) \
;         __builtin_amdgcn_global_load_lds((const unsigned*)((const char*)(gbase) + (voff)[_i]), (PG8_LAS unsigned*)(lds + (bufoff) + ldsw + _i * 8192), 16, 0, 0); } while (0)
; #define PG8_LDA(dst, b, h) do { _Pragma("unroll") for (int m = 0; m < 4; ++m) _Pragma("unroll") for (int k = 0; k < 2; ++k) dst[m][k] = *(const PG8_LAS bf16x8*)(lds + PG8_SA(b, h) + aoff + m * 2048 + k * 1024); } while (0)
; #define PG8_MMA(ai, bj, At, Bt) do { __builtin_amdgcn_s_setprio(3); _Pragma("unroll") for (int m = 0; m < 4; ++m) _Pragma("unroll") for (int n = 0; n < 2; ++n) _Pragma("unroll") for (int k = 0; k < 2; ++k) \
;         acc[ai][bj][m][n] = __builtin_amdgcn_mfma_f32_16x16x32_bf16(Bt[n][k], At[m][k], acc[ai][bj][m][n], 0, 0, 0); __builtin_amdgcn_s_setprio(0); } while (0)
; #define PG8_WAIT_V(n) asm volatile("s_waitcnt vmcnt(" #n ")" ::: "memory")
; #define PG8_WAIT_L(n) asm volatile("s_waitcnt lgkmcnt(" #n ")" ::: "memory")
; #define PG8_BAR __builtin_amdgcn_s_barrier()
; #define PG8_SCHED __builtin_amdgcn_sched_barrier(0)
; template <class Epi, class Sched, bool ALIGN_EPI = false, bool SP2 = false>
; __device__ __forceinline__ void gemm_phase(PG8_LAS unsigned char* lds, const Gemm g, const Sched& S, const Epi& E) {
;     ...
;         for (int t = 0; t < nt; t += 2) {
;     ...
;             PG8_WAIT_V(8); PG8_WAIT_L(0); PG8_BAR; PG8_MMA(0, 0, At, B0); PG8_MMA(0, 1, At, B1); PG8_BAR; PG8_SCHED;
;             PG8_LDA(At, 1, 1); PG8_STAGE(PG8_SB(1, 0), b3, voffB); PG8_STAGE(PG8_SB(1, 1), b3 + hstep, voffB); PG8_STAGE(PG8_SA(1, 0), a3, voffA);
;             PG8_WAIT_V(8); PG8_WAIT_L(0); PG8_BAR; PG8_MMA(1, 0, At, B0); PG8_MMA(1, 1, At, B1); PG8_BAR; PG8_SCHED;
	v_mfma_f32_16x16x32_bf16 v[66:69], v[184:187], v[216:219], v[66:69]
	s_setprio 0
	s_add_i32 s10, s10, s42
	v_lshl_add_u64 v[164:165], v[164:165], 0, s[24:25]
	s_mov_b32 m0, s10
	ds_read_b128 v[188:191], v159 offset:49152
	ds_read_b128 v[192:195], v159 offset:50176
	ds_read_b128 v[196:199], v159 offset:51200
	ds_read_b128 v[200:203], v159 offset:52224
	ds_read_b128 v[204:207], v159 offset:53248
	ds_read_b128 v[208:211], v159 offset:54272
	ds_read_b128 v[212:215], v159 offset:55296
	ds_read_b128 v[216:219], v159 offset:56320
	global_load_lds_dwordx4 v[164:165], off
	s_add_i32 m0, s10, 0x2000
	s_add_u32 s58, s58, 0x80080
	v_lshl_add_u64 v[164:165], v[220:221], 0, s[24:25]
	s_addc_u32 s59, s59, 0
	s_add_i32 s10, s11, s42
	global_load_lds_dwordx4 v[164:165], off
	v_lshl_add_u64 v[164:165], s[58:59], 0, v[132:133]
	s_mov_b32 m0, s10
	s_nop 0
	global_load_lds_dwordx4 v[164:165], off
	v_lshl_add_u64 v[164:165], s[58:59], 0, v[136:137]
	s_add_i32 m0, s10, 0x2000
	s_nop 0
	global_load_lds_dwordx4 v[164:165], off
	v_lshl_add_u64 v[164:165], v[222:223], 0, s[24:25]
	s_mov_b32 m0, s69
	s_nop 0
	global_load_lds_dwordx4 v[164:165], off
	v_lshl_add_u64 v[164:165], v[224:225], 0, s[24:25]
	s_mov_b32 m0, s70
	s_nop 0
	global_load_lds_dwordx4 v[164:165], off
	s_waitcnt vmcnt(8)
	s_waitcnt lgkmcnt(0)
	s_barrier
	s_waitcnt lgkmcnt(0)
	v_mfma_f32_16x16x32_bf16 v[62:65], v[148:151], v[188:191], v[62:65]
	s_setprio 3
	v_mfma_f32_16x16x32_bf16 v[58:61], v[160:163], v[188:191], v[58:61]
	v_mfma_f32_16x16x32_bf16 v[50:53], v[148:151], v[196:199], v[50:53]
	v_mfma_f32_16x16x32_bf16 v[42:45], v[160:163], v[196:199], v[42:45]
	v_mfma_f32_16x16x32_bf16 v[34:37], v[148:151], v[204:207], v[34:37]
	v_mfma_f32_16x16x32_bf16 v[26:29], v[160:163], v[204:207], v[26:29]
	v_mfma_f32_16x16x32_bf16 v[18:21], v[148:151], v[212:215], v[18:21]
	v_mfma_f32_16x16x32_bf16 v[10:13], v[160:163], v[212:215], v[10:13]
	v_mfma_f32_16x16x32_bf16 v[62:65], v[152:155], v[192:195], v[62:65]
	v_mfma_f32_16x16x32_bf16 v[58:61], v[168:171], v[192:195], v[58:61]
	v_mfma_f32_16x16x32_bf16 v[50:53], v[152:155], v[200:203], v[50:53]
	v_mfma_f32_16x16x32_bf16 v[42:45], v[168:171], v[200:203], v[42:45]
	v_mfma_f32_16x16x32_bf16 v[34:37], v[152:155], v[208:211], v[34:37]
	v_mfma_f32_16x16x32_bf16 v[26:29], v[168:171], v[208:211], v[26:29]
	v_mfma_f32_16x16x32_bf16 v[18:21], v[152:155], v[216:219], v[18:21]
	v_mfma_f32_16x16x32_bf16 v[10:13], v[168:171], v[216:219], v[10:13]
	s_setprio 0
	s_setprio 3
	v_mfma_f32_16x16x32_bf16 v[54:57], v[172:175], v[188:191], v[54:57]
	v_mfma_f32_16x16x32_bf16 v[46:49], v[180:183], v[188:191], v[46:49]
	v_mfma_f32_16x16x32_bf16 v[38:41], v[172:175], v[196:199], v[38:41]
	v_mfma_f32_16x16x32_bf16 v[30:33], v[180:183], v[196:199], v[30:33]
	v_mfma_f32_16x16x32_bf16 v[22:25], v[172:175], v[204:207], v[22:25]
	v_mfma_f32_16x16x32_bf16 v[14:17], v[180:183], v[204:207], v[14:17]
	v_mfma_f32_16x16x32_bf16 v[6:9], v[172:175], v[212:215], v[6:9]
	v_mfma_f32_16x16x32_bf16 v[2:5], v[180:183], v[212:215], v[2:5]
	v_mfma_f32_16x16x32_bf16 v[54:57], v[176:179], v[192:195], v[54:57]
	v_mfma_f32_16x16x32_bf16 v[46:49], v[184:187], v[192:195], v[46:49]
	v_mfma_f32_16x16x32_bf16 v[38:41], v[176:179], v[200:203], v[38:41]
	v_mfma_f32_16x16x32_bf16 v[30:33], v[184:187], v[200:203], v[30:33]
	v_mfma_f32_16x16x32_bf16 v[22:25], v[176:179], v[208:211], v[22:25]
	v_mfma_f32_16x16x32_bf16 v[14:17], v[184:187], v[208:211], v[14:17]
	v_mfma_f32_16x16x32_bf16 v[6:9], v[176:179], v[216:219], v[6:9]
	s_barrier
	v_mfma_f32_16x16x32_bf16 v[2:5], v[184:187], v[216:219], v[2:5]
	s_setprio 0
	s_add_u32 s56, s56, 0x100
	s_addc_u32 s57, s57, 0
	s_add_u32 s47, s47, 0x100
	s_addc_u32 s51, s51, 0
	s_cmp_ge_u32 s79, s78
	s_mov_b32 s55, s79
	s_cbranch_scc0 .LBB0_1013
	s_and_b64 vcc, exec, s[26:27]
	s_cbranch_vccz .LBB0_1016
	s_barrier

; #define PG8_STAGE(bufoff, gbase, voff) do { _Pragma("unroll") for (int _i = 0; _i < 2; ++_i) \
;         __builtin_amdgcn_global_load_lds((const unsigned*)((const char*)(gbase) + (voff)[_i]), (PG8_LAS unsigned*)(lds + (bufoff) + ldsw + _i * 8192), 16, 0, 0); } while (0)
; #define PG8_LDA(dst, b, h) do { _Pragma("unroll") for (int m = 0; m < 4; ++m) _Pragma("unroll") for (int k = 0; k < 2; ++k) dst[m][k] = *(const PG8_LAS bf16x8*)(lds + PG8_SA(b, h) + aoff + m * 2048 + k * 1024); } while (0)
; #define PG8_LDB(dst, b, h) do { _Pragma("unroll") for (int n = 0; n < 2; ++n) _Pragma("unroll") for (int k = 0; k < 2; ++k) dst[n][k] = *(const PG8_LAS bf16x8*)(lds + PG8_SB(b, h) + boff + n * 2048 + k * 1024); } while (0)
; #define PG8_MMA(ai, bj, At, Bt) do { __builtin_amdgcn_s_setprio(3); _Pragma("unroll") for (int m = 0; m < 4; ++m) _Pragma("unroll") for (int n = 0; n < 2; ++n) _Pragma("unroll") for (int k = 0; k < 2; ++k) \
;         acc[ai][bj][m][n] = __builtin_amdgcn_mfma_f32_16x16x32_bf16(Bt[n][k], At[m][k], acc[ai][bj][m][n], 0, 0, 0); __builtin_amdgcn_s_setprio(0); } while (0)
; #define PG8_WAIT_V(n) asm volatile("s_waitcnt vmcnt(" #n ")" ::: "memory")
; #define PG8_WAIT_L(n) asm volatile("s_waitcnt lgkmcnt(" #n ")" ::: "memory")
; #define PG8_BAR __builtin_amdgcn_s_barrier()
; #define PG8_SCHED __builtin_amdgcn_sched_barrier(0)
; template <class Epi, class Sched, bool ALIGN_EPI = false, bool SP2 = false>
; __device__ __forceinline__ void gemm_phase(PG8_LAS unsigned char* lds, const Gemm g, const Sched& S, const Epi& E) {
;     ...
;             const bool last = (t == nt - 2);
;             const char* a1 = cA + (size_t)(t + 1) * kstep;
;             const char* a2 = last ? nA : cA + (size_t)(t + 2) * kstep; const char* b2 = last ? nB : cB + (size_t)(t + 2) * kstep;
;             const char* a3 = a2 + kstep; const char* b3 = b2 + kstep;
;             if (last && has_next) S.a_ready(nxt);
;             if constexpr (SP2) {
;             PG8_LDB(B0, 0, 0); PG8_LDB(B1, 0, 1); PG8_SCHED; PG8_LDA(At, 0, 0); PG8_STAGE(PG8_SA(1, 1), a1 + hstep, voffA);
;             PG8_WAIT_V(8); PG8_WAIT_L(0); PG8_BAR; PG8_MMA(0, 0, At, B0); PG8_MMA(0, 1, At, B1); PG8_BAR; PG8_SCHED;
;             PG8_LDA(At, 0, 1); PG8_STAGE(PG8_SB(0, 0), b2, voffB); PG8_STAGE(PG8_SB(0, 1), b2 + hstep, voffB); PG8_STAGE(PG8_SA(0, 0), a2, voffA);
.LBB0_1218:
	ds_read_b128 v[148:151], v153
	ds_read_b128 v[156:159], v153 offset:1024
	ds_read_b128 v[160:163], v153 offset:2048
	ds_read_b128 v[168:171], v153 offset:3072
	ds_read_b128 v[172:175], v154
	ds_read_b128 v[176:179], v154 offset:1024
	ds_read_b128 v[180:183], v154 offset:2048
	ds_read_b128 v[184:187], v154 offset:3072
	s_add_u32 s10, s46, 0xfff80080
	s_addc_u32 s11, s47, -1
	s_cmp_eq_u32 s66, 28
	s_cselect_b32 s51, s27, s11
	s_cselect_b32 s50, s62, s10
	s_cselect_b32 s49, s25, s65
	s_cselect_b32 s48, s63, s64
	v_lshl_add_u64 v[164:165], s[46:47], 0, v[138:139]
	s_add_i32 m0, s42, 0xc000
	ds_read_b128 v[188:191], v155
	ds_read_b128 v[192:195], v155 offset:1024
	ds_read_b128 v[196:199], v155 offset:2048
	ds_read_b128 v[200:203], v155 offset:3072
	ds_read_b128 v[204:207], v155 offset:4096
	ds_read_b128 v[208:211], v155 offset:5120
	ds_read_b128 v[212:215], v155 offset:6144
	ds_read_b128 v[216:219], v155 offset:7168
	global_load_lds_dwordx4 v[164:165], off
	v_lshl_add_u64 v[164:165], s[46:47], 0, v[142:143]
	s_add_i32 m0, s42, 0xe000
	s_nop 0
	global_load_lds_dwordx4 v[164:165], off
	s_waitcnt vmcnt(8)
	s_waitcnt lgkmcnt(0)
	s_barrier
	s_waitcnt lgkmcnt(0)
	v_mfma_f32_16x16x32_bf16 v[126:129], v[148:151], v[188:191], v[126:129]
	s_setprio 3
	v_mfma_f32_16x16x32_bf16 v[118:121], v[160:163], v[188:191], v[118:121]
	v_mfma_f32_16x16x32_bf16 v[110:113], v[148:151], v[196:199], v[110:113]
	v_mfma_f32_16x16x32_bf16 v[102:105], v[160:163], v[196:199], v[102:105]
	v_mfma_f32_16x16x32_bf16 v[94:97], v[148:151], v[204:207], v[94:97]
	v_mfma_f32_16x16x32_bf16 v[86:89], v[160:163], v[204:207], v[86:89]
	v_mfma_f32_16x16x32_bf16 v[78:81], v[148:151], v[212:215], v[78:81]
	v_mfma_f32_16x16x32_bf16 v[70:73], v[160:163], v[212:215], v[70:73]
	v_mfma_f32_16x16x32_bf16 v[126:129], v[156:159], v[192:195], v[126:129]
	v_mfma_f32_16x16x32_bf16 v[118:121], v[168:171], v[192:195], v[118:121]
	v_mfma_f32_16x16x32_bf16 v[110:113], v[156:159], v[200:203], v[110:113]
	v_mfma_f32_16x16x32_bf16 v[102:105], v[168:171], v[200:203], v[102:105]
	v_mfma_f32_16x16x32_bf16 v[94:97], v[156:159], v[208:211], v[94:97]
	v_mfma_f32_16x16x32_bf16 v[86:89], v[168:171], v[208:211], v[86:89]
	v_mfma_f32_16x16x32_bf16 v[78:81], v[156:159], v[216:219], v[78:81]
	v_mfma_f32_16x16x32_bf16 v[70:73], v[168:171], v[216:219], v[70:73]
	s_setprio 0
	s_setprio 3
	v_mfma_f32_16x16x32_bf16 v[122:125], v[172:175], v[188:191], v[122:125]
	v_mfma_f32_16x16x32_bf16 v[114:117], v[180:183], v[188:191], v[114:117]
	v_mfma_f32_16x16x32_bf16 v[106:109], v[172:175], v[196:199], v[106:109]
	v_mfma_f32_16x16x32_bf16 v[98:101], v[180:183], v[196:199], v[98:101]
	v_mfma_f32_16x16x32_bf16 v[90:93], v[172:175], v[204:207], v[90:93]
	v_mfma_f32_16x16x32_bf16 v[82:85], v[180:183], v[204:207], v[82:85]
	v_mfma_f32_16x16x32_bf16 v[74:77], v[172:175], v[212:215], v[74:77]
	v_mfma_f32_16x16x32_bf16 v[66:69], v[180:183], v[212:215], v[66:69]
	v_mfma_f32_16x16x32_bf16 v[122:125], v[176:179], v[192:195], v[122:125]
	v_mfma_f32_16x16x32_bf16 v[114:117], v[184:187], v[192:195], v[114:117]
	v_mfma_f32_16x16x32_bf16 v[106:109], v[176:179], v[200:203], v[106:109]
	v_mfma_f32_16x16x32_bf16 v[98:101], v[184:187], v[200:203], v[98:101]
	v_mfma_f32_16x16x32_bf16 v[90:93], v[176:179], v[208:211], v[90:93]
	v_mfma_f32_16x16x32_bf16 v[82:85], v[184:187], v[208:211], v[82:85]
	v_mfma_f32_16x16x32_bf16 v[74:77], v[176:179], v[216:219], v[74:77]
	s_barrier
	v_mfma_f32_16x16x32_bf16 v[66:69], v[184:187], v[216:219], v[66:69]
	s_setprio 0
	s_add_i32 s10, s58, s35
	v_lshl_add_u64 v[164:165], s[48:49], 0, v[132:133]
	s_mov_b32 m0, s10
	ds_read_b128 v[188:191], v155 offset:16384
	ds_read_b128 v[192:195], v155 offset:17408
	ds_read_b128 v[196:199], v155 offset:18432
	ds_read_b128 v[200:203], v155 offset:19456
	ds_read_b128 v[204:207], v155 offset:20480
	ds_read_b128 v[208:211], v155 offset:21504
	ds_read_b128 v[212:215], v155 offset:22528
	ds_read_b128 v[216:219], v155 offset:23552
	global_load_lds_dwordx4 v[164:165], off
	s_add_i32 m0, s10, 0x2000
	s_add_u32 s68, s48, 0x80000
	v_lshl_add_u64 v[220:221], s[48:49], 0, v[136:137]
	s_addc_u32 s69, s49, 0
	s_add_i32 s10, s59, s35
	global_load_lds_dwordx4 v[220:221], off
	v_lshl_add_u64 v[222:223], s[68:69], 0, v[132:133]
	s_mov_b32 m0, s10
	v_lshl_add_u64 v[224:225], s[50:51], 0, v[134:135]
	global_load_lds_dwordx4 v[222:223], off
	v_lshl_add_u64 v[222:223], s[68:69], 0, v[136:137]
	s_add_i32 m0, s10, 0x2000
	s_nop 0
	global_load_lds_dwordx4 v[222:223], off
	v_lshl_add_u64 v[222:223], s[50:51], 0, v[130:131]
	s_mov_b32 m0, s42
	s_nop 0
	global_load_lds_dwordx4 v[222:223], off
	s_mov_b32 m0, s43
	s_nop 0
	global_load_lds_dwordx4 v[224:225], off
	s_waitcnt vmcnt(8)
	s_waitcnt lgkmcnt(0)
	s_barrier
; #define PG8_STAGE(bufoff, gbase, voff) do { _Pragma("unroll") for (int _i = 0; _i < 2; ++_i) \
;         __builtin_amdgcn_global_load_lds((const unsigned*)((const char*)(gbase) + (voff)[_i]), (PG8_LAS unsigned*)(lds + (bufoff) + ldsw + _i * 8192), 16, 0, 0); } while (0)
; #define PG8_LDA(dst, b, h) do { _Pragma("unroll") for (int m = 0; m < 4; ++m) _Pragma("unroll") for (int k = 0; k < 2; ++k) dst[m][k] = *(const PG8_LAS bf16x8*)(lds + PG8_SA(b, h) + aoff + m * 2048 + k * 1024); } while (0)
; #define PG8_LDB(dst, b, h) do { _Pragma("unroll") for (int n = 0; n < 2; ++n) _Pragma("unroll") for (int k = 0; k < 2; ++k) dst[n][k] = *(const PG8_LAS bf16x8*)(lds + PG8_SB(b, h) + boff + n * 2048 + k * 1024); } while (0)
; #define PG8_MMA(ai, bj, At, Bt) do { __builtin_amdgcn_s_setprio(3); _Pragma("unroll") for (int m = 0; m < 4; ++m) _Pragma("unroll") for (int n = 0; n < 2; ++n) _Pragma("unroll") for (int k = 0; k < 2; ++k) \
;         acc[ai][bj][m][n] = __builtin_amdgcn_mfma_f32_16x16x32_bf16(Bt[n][k], At[m][k], acc[ai][bj][m][n], 0, 0, 0); __builtin_amdgcn_s_setprio(0); } while (0)
; #define PG8_WAIT_V(n) asm volatile("s_waitcnt vmcnt(" #n ")" ::: "memory")
; #define PG8_WAIT_L(n) asm volatile("s_waitcnt lgkmcnt(" #n ")" ::: "memory")
; #define PG8_BAR __builtin_amdgcn_s_barrier()
; #define PG8_SCHED __builtin_amdgcn_sched_barrier(0)
; template <class Epi, class Sched, bool ALIGN_EPI = false, bool SP2 = false>
; __device__ __forceinline__ void gemm_phase(PG8_LAS unsigned char* lds, const Gemm g, const Sched& S, const Epi& E) {
;     ...
;             PG8_WAIT_V(8); PG8_WAIT_L(0); PG8_BAR; PG8_MMA(1, 0, At, B0); PG8_MMA(1, 1, At, B1); PG8_BAR; PG8_SCHED;
;             PG8_LDB(B0, 1, 0); PG8_LDB(B1, 1, 1); PG8_SCHED; PG8_LDA(At, 1, 0); PG8_STAGE(PG8_SA(0, 1), a2 + hstep, voffA);
;             PG8_WAIT_V(8); PG8_WAIT_L(0); PG8_BAR; PG8_MMA(0, 0, At, B0); PG8_MMA(0, 1, At, B1); PG8_BAR; PG8_SCHED;
	s_waitcnt lgkmcnt(0)
	v_mfma_f32_16x16x32_bf16 v[62:65], v[148:151], v[188:191], v[62:65]
	s_setprio 3
	v_mfma_f32_16x16x32_bf16 v[54:57], v[160:163], v[188:191], v[54:57]
	v_mfma_f32_16x16x32_bf16 v[46:49], v[148:151], v[196:199], v[46:49]
	v_mfma_f32_16x16x32_bf16 v[38:41], v[160:163], v[196:199], v[38:41]
	v_mfma_f32_16x16x32_bf16 v[30:33], v[148:151], v[204:207], v[30:33]
	v_mfma_f32_16x16x32_bf16 v[22:25], v[160:163], v[204:207], v[22:25]
	v_mfma_f32_16x16x32_bf16 v[14:17], v[148:151], v[212:215], v[14:17]
	v_mfma_f32_16x16x32_bf16 v[6:9], v[160:163], v[212:215], v[6:9]
	v_mfma_f32_16x16x32_bf16 v[62:65], v[156:159], v[192:195], v[62:65]
	v_mfma_f32_16x16x32_bf16 v[54:57], v[168:171], v[192:195], v[54:57]
	v_mfma_f32_16x16x32_bf16 v[46:49], v[156:159], v[200:203], v[46:49]
	v_mfma_f32_16x16x32_bf16 v[38:41], v[168:171], v[200:203], v[38:41]
	v_mfma_f32_16x16x32_bf16 v[30:33], v[156:159], v[208:211], v[30:33]
	v_mfma_f32_16x16x32_bf16 v[22:25], v[168:171], v[208:211], v[22:25]
	v_mfma_f32_16x16x32_bf16 v[14:17], v[156:159], v[216:219], v[14:17]
	v_mfma_f32_16x16x32_bf16 v[6:9], v[168:171], v[216:219], v[6:9]
	s_setprio 0
	s_setprio 3
	v_mfma_f32_16x16x32_bf16 v[58:61], v[172:175], v[188:191], v[58:61]
	v_mfma_f32_16x16x32_bf16 v[50:53], v[180:183], v[188:191], v[50:53]
	v_mfma_f32_16x16x32_bf16 v[42:45], v[172:175], v[196:199], v[42:45]
	v_mfma_f32_16x16x32_bf16 v[34:37], v[180:183], v[196:199], v[34:37]
	v_mfma_f32_16x16x32_bf16 v[26:29], v[172:175], v[204:207], v[26:29]
	v_mfma_f32_16x16x32_bf16 v[18:21], v[180:183], v[204:207], v[18:21]
	v_mfma_f32_16x16x32_bf16 v[10:13], v[172:175], v[212:215], v[10:13]
	v_mfma_f32_16x16x32_bf16 v[2:5], v[180:183], v[212:215], v[2:5]
	v_mfma_f32_16x16x32_bf16 v[58:61], v[176:179], v[192:195], v[58:61]
	v_mfma_f32_16x16x32_bf16 v[50:53], v[184:187], v[192:195], v[50:53]
	v_mfma_f32_16x16x32_bf16 v[42:45], v[176:179], v[200:203], v[42:45]
	v_mfma_f32_16x16x32_bf16 v[34:37], v[184:187], v[200:203], v[34:37]
	v_mfma_f32_16x16x32_bf16 v[26:29], v[176:179], v[208:211], v[26:29]
	v_mfma_f32_16x16x32_bf16 v[18:21], v[184:187], v[208:211], v[18:21]
	v_mfma_f32_16x16x32_bf16 v[10:13], v[176:179], v[216:219], v[10:13]
	s_barrier
	v_mfma_f32_16x16x32_bf16 v[2:5], v[184:187], v[216:219], v[2:5]
	s_setprio 0
	s_add_i32 s10, 0, 0x18000
	v_add_u32_e32 v167, s10, v141
	s_add_i32 s11, 0, 0x1c000
	ds_read_b128 v[148:151], v167
	ds_read_b128 v[156:159], v167 offset:1024
	ds_read_b128 v[160:163], v167 offset:2048
	ds_read_b128 v[168:171], v167 offset:3072
	v_add_u32_e32 v167, s11, v141
	ds_read_b128 v[172:175], v167
	ds_read_b128 v[176:179], v167 offset:1024
	ds_read_b128 v[180:183], v167 offset:2048
	ds_read_b128 v[184:187], v167 offset:3072
	s_add_u32 s50, s50, 0x80000
	s_addc_u32 s51, s51, 0
	s_mov_b32 m0, s45
	v_lshl_add_u64 v[226:227], s[50:51], 0, v[130:131]
	ds_read_b128 v[188:191], v155 offset:32768
	ds_read_b128 v[192:195], v155 offset:33792
	ds_read_b128 v[196:199], v155 offset:34816
	ds_read_b128 v[200:203], v155 offset:35840
	ds_read_b128 v[204:207], v155 offset:36864
	ds_read_b128 v[208:211], v155 offset:37888
	ds_read_b128 v[212:215], v155 offset:38912
	ds_read_b128 v[216:219], v155 offset:39936
	global_load_lds_dwordx4 v[226:227], off
	v_lshl_add_u64 v[226:227], s[50:51], 0, v[134:135]
	s_mov_b32 m0, s52
	s_nop 0
	global_load_lds_dwordx4 v[226:227], off
	s_waitcnt vmcnt(8)
	s_waitcnt lgkmcnt(0)
	s_barrier
	s_waitcnt lgkmcnt(0)
	v_mfma_f32_16x16x32_bf16 v[126:129], v[148:151], v[188:191], v[126:129]
	s_setprio 3
	v_mfma_f32_16x16x32_bf16 v[118:121], v[160:163], v[188:191], v[118:121]
	v_mfma_f32_16x16x32_bf16 v[110:113], v[148:151], v[196:199], v[110:113]
	v_mfma_f32_16x16x32_bf16 v[102:105], v[160:163], v[196:199], v[102:105]
	v_mfma_f32_16x16x32_bf16 v[94:97], v[148:151], v[204:207], v[94:97]
	v_mfma_f32_16x16x32_bf16 v[86:89], v[160:163], v[204:207], v[86:89]
	v_mfma_f32_16x16x32_bf16 v[78:81], v[148:151], v[212:215], v[78:81]
	v_mfma_f32_16x16x32_bf16 v[70:73], v[160:163], v[212:215], v[70:73]
	v_mfma_f32_16x16x32_bf16 v[126:129], v[156:159], v[192:195], v[126:129]
	v_mfma_f32_16x16x32_bf16 v[118:121], v[168:171], v[192:195], v[118:121]
	v_mfma_f32_16x16x32_bf16 v[110:113], v[156:159], v[200:203], v[110:113]
	v_mfma_f32_16x16x32_bf16 v[102:105], v[168:171], v[200:203], v[102:105]
	v_mfma_f32_16x16x32_bf16 v[94:97], v[156:159], v[208:211], v[94:97]
	v_mfma_f32_16x16x32_bf16 v[86:89], v[168:171], v[208:211], v[86:89]
	v_mfma_f32_16x16x32_bf16 v[78:81], v[156:159], v[216:219], v[78:81]
	v_mfma_f32_16x16x32_bf16 v[70:73], v[168:171], v[216:219], v[70:73]
	s_setprio 0
	s_setprio 3
	v_mfma_f32_16x16x32_bf16 v[122:125], v[172:175], v[188:191], v[122:125]
	v_mfma_f32_16x16x32_bf16 v[114:117], v[180:183], v[188:191], v[114:117]
	v_mfma_f32_16x16x32_bf16 v[106:109], v[172:175], v[196:199], v[106:109]
	v_mfma_f32_16x16x32_bf16 v[98:101], v[180:183], v[196:199], v[98:101]
	v_mfma_f32_16x16x32_bf16 v[90:93], v[172:175], v[204:207], v[90:93]
	v_mfma_f32_16x16x32_bf16 v[82:85], v[180:183], v[204:207], v[82:85]
	v_mfma_f32_16x16x32_bf16 v[74:77], v[172:175], v[212:215], v[74:77]
	v_mfma_f32_16x16x32_bf16 v[66:69], v[180:183], v[212:215], v[66:69]
	v_mfma_f32_16x16x32_bf16 v[122:125], v[176:179], v[192:195], v[122:125]
	v_mfma_f32_16x16x32_bf16 v[114:117], v[184:187], v[192:195], v[114:117]
	v_mfma_f32_16x16x32_bf16 v[106:109], v[176:179], v[200:203], v[106:109]
	v_mfma_f32_16x16x32_bf16 v[98:101], v[184:187], v[200:203], v[98:101]
	v_mfma_f32_16x16x32_bf16 v[90:93], v[176:179], v[208:211], v[90:93]
	v_mfma_f32_16x16x32_bf16 v[82:85], v[184:187], v[208:211], v[82:85]
	v_mfma_f32_16x16x32_bf16 v[74:77], v[176:179], v[216:219], v[74:77]
	s_barrier
; #define PG8_STAGE(bufoff, gbase, voff) do { _Pragma("unroll") for (int _i = 0; _i < 2; ++_i) \
;         __builtin_amdgcn_global_load_lds((const unsigned*)((const char*)(gbase) + (voff)[_i]), (PG8_LAS unsigned*)(lds + (bufoff) + ldsw + _i * 8192), 16, 0, 0); } while (0)
; #define PG8_LDA(dst, b, h) do { _Pragma("unroll") for (int m = 0; m < 4; ++m) _Pragma("unroll") for (int k = 0; k < 2; ++k) dst[m][k] = *(const PG8_LAS bf16x8*)(lds + PG8_SA(b, h) + aoff + m * 2048 + k * 1024); } while (0)
; #define PG8_MMA(ai, bj, At, Bt) do { __builtin_amdgcn_s_setprio(3); _Pragma("unroll") for (int m = 0; m < 4; ++m) _Pragma("unroll") for (int n = 0; n < 2; ++n) _Pragma("unroll") for (int k = 0; k < 2; ++k) \
;         acc[ai][bj][m][n] = __builtin_amdgcn_mfma_f32_16x16x32_bf16(Bt[n][k], At[m][k], acc[ai][bj][m][n], 0, 0, 0); __builtin_amdgcn_s_setprio(0); } while (0)
; #define PG8_WAIT_V(n) asm volatile("s_waitcnt vmcnt(" #n ")" ::: "memory")
; #define PG8_WAIT_L(n) asm volatile("s_waitcnt lgkmcnt(" #n ")" ::: "memory")
; #define PG8_BAR __builtin_amdgcn_s_barrier()
; #define PG8_SCHED __builtin_amdgcn_sched_barrier(0)
; template <class Epi, class Sched, bool ALIGN_EPI = false, bool SP2 = false>
; __device__ __forceinline__ void gemm_phase(PG8_LAS unsigned char* lds, const Gemm g, const Sched& S, const Epi& E) {
;     ...
;         for (int t = 0; t < nt; t += 2) {
;     ...
;             PG8_WAIT_V(8); PG8_WAIT_L(0); PG8_BAR; PG8_MMA(0, 0, At, B0); PG8_MMA(0, 1, At, B1); PG8_BAR; PG8_SCHED;
;             PG8_LDA(At, 1, 1); PG8_STAGE(PG8_SB(1, 0), b3, voffB); PG8_STAGE(PG8_SB(1, 1), b3 + hstep, voffB); PG8_STAGE(PG8_SA(1, 0), a3, voffA);
;             PG8_WAIT_V(8); PG8_WAIT_L(0); PG8_BAR; PG8_MMA(1, 0, At, B0); PG8_MMA(1, 1, At, B1); PG8_BAR; PG8_SCHED;
	v_mfma_f32_16x16x32_bf16 v[66:69], v[184:187], v[216:219], v[66:69]
	s_setprio 0
	s_add_i32 s10, s10, s35
	v_lshl_add_u64 v[164:165], v[164:165], 0, s[16:17]
	s_mov_b32 m0, s10
	ds_read_b128 v[188:191], v155 offset:49152
	ds_read_b128 v[192:195], v155 offset:50176
	ds_read_b128 v[196:199], v155 offset:51200
	ds_read_b128 v[200:203], v155 offset:52224
	ds_read_b128 v[204:207], v155 offset:53248
	ds_read_b128 v[208:211], v155 offset:54272
	ds_read_b128 v[212:215], v155 offset:55296
	ds_read_b128 v[216:219], v155 offset:56320
	global_load_lds_dwordx4 v[164:165], off
	s_add_i32 m0, s10, 0x2000
	s_add_u32 s48, s48, 0x80080
	v_lshl_add_u64 v[164:165], v[220:221], 0, s[16:17]
	s_addc_u32 s49, s49, 0
	s_add_i32 s10, s11, s35
	global_load_lds_dwordx4 v[164:165], off
	v_lshl_add_u64 v[164:165], s[48:49], 0, v[132:133]
	s_mov_b32 m0, s10
	s_nop 0
	global_load_lds_dwordx4 v[164:165], off
	v_lshl_add_u64 v[164:165], s[48:49], 0, v[136:137]
	s_add_i32 m0, s10, 0x2000
	s_nop 0
	global_load_lds_dwordx4 v[164:165], off
	v_lshl_add_u64 v[164:165], v[222:223], 0, s[16:17]
	s_mov_b32 m0, s55
	s_nop 0
	global_load_lds_dwordx4 v[164:165], off
	v_lshl_add_u64 v[164:165], v[224:225], 0, s[16:17]
	s_mov_b32 m0, s56
	s_nop 0
	global_load_lds_dwordx4 v[164:165], off
	s_waitcnt vmcnt(8)
	s_waitcnt lgkmcnt(0)
	s_barrier
	s_waitcnt lgkmcnt(0)
	v_mfma_f32_16x16x32_bf16 v[62:65], v[148:151], v[188:191], v[62:65]
	s_setprio 3
	v_mfma_f32_16x16x32_bf16 v[54:57], v[160:163], v[188:191], v[54:57]
	v_mfma_f32_16x16x32_bf16 v[46:49], v[148:151], v[196:199], v[46:49]
	v_mfma_f32_16x16x32_bf16 v[38:41], v[160:163], v[196:199], v[38:41]
	v_mfma_f32_16x16x32_bf16 v[30:33], v[148:151], v[204:207], v[30:33]
	v_mfma_f32_16x16x32_bf16 v[22:25], v[160:163], v[204:207], v[22:25]
	v_mfma_f32_16x16x32_bf16 v[14:17], v[148:151], v[212:215], v[14:17]
	v_mfma_f32_16x16x32_bf16 v[6:9], v[160:163], v[212:215], v[6:9]
	v_mfma_f32_16x16x32_bf16 v[62:65], v[156:159], v[192:195], v[62:65]
	v_mfma_f32_16x16x32_bf16 v[54:57], v[168:171], v[192:195], v[54:57]
	v_mfma_f32_16x16x32_bf16 v[46:49], v[156:159], v[200:203], v[46:49]
	v_mfma_f32_16x16x32_bf16 v[38:41], v[168:171], v[200:203], v[38:41]
	v_mfma_f32_16x16x32_bf16 v[30:33], v[156:159], v[208:211], v[30:33]
	v_mfma_f32_16x16x32_bf16 v[22:25], v[168:171], v[208:211], v[22:25]
	v_mfma_f32_16x16x32_bf16 v[14:17], v[156:159], v[216:219], v[14:17]
	v_mfma_f32_16x16x32_bf16 v[6:9], v[168:171], v[216:219], v[6:9]
	s_setprio 0
	s_setprio 3
	v_mfma_f32_16x16x32_bf16 v[58:61], v[172:175], v[188:191], v[58:61]
	v_mfma_f32_16x16x32_bf16 v[50:53], v[180:183], v[188:191], v[50:53]
	v_mfma_f32_16x16x32_bf16 v[42:45], v[172:175], v[196:199], v[42:45]
	v_mfma_f32_16x16x32_bf16 v[34:37], v[180:183], v[196:199], v[34:37]
	v_mfma_f32_16x16x32_bf16 v[26:29], v[172:175], v[204:207], v[26:29]
	v_mfma_f32_16x16x32_bf16 v[18:21], v[180:183], v[204:207], v[18:21]
	v_mfma_f32_16x16x32_bf16 v[10:13], v[172:175], v[212:215], v[10:13]
	v_mfma_f32_16x16x32_bf16 v[2:5], v[180:183], v[212:215], v[2:5]
	v_mfma_f32_16x16x32_bf16 v[58:61], v[176:179], v[192:195], v[58:61]
	v_mfma_f32_16x16x32_bf16 v[50:53], v[184:187], v[192:195], v[50:53]
	v_mfma_f32_16x16x32_bf16 v[42:45], v[176:179], v[200:203], v[42:45]
	v_mfma_f32_16x16x32_bf16 v[34:37], v[184:187], v[200:203], v[34:37]
	v_mfma_f32_16x16x32_bf16 v[26:29], v[176:179], v[208:211], v[26:29]
	v_mfma_f32_16x16x32_bf16 v[18:21], v[184:187], v[208:211], v[18:21]
	v_mfma_f32_16x16x32_bf16 v[10:13], v[176:179], v[216:219], v[10:13]
	s_barrier
	v_mfma_f32_16x16x32_bf16 v[2:5], v[184:187], v[216:219], v[2:5]
	s_setprio 0
	s_add_i32 s66, s66, 2
	s_add_u32 s46, s46, 0x100
	s_addc_u32 s47, s47, 0
	s_add_u32 s64, s64, 0x100
	s_addc_u32 s65, s65, 0
	s_cmp_gt_u32 s66, 29
	s_cbranch_scc0 .LBB0_1218
	s_and_b64 vcc, exec, s[18:19]
	s_cbranch_vccz .LBB0_1221
	s_barrier

; #define PG8_STAGE(bufoff, gbase, voff) do { _Pragma("unroll") for (int _i = 0; _i < 2; ++_i) \
;         __builtin_amdgcn_global_load_lds((const unsigned*)((const char*)(gbase) + (voff)[_i]), (PG8_LAS unsigned*)(lds + (bufoff) + ldsw + _i * 8192), 16, 0, 0); } while (0)
; #define PG8_LDA(dst, b, h) do { _Pragma("unroll") for (int m = 0; m < 4; ++m) _Pragma("unroll") for (int k = 0; k < 2; ++k) dst[m][k] = *(const PG8_LAS bf16x8*)(lds + PG8_SA(b, h) + aoff + m * 2048 + k * 1024); } while (0)
; #define PG8_LDB(dst, b, h) do { _Pragma("unroll") for (int n = 0; n < 2; ++n) _Pragma("unroll") for (int k = 0; k < 2; ++k) dst[n][k] = *(const PG8_LAS bf16x8*)(lds + PG8_SB(b, h) + boff + n * 2048 + k * 1024); } while (0)
; #define PG8_MMA(ai, bj, At, Bt) do { __builtin_amdgcn_s_setprio(3); _Pragma("unroll") for (int m = 0; m < 4; ++m) _Pragma("unroll") for (int n = 0; n < 2; ++n) _Pragma("unroll") for (int k = 0; k < 2; ++k) \
;         acc[ai][bj][m][n] = __builtin_amdgcn_mfma_f32_16x16x32_bf16(Bt[n][k], At[m][k], acc[ai][bj][m][n], 0, 0, 0); __builtin_amdgcn_s_setprio(0); } while (0)
; #define PG8_WAIT_V(n) asm volatile("s_waitcnt vmcnt(" #n ")" ::: "memory")
; #define PG8_WAIT_L(n) asm volatile("s_waitcnt lgkmcnt(" #n ")" ::: "memory")
; #define PG8_BAR __builtin_amdgcn_s_barrier()
; #define PG8_SCHED __builtin_amdgcn_sched_barrier(0)
; template <class Epi, class Sched, bool ALIGN_EPI = false, bool SP2 = false>
; __device__ __forceinline__ void gemm_phase(PG8_LAS unsigned char* lds, const Gemm g, const Sched& S, const Epi& E) {
;     ...
;             const bool last = (t == nt - 2);
;             const char* a1 = cA + (size_t)(t + 1) * kstep;
;             const char* a2 = last ? nA : cA + (size_t)(t + 2) * kstep; const char* b2 = last ? nB : cB + (size_t)(t + 2) * kstep;
;             const char* a3 = a2 + kstep; const char* b3 = b2 + kstep;
;             if (last && has_next) S.a_ready(nxt);
;             if constexpr (SP2) {
;             PG8_LDB(B0, 0, 0); PG8_LDB(B1, 0, 1); PG8_SCHED; PG8_LDA(At, 0, 0); PG8_STAGE(PG8_SA(1, 1), a1 + hstep, voffA);
;             PG8_WAIT_V(8); PG8_WAIT_L(0); PG8_BAR; PG8_MMA(0, 0, At, B0); PG8_MMA(0, 1, At, B1); PG8_BAR; PG8_SCHED;
;             PG8_LDA(At, 0, 1); PG8_STAGE(PG8_SB(0, 0), b2, voffB); PG8_STAGE(PG8_SB(0, 1), b2 + hstep, voffB); PG8_STAGE(PG8_SA(0, 0), a2, voffA);
.LBB0_1309:
	ds_read_b128 v[148:151], v157
	ds_read_b128 v[152:155], v157 offset:1024
	ds_read_b128 v[160:163], v157 offset:2048
	ds_read_b128 v[168:171], v157 offset:3072
	ds_read_b128 v[172:175], v158
	ds_read_b128 v[176:179], v158 offset:1024
	ds_read_b128 v[180:183], v158 offset:2048
	ds_read_b128 v[184:187], v158 offset:3072
	s_add_i32 s79, s50, 2
	s_add_u32 s10, s8, 0xffea8080
	s_addc_u32 s11, s9, -1
	s_cmp_eq_u32 s76, s50
	s_cselect_b32 s50, s48, s77
	s_cselect_b32 s53, s47, s11
	s_cselect_b32 s52, s46, s10
	s_cselect_b32 s51, s49, s78
	v_lshl_add_u64 v[164:165], s[8:9], 0, v[138:139]
	s_add_i32 m0, s43, 0xc000
	ds_read_b128 v[188:191], v159
	ds_read_b128 v[192:195], v159 offset:1024
	ds_read_b128 v[196:199], v159 offset:2048
	ds_read_b128 v[200:203], v159 offset:3072
	ds_read_b128 v[204:207], v159 offset:4096
	ds_read_b128 v[208:211], v159 offset:5120
	ds_read_b128 v[212:215], v159 offset:6144
	ds_read_b128 v[216:219], v159 offset:7168
	global_load_lds_dwordx4 v[164:165], off
	v_lshl_add_u64 v[164:165], s[8:9], 0, v[142:143]
	s_add_i32 m0, s43, 0xe000
	s_nop 0
	global_load_lds_dwordx4 v[164:165], off
	s_waitcnt vmcnt(8)
	s_waitcnt lgkmcnt(0)
	s_barrier
	s_waitcnt lgkmcnt(0)
	v_mfma_f32_16x16x32_bf16 v[126:129], v[148:151], v[188:191], v[126:129]
	s_setprio 3
	v_mfma_f32_16x16x32_bf16 v[122:125], v[160:163], v[188:191], v[122:125]
	v_mfma_f32_16x16x32_bf16 v[114:117], v[148:151], v[196:199], v[114:117]
	v_mfma_f32_16x16x32_bf16 v[106:109], v[160:163], v[196:199], v[106:109]
	v_mfma_f32_16x16x32_bf16 v[98:101], v[148:151], v[204:207], v[98:101]
	v_mfma_f32_16x16x32_bf16 v[90:93], v[160:163], v[204:207], v[90:93]
	v_mfma_f32_16x16x32_bf16 v[82:85], v[148:151], v[212:215], v[82:85]
	v_mfma_f32_16x16x32_bf16 v[74:77], v[160:163], v[212:215], v[74:77]
	v_mfma_f32_16x16x32_bf16 v[126:129], v[152:155], v[192:195], v[126:129]
	v_mfma_f32_16x16x32_bf16 v[122:125], v[168:171], v[192:195], v[122:125]
	v_mfma_f32_16x16x32_bf16 v[114:117], v[152:155], v[200:203], v[114:117]
	v_mfma_f32_16x16x32_bf16 v[106:109], v[168:171], v[200:203], v[106:109]
	v_mfma_f32_16x16x32_bf16 v[98:101], v[152:155], v[208:211], v[98:101]
	v_mfma_f32_16x16x32_bf16 v[90:93], v[168:171], v[208:211], v[90:93]
	v_mfma_f32_16x16x32_bf16 v[82:85], v[152:155], v[216:219], v[82:85]
	v_mfma_f32_16x16x32_bf16 v[74:77], v[168:171], v[216:219], v[74:77]
	s_setprio 0
	s_setprio 3
	v_mfma_f32_16x16x32_bf16 v[118:121], v[172:175], v[188:191], v[118:121]
	v_mfma_f32_16x16x32_bf16 v[110:113], v[180:183], v[188:191], v[110:113]
	v_mfma_f32_16x16x32_bf16 v[102:105], v[172:175], v[196:199], v[102:105]
	v_mfma_f32_16x16x32_bf16 v[94:97], v[180:183], v[196:199], v[94:97]
	v_mfma_f32_16x16x32_bf16 v[86:89], v[172:175], v[204:207], v[86:89]
	v_mfma_f32_16x16x32_bf16 v[78:81], v[180:183], v[204:207], v[78:81]
	v_mfma_f32_16x16x32_bf16 v[70:73], v[172:175], v[212:215], v[70:73]
	v_mfma_f32_16x16x32_bf16 v[66:69], v[180:183], v[212:215], v[66:69]
	v_mfma_f32_16x16x32_bf16 v[118:121], v[176:179], v[192:195], v[118:121]
	v_mfma_f32_16x16x32_bf16 v[110:113], v[184:187], v[192:195], v[110:113]
	v_mfma_f32_16x16x32_bf16 v[102:105], v[176:179], v[200:203], v[102:105]
	v_mfma_f32_16x16x32_bf16 v[94:97], v[184:187], v[200:203], v[94:97]
	v_mfma_f32_16x16x32_bf16 v[86:89], v[176:179], v[208:211], v[86:89]
	v_mfma_f32_16x16x32_bf16 v[78:81], v[184:187], v[208:211], v[78:81]
	v_mfma_f32_16x16x32_bf16 v[70:73], v[176:179], v[216:219], v[70:73]
	s_barrier
	v_mfma_f32_16x16x32_bf16 v[66:69], v[184:187], v[216:219], v[66:69]
	s_setprio 0
	s_add_i32 s10, s66, s42
	v_lshl_add_u64 v[164:165], s[50:51], 0, v[132:133]
	s_mov_b32 m0, s10
	ds_read_b128 v[188:191], v159 offset:16384
	ds_read_b128 v[192:195], v159 offset:17408
	ds_read_b128 v[196:199], v159 offset:18432
	ds_read_b128 v[200:203], v159 offset:19456
	ds_read_b128 v[204:207], v159 offset:20480
	ds_read_b128 v[208:211], v159 offset:21504
	ds_read_b128 v[212:215], v159 offset:22528
	ds_read_b128 v[216:219], v159 offset:23552
	global_load_lds_dwordx4 v[164:165], off
	s_add_i32 m0, s10, 0x2000
	s_add_u32 s82, s50, 0x158000
	v_lshl_add_u64 v[220:221], s[50:51], 0, v[136:137]
	s_addc_u32 s83, s51, 0
	s_add_i32 s10, s67, s42
	global_load_lds_dwordx4 v[220:221], off
	v_lshl_add_u64 v[222:223], s[82:83], 0, v[132:133]
	s_mov_b32 m0, s10
	v_lshl_add_u64 v[224:225], s[52:53], 0, v[134:135]
	global_load_lds_dwordx4 v[222:223], off
	v_lshl_add_u64 v[222:223], s[82:83], 0, v[136:137]
	s_add_i32 m0, s10, 0x2000
	s_nop 0
	global_load_lds_dwordx4 v[222:223], off
	v_lshl_add_u64 v[222:223], s[52:53], 0, v[130:131]
	s_mov_b32 m0, s43
	s_nop 0
	global_load_lds_dwordx4 v[222:223], off
	s_mov_b32 m0, s54
	s_nop 0
	global_load_lds_dwordx4 v[224:225], off
	s_waitcnt vmcnt(8)
	s_waitcnt lgkmcnt(0)
	s_barrier
; #define PG8_STAGE(bufoff, gbase, voff) do { _Pragma("unroll") for (int _i = 0; _i < 2; ++_i) \
;         __builtin_amdgcn_global_load_lds((const unsigned*)((const char*)(gbase) + (voff)[_i]), (PG8_LAS unsigned*)(lds + (bufoff) + ldsw + _i * 8192), 16, 0, 0); } while (0)
; #define PG8_LDA(dst, b, h) do { _Pragma("unroll") for (int m = 0; m < 4; ++m) _Pragma("unroll") for (int k = 0; k < 2; ++k) dst[m][k] = *(const PG8_LAS bf16x8*)(lds + PG8_SA(b, h) + aoff + m * 2048 + k * 1024); } while (0)
; #define PG8_LDB(dst, b, h) do { _Pragma("unroll") for (int n = 0; n < 2; ++n) _Pragma("unroll") for (int k = 0; k < 2; ++k) dst[n][k] = *(const PG8_LAS bf16x8*)(lds + PG8_SB(b, h) + boff + n * 2048 + k * 1024); } while (0)
; #define PG8_MMA(ai, bj, At, Bt) do { __builtin_amdgcn_s_setprio(3); _Pragma("unroll") for (int m = 0; m < 4; ++m) _Pragma("unroll") for (int n = 0; n < 2; ++n) _Pragma("unroll") for (int k = 0; k < 2; ++k) \
;         acc[ai][bj][m][n] = __builtin_amdgcn_mfma_f32_16x16x32_bf16(Bt[n][k], At[m][k], acc[ai][bj][m][n], 0, 0, 0); __builtin_amdgcn_s_setprio(0); } while (0)
; #define PG8_WAIT_V(n) asm volatile("s_waitcnt vmcnt(" #n ")" ::: "memory")
; #define PG8_WAIT_L(n) asm volatile("s_waitcnt lgkmcnt(" #n ")" ::: "memory")
; #define PG8_BAR __builtin_amdgcn_s_barrier()
; #define PG8_SCHED __builtin_amdgcn_sched_barrier(0)
; template <class Epi, class Sched, bool ALIGN_EPI = false, bool SP2 = false>
; __device__ __forceinline__ void gemm_phase(PG8_LAS unsigned char* lds, const Gemm g, const Sched& S, const Epi& E) {
;     ...
;             PG8_WAIT_V(8); PG8_WAIT_L(0); PG8_BAR; PG8_MMA(1, 0, At, B0); PG8_MMA(1, 1, At, B1); PG8_BAR; PG8_SCHED;
;             PG8_LDB(B0, 1, 0); PG8_LDB(B1, 1, 1); PG8_SCHED; PG8_LDA(At, 1, 0); PG8_STAGE(PG8_SA(0, 1), a2 + hstep, voffA);
;             PG8_WAIT_V(8); PG8_WAIT_L(0); PG8_BAR; PG8_MMA(0, 0, At, B0); PG8_MMA(0, 1, At, B1); PG8_BAR; PG8_SCHED;
	s_waitcnt lgkmcnt(0)
	v_mfma_f32_16x16x32_bf16 v[62:65], v[148:151], v[188:191], v[62:65]
	s_setprio 3
	v_mfma_f32_16x16x32_bf16 v[58:61], v[160:163], v[188:191], v[58:61]
	v_mfma_f32_16x16x32_bf16 v[50:53], v[148:151], v[196:199], v[50:53]
	v_mfma_f32_16x16x32_bf16 v[42:45], v[160:163], v[196:199], v[42:45]
	v_mfma_f32_16x16x32_bf16 v[34:37], v[148:151], v[204:207], v[34:37]
	v_mfma_f32_16x16x32_bf16 v[26:29], v[160:163], v[204:207], v[26:29]
	v_mfma_f32_16x16x32_bf16 v[18:21], v[148:151], v[212:215], v[18:21]
	v_mfma_f32_16x16x32_bf16 v[10:13], v[160:163], v[212:215], v[10:13]
	v_mfma_f32_16x16x32_bf16 v[62:65], v[152:155], v[192:195], v[62:65]
	v_mfma_f32_16x16x32_bf16 v[58:61], v[168:171], v[192:195], v[58:61]
	v_mfma_f32_16x16x32_bf16 v[50:53], v[152:155], v[200:203], v[50:53]
	v_mfma_f32_16x16x32_bf16 v[42:45], v[168:171], v[200:203], v[42:45]
	v_mfma_f32_16x16x32_bf16 v[34:37], v[152:155], v[208:211], v[34:37]
	v_mfma_f32_16x16x32_bf16 v[26:29], v[168:171], v[208:211], v[26:29]
	v_mfma_f32_16x16x32_bf16 v[18:21], v[152:155], v[216:219], v[18:21]
	v_mfma_f32_16x16x32_bf16 v[10:13], v[168:171], v[216:219], v[10:13]
	s_setprio 0
	s_setprio 3
	v_mfma_f32_16x16x32_bf16 v[54:57], v[172:175], v[188:191], v[54:57]
	v_mfma_f32_16x16x32_bf16 v[46:49], v[180:183], v[188:191], v[46:49]
	v_mfma_f32_16x16x32_bf16 v[38:41], v[172:175], v[196:199], v[38:41]
	v_mfma_f32_16x16x32_bf16 v[30:33], v[180:183], v[196:199], v[30:33]
	v_mfma_f32_16x16x32_bf16 v[22:25], v[172:175], v[204:207], v[22:25]
	v_mfma_f32_16x16x32_bf16 v[14:17], v[180:183], v[204:207], v[14:17]
	v_mfma_f32_16x16x32_bf16 v[6:9], v[172:175], v[212:215], v[6:9]
	v_mfma_f32_16x16x32_bf16 v[2:5], v[180:183], v[212:215], v[2:5]
	v_mfma_f32_16x16x32_bf16 v[54:57], v[176:179], v[192:195], v[54:57]
	v_mfma_f32_16x16x32_bf16 v[46:49], v[184:187], v[192:195], v[46:49]
	v_mfma_f32_16x16x32_bf16 v[38:41], v[176:179], v[200:203], v[38:41]
	v_mfma_f32_16x16x32_bf16 v[30:33], v[184:187], v[200:203], v[30:33]
	v_mfma_f32_16x16x32_bf16 v[22:25], v[176:179], v[208:211], v[22:25]
	v_mfma_f32_16x16x32_bf16 v[14:17], v[184:187], v[208:211], v[14:17]
	v_mfma_f32_16x16x32_bf16 v[6:9], v[176:179], v[216:219], v[6:9]
	s_barrier
	v_mfma_f32_16x16x32_bf16 v[2:5], v[184:187], v[216:219], v[2:5]
	s_setprio 0
	s_add_i32 s10, 0, 0x18000
	v_add_u32_e32 v167, s10, v141
	s_add_i32 s11, 0, 0x1c000
	ds_read_b128 v[148:151], v167
	ds_read_b128 v[152:155], v167 offset:1024
	ds_read_b128 v[160:163], v167 offset:2048
	ds_read_b128 v[168:171], v167 offset:3072
	v_add_u32_e32 v167, s11, v141
	ds_read_b128 v[172:175], v167
	ds_read_b128 v[176:179], v167 offset:1024
	ds_read_b128 v[180:183], v167 offset:2048
	ds_read_b128 v[184:187], v167 offset:3072
	s_add_u32 s52, s52, 0x158000
	s_addc_u32 s53, s53, 0
	s_mov_b32 m0, s55
	v_lshl_add_u64 v[226:227], s[52:53], 0, v[130:131]
	ds_read_b128 v[188:191], v159 offset:32768
	ds_read_b128 v[192:195], v159 offset:33792
	ds_read_b128 v[196:199], v159 offset:34816
	ds_read_b128 v[200:203], v159 offset:35840
	ds_read_b128 v[204:207], v159 offset:36864
	ds_read_b128 v[208:211], v159 offset:37888
	ds_read_b128 v[212:215], v159 offset:38912
	ds_read_b128 v[216:219], v159 offset:39936
	global_load_lds_dwordx4 v[226:227], off
	v_lshl_add_u64 v[226:227], s[52:53], 0, v[134:135]
	s_mov_b32 m0, s56
	s_nop 0
	global_load_lds_dwordx4 v[226:227], off
	s_waitcnt vmcnt(8)
	s_waitcnt lgkmcnt(0)
	s_barrier
	s_waitcnt lgkmcnt(0)
	v_mfma_f32_16x16x32_bf16 v[126:129], v[148:151], v[188:191], v[126:129]
	s_setprio 3
	v_mfma_f32_16x16x32_bf16 v[122:125], v[160:163], v[188:191], v[122:125]
	v_mfma_f32_16x16x32_bf16 v[114:117], v[148:151], v[196:199], v[114:117]
	v_mfma_f32_16x16x32_bf16 v[106:109], v[160:163], v[196:199], v[106:109]
	v_mfma_f32_16x16x32_bf16 v[98:101], v[148:151], v[204:207], v[98:101]
	v_mfma_f32_16x16x32_bf16 v[90:93], v[160:163], v[204:207], v[90:93]
	v_mfma_f32_16x16x32_bf16 v[82:85], v[148:151], v[212:215], v[82:85]
	v_mfma_f32_16x16x32_bf16 v[74:77], v[160:163], v[212:215], v[74:77]
	v_mfma_f32_16x16x32_bf16 v[126:129], v[152:155], v[192:195], v[126:129]
	v_mfma_f32_16x16x32_bf16 v[122:125], v[168:171], v[192:195], v[122:125]
	v_mfma_f32_16x16x32_bf16 v[114:117], v[152:155], v[200:203], v[114:117]
	v_mfma_f32_16x16x32_bf16 v[106:109], v[168:171], v[200:203], v[106:109]
	v_mfma_f32_16x16x32_bf16 v[98:101], v[152:155], v[208:211], v[98:101]
	v_mfma_f32_16x16x32_bf16 v[90:93], v[168:171], v[208:211], v[90:93]
	v_mfma_f32_16x16x32_bf16 v[82:85], v[152:155], v[216:219], v[82:85]
	v_mfma_f32_16x16x32_bf16 v[74:77], v[168:171], v[216:219], v[74:77]
	s_setprio 0
	s_setprio 3
	v_mfma_f32_16x16x32_bf16 v[118:121], v[172:175], v[188:191], v[118:121]
	v_mfma_f32_16x16x32_bf16 v[110:113], v[180:183], v[188:191], v[110:113]
	v_mfma_f32_16x16x32_bf16 v[102:105], v[172:175], v[196:199], v[102:105]
	v_mfma_f32_16x16x32_bf16 v[94:97], v[180:183], v[196:199], v[94:97]
	v_mfma_f32_16x16x32_bf16 v[86:89], v[172:175], v[204:207], v[86:89]
	v_mfma_f32_16x16x32_bf16 v[78:81], v[180:183], v[204:207], v[78:81]
	v_mfma_f32_16x16x32_bf16 v[70:73], v[172:175], v[212:215], v[70:73]
	v_mfma_f32_16x16x32_bf16 v[66:69], v[180:183], v[212:215], v[66:69]
	v_mfma_f32_16x16x32_bf16 v[118:121], v[176:179], v[192:195], v[118:121]
	v_mfma_f32_16x16x32_bf16 v[110:113], v[184:187], v[192:195], v[110:113]
	v_mfma_f32_16x16x32_bf16 v[102:105], v[176:179], v[200:203], v[102:105]
	v_mfma_f32_16x16x32_bf16 v[94:97], v[184:187], v[200:203], v[94:97]
	v_mfma_f32_16x16x32_bf16 v[86:89], v[176:179], v[208:211], v[86:89]
	v_mfma_f32_16x16x32_bf16 v[78:81], v[184:187], v[208:211], v[78:81]
	v_mfma_f32_16x16x32_bf16 v[70:73], v[176:179], v[216:219], v[70:73]
	s_barrier
; #define PG8_STAGE(bufoff, gbase, voff) do { _Pragma("unroll") for (int _i = 0; _i < 2; ++_i) \
;         __builtin_amdgcn_global_load_lds((const unsigned*)((const char*)(gbase) + (voff)[_i]), (PG8_LAS unsigned*)(lds + (bufoff) + ldsw + _i * 8192), 16, 0, 0); } while (0)
; #define PG8_LDA(dst, b, h) do { _Pragma("unroll") for (int m = 0; m < 4; ++m) _Pragma("unroll") for (int k = 0; k < 2; ++k) dst[m][k] = *(const PG8_LAS bf16x8*)(lds + PG8_SA(b, h) + aoff + m * 2048 + k * 1024); } while (0)
; #define PG8_MMA(ai, bj, At, Bt) do { __builtin_amdgcn_s_setprio(3); _Pragma("unroll") for (int m = 0; m < 4; ++m) _Pragma("unroll") for (int n = 0; n < 2; ++n) _Pragma("unroll") for (int k = 0; k < 2; ++k) \
;         acc[ai][bj][m][n] = __builtin_amdgcn_mfma_f32_16x16x32_bf16(Bt[n][k], At[m][k], acc[ai][bj][m][n], 0, 0, 0); __builtin_amdgcn_s_setprio(0); } while (0)
; #define PG8_WAIT_V(n) asm volatile("s_waitcnt vmcnt(" #n ")" ::: "memory")
; #define PG8_WAIT_L(n) asm volatile("s_waitcnt lgkmcnt(" #n ")" ::: "memory")
; #define PG8_BAR __builtin_amdgcn_s_barrier()
; #define PG8_SCHED __builtin_amdgcn_sched_barrier(0)
; template <class Epi, class Sched, bool ALIGN_EPI = false, bool SP2 = false>
; __device__ __forceinline__ void gemm_phase(PG8_LAS unsigned char* lds, const Gemm g, const Sched& S, const Epi& E) {
;     ...
;         for (int t = 0; t < nt; t += 2) {
;     ...
;             PG8_WAIT_V(8); PG8_WAIT_L(0); PG8_BAR; PG8_MMA(0, 0, At, B0); PG8_MMA(0, 1, At, B1); PG8_BAR; PG8_SCHED;
;             PG8_LDA(At, 1, 1); PG8_STAGE(PG8_SB(1, 0), b3, voffB); PG8_STAGE(PG8_SB(1, 1), b3 + hstep, voffB); PG8_STAGE(PG8_SA(1, 0), a3, voffA);
;             PG8_WAIT_V(8); PG8_WAIT_L(0); PG8_BAR; PG8_MMA(1, 0, At, B0); PG8_MMA(1, 1, At, B1); PG8_BAR; PG8_SCHED;
	v_mfma_f32_16x16x32_bf16 v[66:69], v[184:187], v[216:219], v[66:69]
	s_setprio 0
	s_add_i32 s10, s10, s42
	v_lshl_add_u64 v[164:165], v[164:165], 0, s[18:19]
	s_mov_b32 m0, s10
	ds_read_b128 v[188:191], v159 offset:49152
	ds_read_b128 v[192:195], v159 offset:50176
	ds_read_b128 v[196:199], v159 offset:51200
	ds_read_b128 v[200:203], v159 offset:52224
	ds_read_b128 v[204:207], v159 offset:53248
	ds_read_b128 v[208:211], v159 offset:54272
	ds_read_b128 v[212:215], v159 offset:55296
	ds_read_b128 v[216:219], v159 offset:56320
	global_load_lds_dwordx4 v[164:165], off
	s_add_i32 m0, s10, 0x2000
	s_add_u32 s50, s50, 0x158080
	v_lshl_add_u64 v[164:165], v[220:221], 0, s[18:19]
	s_addc_u32 s51, s51, 0
	s_add_i32 s10, s11, s42
	global_load_lds_dwordx4 v[164:165], off
	v_lshl_add_u64 v[164:165], s[50:51], 0, v[132:133]
	s_mov_b32 m0, s10
	s_nop 0
	global_load_lds_dwordx4 v[164:165], off
	v_lshl_add_u64 v[164:165], s[50:51], 0, v[136:137]
	s_add_i32 m0, s10, 0x2000
	s_nop 0
	global_load_lds_dwordx4 v[164:165], off
	v_lshl_add_u64 v[164:165], v[222:223], 0, s[18:19]
	s_mov_b32 m0, s61
	s_nop 0
	global_load_lds_dwordx4 v[164:165], off
	v_lshl_add_u64 v[164:165], v[224:225], 0, s[18:19]
	s_mov_b32 m0, s62
	s_nop 0
	global_load_lds_dwordx4 v[164:165], off
	s_waitcnt vmcnt(8)
	s_waitcnt lgkmcnt(0)
	s_barrier
	s_waitcnt lgkmcnt(0)
	v_mfma_f32_16x16x32_bf16 v[62:65], v[148:151], v[188:191], v[62:65]
	s_setprio 3
	v_mfma_f32_16x16x32_bf16 v[58:61], v[160:163], v[188:191], v[58:61]
	v_mfma_f32_16x16x32_bf16 v[50:53], v[148:151], v[196:199], v[50:53]
	v_mfma_f32_16x16x32_bf16 v[42:45], v[160:163], v[196:199], v[42:45]
	v_mfma_f32_16x16x32_bf16 v[34:37], v[148:151], v[204:207], v[34:37]
	v_mfma_f32_16x16x32_bf16 v[26:29], v[160:163], v[204:207], v[26:29]
	v_mfma_f32_16x16x32_bf16 v[18:21], v[148:151], v[212:215], v[18:21]
	v_mfma_f32_16x16x32_bf16 v[10:13], v[160:163], v[212:215], v[10:13]
	v_mfma_f32_16x16x32_bf16 v[62:65], v[152:155], v[192:195], v[62:65]
	v_mfma_f32_16x16x32_bf16 v[58:61], v[168:171], v[192:195], v[58:61]
	v_mfma_f32_16x16x32_bf16 v[50:53], v[152:155], v[200:203], v[50:53]
	v_mfma_f32_16x16x32_bf16 v[42:45], v[168:171], v[200:203], v[42:45]
	v_mfma_f32_16x16x32_bf16 v[34:37], v[152:155], v[208:211], v[34:37]
	v_mfma_f32_16x16x32_bf16 v[26:29], v[168:171], v[208:211], v[26:29]
	v_mfma_f32_16x16x32_bf16 v[18:21], v[152:155], v[216:219], v[18:21]
	v_mfma_f32_16x16x32_bf16 v[10:13], v[168:171], v[216:219], v[10:13]
	s_setprio 0
	s_setprio 3
	v_mfma_f32_16x16x32_bf16 v[54:57], v[172:175], v[188:191], v[54:57]
	v_mfma_f32_16x16x32_bf16 v[46:49], v[180:183], v[188:191], v[46:49]
	v_mfma_f32_16x16x32_bf16 v[38:41], v[172:175], v[196:199], v[38:41]
	v_mfma_f32_16x16x32_bf16 v[30:33], v[180:183], v[196:199], v[30:33]
	v_mfma_f32_16x16x32_bf16 v[22:25], v[172:175], v[204:207], v[22:25]
	v_mfma_f32_16x16x32_bf16 v[14:17], v[180:183], v[204:207], v[14:17]
	v_mfma_f32_16x16x32_bf16 v[6:9], v[172:175], v[212:215], v[6:9]
	v_mfma_f32_16x16x32_bf16 v[2:5], v[180:183], v[212:215], v[2:5]
	v_mfma_f32_16x16x32_bf16 v[54:57], v[176:179], v[192:195], v[54:57]
	v_mfma_f32_16x16x32_bf16 v[46:49], v[184:187], v[192:195], v[46:49]
	v_mfma_f32_16x16x32_bf16 v[38:41], v[176:179], v[200:203], v[38:41]
	v_mfma_f32_16x16x32_bf16 v[30:33], v[184:187], v[200:203], v[30:33]
	v_mfma_f32_16x16x32_bf16 v[22:25], v[176:179], v[208:211], v[22:25]
	v_mfma_f32_16x16x32_bf16 v[14:17], v[184:187], v[208:211], v[14:17]
	v_mfma_f32_16x16x32_bf16 v[6:9], v[176:179], v[216:219], v[6:9]
	s_barrier
	v_mfma_f32_16x16x32_bf16 v[2:5], v[184:187], v[216:219], v[2:5]
	s_setprio 0
	s_add_u32 s8, s8, 0x100
	s_addc_u32 s9, s9, 0
	s_add_u32 s77, s77, 0x100
	s_addc_u32 s78, s78, 0
	s_cmp_ge_u32 s79, s75
	s_mov_b32 s50, s79
	s_cbranch_scc0 .LBB0_1309
	s_and_b64 vcc, exec, s[24:25]
	s_cbranch_vccz .LBB0_1312
	s_barrier
